# bundle11 + parity-1 held-operand ds_reads use immediate offsets off the parity-0 base VGPR (2-4 VALU adds per iteration removed from load-segment heads)
# speedup vs baseline: 1.0074x; 1.0054x over previous
.LBB0_292:
	s_ashr_i32 s13, s12, 31
	s_lshl_b64 s[14:15], s[12:13], 20
	s_add_u32 s14, s19, s14
	s_addc_u32 s15, s22, s15
	s_and_b64 s[16:17], s[2:3], exec
	s_cselect_b32 s13, s15, s41
	s_cselect_b32 s74, s14, s40
	s_ashr_i32 s11, s10, 31
	s_lshl_b64 s[16:17], s[10:11], 20
	s_add_u32 s16, s23, s16
	s_addc_u32 s17, s28, s17
	s_and_b64 s[54:55], s[2:3], exec
	s_cselect_b32 s11, s17, s43
	s_cselect_b32 s75, s16, s42
	s_add_u32 s40, s40, 0x80080
	s_addc_u32 s41, s41, 0
	s_add_u32 s76, s42, 0x100
	s_addc_u32 s77, s43, 0
	s_mov_b32 s78, -2
	ds_read_b128 v[146:149], v153
	ds_read_b128 v[156:159], v153 offset:1024
	ds_read_b128 v[160:163], v153 offset:2048
	ds_read_b128 v[164:167], v153 offset:3072
	ds_read_b128 v[168:171], v154
	ds_read_b128 v[172:175], v154 offset:1024
	ds_read_b128 v[180:183], v154 offset:2048
	ds_read_b128 v[184:187], v154 offset:3072
	s_add_u32 s42, s40, 0xfff80080
	s_addc_u32 s43, s41, -1
	s_cmp_eq_u32 s78, 28
	s_cselect_b32 s55, s13, s43
	s_cselect_b32 s54, s74, s42
	s_cselect_b32 s43, s11, s77
	s_cselect_b32 s42, s75, s76
	s_add_i32 m0, s35, 0xc000
	ds_read_b128 v[188:191], v155
	ds_read_b128 v[192:195], v155 offset:1024
	ds_read_b128 v[196:199], v155 offset:2048
	ds_read_b128 v[200:203], v155 offset:3072
	ds_read_b128 v[204:207], v155 offset:4096
	ds_read_b128 v[208:211], v155 offset:5120
	ds_read_b128 v[212:215], v155 offset:6144
	ds_read_b128 v[216:219], v155 offset:7168
	global_load_lds_dwordx4 v138, s[40:41]
	s_add_i32 m0, s35, 0xe000
	s_nop 0
	global_load_lds_dwordx4 v140, s[40:41]
	s_waitcnt vmcnt(8)
	s_waitcnt lgkmcnt(0)
	s_setprio 1
	s_barrier
	v_mfma_f32_16x16x32_bf16 v[126:129], v[146:149], v[188:191], 0
	v_mfma_f32_16x16x32_bf16 v[118:121], v[160:163], v[188:191], 0
	v_mfma_f32_16x16x32_bf16 v[110:113], v[146:149], v[196:199], 0
	v_mfma_f32_16x16x32_bf16 v[102:105], v[160:163], v[196:199], 0
	v_mfma_f32_16x16x32_bf16 v[94:97], v[146:149], v[204:207], 0
	v_mfma_f32_16x16x32_bf16 v[86:89], v[160:163], v[204:207], 0
	v_mfma_f32_16x16x32_bf16 v[78:81], v[146:149], v[212:215], 0
	v_mfma_f32_16x16x32_bf16 v[70:73], v[160:163], v[212:215], 0
	v_mfma_f32_16x16x32_bf16 v[126:129], v[156:159], v[192:195], v[126:129]
	v_mfma_f32_16x16x32_bf16 v[118:121], v[164:167], v[192:195], v[118:121]
	v_mfma_f32_16x16x32_bf16 v[110:113], v[156:159], v[200:203], v[110:113]
	v_mfma_f32_16x16x32_bf16 v[102:105], v[164:167], v[200:203], v[102:105]
	v_mfma_f32_16x16x32_bf16 v[94:97], v[156:159], v[208:211], v[94:97]
	v_mfma_f32_16x16x32_bf16 v[86:89], v[164:167], v[208:211], v[86:89]
	v_mfma_f32_16x16x32_bf16 v[78:81], v[156:159], v[216:219], v[78:81]
	v_mfma_f32_16x16x32_bf16 v[70:73], v[164:167], v[216:219], v[70:73]
	s_setprio 0
	s_setprio 1
	v_mfma_f32_16x16x32_bf16 v[122:125], v[168:171], v[188:191], 0
	v_mfma_f32_16x16x32_bf16 v[114:117], v[180:183], v[188:191], 0
	v_mfma_f32_16x16x32_bf16 v[106:109], v[168:171], v[196:199], 0
	v_mfma_f32_16x16x32_bf16 v[98:101], v[180:183], v[196:199], 0
	v_mfma_f32_16x16x32_bf16 v[90:93], v[168:171], v[204:207], 0
	v_mfma_f32_16x16x32_bf16 v[82:85], v[180:183], v[204:207], 0
	v_mfma_f32_16x16x32_bf16 v[74:77], v[168:171], v[212:215], 0
	v_mfma_f32_16x16x32_bf16 v[66:69], v[180:183], v[212:215], 0
	v_mfma_f32_16x16x32_bf16 v[122:125], v[172:175], v[192:195], v[122:125]
	v_mfma_f32_16x16x32_bf16 v[114:117], v[184:187], v[192:195], v[114:117]
	v_mfma_f32_16x16x32_bf16 v[106:109], v[172:175], v[200:203], v[106:109]
	v_mfma_f32_16x16x32_bf16 v[98:101], v[184:187], v[200:203], v[98:101]
	v_mfma_f32_16x16x32_bf16 v[90:93], v[172:175], v[208:211], v[90:93]
	v_mfma_f32_16x16x32_bf16 v[82:85], v[184:187], v[208:211], v[82:85]
	v_mfma_f32_16x16x32_bf16 v[74:77], v[172:175], v[216:219], v[74:77]
	v_mfma_f32_16x16x32_bf16 v[66:69], v[184:187], v[216:219], v[66:69]
	s_barrier
	s_setprio 0
	s_add_i32 s79, s70, s29
	s_add_u32 s98, s42, 0x80
	s_addc_u32 s99, s43, 0
	s_mov_b32 m0, s79
	ds_read_b128 v[188:191], v155 offset:16384
	ds_read_b128 v[192:195], v155 offset:17408
	ds_read_b128 v[196:199], v155 offset:18432
	ds_read_b128 v[200:203], v155 offset:19456
	ds_read_b128 v[204:207], v155 offset:20480
	ds_read_b128 v[208:211], v155 offset:21504
	ds_read_b128 v[212:215], v155 offset:22528
	ds_read_b128 v[216:219], v155 offset:23552
	global_load_lds_dwordx4 v134, s[42:43]
	s_add_i32 m0, s79, 0x2000
	s_add_u32 s80, s42, 0x80000
	s_addc_u32 s81, s43, 0
	s_add_i32 s79, s71, s29
	global_load_lds_dwordx4 v130, s[42:43]
	s_mov_b32 m0, s79
	s_nop 0
	global_load_lds_dwordx4 v134, s[80:81]
	s_add_i32 m0, s79, 0x2000
	s_nop 0
	global_load_lds_dwordx4 v130, s[80:81]
	s_add_u32 s100, s54, 0x80
	s_addc_u32 s101, s55, 0
	s_mov_b32 m0, s35
	s_nop 0
	global_load_lds_dwordx4 v136, s[54:55]
	s_mov_b32 m0, s57
	s_nop 0
	global_load_lds_dwordx4 v132, s[54:55]
	s_waitcnt vmcnt(8)
	s_waitcnt lgkmcnt(0)
	s_setprio 1
	s_barrier
	v_mfma_f32_16x16x32_bf16 v[62:65], v[146:149], v[188:191], 0
	v_mfma_f32_16x16x32_bf16 v[54:57], v[160:163], v[188:191], 0
	v_mfma_f32_16x16x32_bf16 v[46:49], v[146:149], v[196:199], 0
	v_mfma_f32_16x16x32_bf16 v[38:41], v[160:163], v[196:199], 0
	v_mfma_f32_16x16x32_bf16 v[30:33], v[146:149], v[204:207], 0
	v_mfma_f32_16x16x32_bf16 v[22:25], v[160:163], v[204:207], 0
	v_mfma_f32_16x16x32_bf16 v[14:17], v[146:149], v[212:215], 0
	v_mfma_f32_16x16x32_bf16 v[6:9], v[160:163], v[212:215], 0
	v_mfma_f32_16x16x32_bf16 v[62:65], v[156:159], v[192:195], v[62:65]
	v_mfma_f32_16x16x32_bf16 v[54:57], v[164:167], v[192:195], v[54:57]
	v_mfma_f32_16x16x32_bf16 v[46:49], v[156:159], v[200:203], v[46:49]
	v_mfma_f32_16x16x32_bf16 v[38:41], v[164:167], v[200:203], v[38:41]
	v_mfma_f32_16x16x32_bf16 v[30:33], v[156:159], v[208:211], v[30:33]
	v_mfma_f32_16x16x32_bf16 v[22:25], v[164:167], v[208:211], v[22:25]
	v_mfma_f32_16x16x32_bf16 v[14:17], v[156:159], v[216:219], v[14:17]
	v_mfma_f32_16x16x32_bf16 v[6:9], v[164:167], v[216:219], v[6:9]
	s_setprio 0
	s_setprio 1
	v_mfma_f32_16x16x32_bf16 v[58:61], v[168:171], v[188:191], 0
	v_mfma_f32_16x16x32_bf16 v[50:53], v[180:183], v[188:191], 0
	v_mfma_f32_16x16x32_bf16 v[42:45], v[168:171], v[196:199], 0
	v_mfma_f32_16x16x32_bf16 v[34:37], v[180:183], v[196:199], 0
	v_mfma_f32_16x16x32_bf16 v[26:29], v[168:171], v[204:207], 0
	v_mfma_f32_16x16x32_bf16 v[18:21], v[180:183], v[204:207], 0
	v_mfma_f32_16x16x32_bf16 v[10:13], v[168:171], v[212:215], 0
	v_mfma_f32_16x16x32_bf16 v[2:5], v[180:183], v[212:215], 0
	v_mfma_f32_16x16x32_bf16 v[58:61], v[172:175], v[192:195], v[58:61]
	v_mfma_f32_16x16x32_bf16 v[50:53], v[184:187], v[192:195], v[50:53]
	v_mfma_f32_16x16x32_bf16 v[42:45], v[172:175], v[200:203], v[42:45]
	v_mfma_f32_16x16x32_bf16 v[34:37], v[184:187], v[200:203], v[34:37]
	v_mfma_f32_16x16x32_bf16 v[26:29], v[172:175], v[208:211], v[26:29]
	v_mfma_f32_16x16x32_bf16 v[18:21], v[184:187], v[208:211], v[18:21]
	v_mfma_f32_16x16x32_bf16 v[10:13], v[172:175], v[216:219], v[10:13]
	v_mfma_f32_16x16x32_bf16 v[2:5], v[184:187], v[216:219], v[2:5]
	s_barrier
	s_setprio 0
	s_add_i32 s79, 0, 0x18000
	s_add_i32 s80, 0, 0x1c000
	ds_read_b128 v[146:149], v153 offset:32768
	ds_read_b128 v[156:159], v153 offset:33792
	ds_read_b128 v[160:163], v153 offset:34816
	ds_read_b128 v[164:167], v153 offset:35840
	ds_read_b128 v[168:171], v154 offset:32768
	ds_read_b128 v[172:175], v154 offset:33792
	ds_read_b128 v[180:183], v154 offset:34816
	ds_read_b128 v[184:187], v154 offset:35840
	s_add_u32 s54, s54, 0x80000
	s_addc_u32 s55, s55, 0
	s_mov_b32 m0, s58
	ds_read_b128 v[188:191], v155 offset:32768
	ds_read_b128 v[192:195], v155 offset:33792
	ds_read_b128 v[196:199], v155 offset:34816
	ds_read_b128 v[200:203], v155 offset:35840
	ds_read_b128 v[204:207], v155 offset:36864
	ds_read_b128 v[208:211], v155 offset:37888
	ds_read_b128 v[212:215], v155 offset:38912
	ds_read_b128 v[216:219], v155 offset:39936
	global_load_lds_dwordx4 v136, s[54:55]
	s_mov_b32 m0, s59
	s_nop 0
	global_load_lds_dwordx4 v132, s[54:55]
	s_waitcnt vmcnt(8)
	s_waitcnt lgkmcnt(0)
	s_setprio 1
	s_barrier
	v_mfma_f32_16x16x32_bf16 v[126:129], v[146:149], v[188:191], v[126:129]
	v_mfma_f32_16x16x32_bf16 v[118:121], v[160:163], v[188:191], v[118:121]
	v_mfma_f32_16x16x32_bf16 v[110:113], v[146:149], v[196:199], v[110:113]
	v_mfma_f32_16x16x32_bf16 v[102:105], v[160:163], v[196:199], v[102:105]
	v_mfma_f32_16x16x32_bf16 v[94:97], v[146:149], v[204:207], v[94:97]
	v_mfma_f32_16x16x32_bf16 v[86:89], v[160:163], v[204:207], v[86:89]
	v_mfma_f32_16x16x32_bf16 v[78:81], v[146:149], v[212:215], v[78:81]
	v_mfma_f32_16x16x32_bf16 v[70:73], v[160:163], v[212:215], v[70:73]
	v_mfma_f32_16x16x32_bf16 v[126:129], v[156:159], v[192:195], v[126:129]
	v_mfma_f32_16x16x32_bf16 v[118:121], v[164:167], v[192:195], v[118:121]
	v_mfma_f32_16x16x32_bf16 v[110:113], v[156:159], v[200:203], v[110:113]
	v_mfma_f32_16x16x32_bf16 v[102:105], v[164:167], v[200:203], v[102:105]
	v_mfma_f32_16x16x32_bf16 v[94:97], v[156:159], v[208:211], v[94:97]
	v_mfma_f32_16x16x32_bf16 v[86:89], v[164:167], v[208:211], v[86:89]
	v_mfma_f32_16x16x32_bf16 v[78:81], v[156:159], v[216:219], v[78:81]
	v_mfma_f32_16x16x32_bf16 v[70:73], v[164:167], v[216:219], v[70:73]
	s_setprio 0
	s_setprio 1
	v_mfma_f32_16x16x32_bf16 v[122:125], v[168:171], v[188:191], v[122:125]
	v_mfma_f32_16x16x32_bf16 v[114:117], v[180:183], v[188:191], v[114:117]
	v_mfma_f32_16x16x32_bf16 v[106:109], v[168:171], v[196:199], v[106:109]
	v_mfma_f32_16x16x32_bf16 v[98:101], v[180:183], v[196:199], v[98:101]
	v_mfma_f32_16x16x32_bf16 v[90:93], v[168:171], v[204:207], v[90:93]
	v_mfma_f32_16x16x32_bf16 v[82:85], v[180:183], v[204:207], v[82:85]
	v_mfma_f32_16x16x32_bf16 v[74:77], v[168:171], v[212:215], v[74:77]
	v_mfma_f32_16x16x32_bf16 v[66:69], v[180:183], v[212:215], v[66:69]
	v_mfma_f32_16x16x32_bf16 v[122:125], v[172:175], v[192:195], v[122:125]
	v_mfma_f32_16x16x32_bf16 v[114:117], v[184:187], v[192:195], v[114:117]
	v_mfma_f32_16x16x32_bf16 v[106:109], v[172:175], v[200:203], v[106:109]
	v_mfma_f32_16x16x32_bf16 v[98:101], v[184:187], v[200:203], v[98:101]
	v_mfma_f32_16x16x32_bf16 v[90:93], v[172:175], v[208:211], v[90:93]
	v_mfma_f32_16x16x32_bf16 v[82:85], v[184:187], v[208:211], v[82:85]
	v_mfma_f32_16x16x32_bf16 v[74:77], v[172:175], v[216:219], v[74:77]
	v_mfma_f32_16x16x32_bf16 v[66:69], v[184:187], v[216:219], v[66:69]
	s_barrier
	s_setprio 0
	s_add_i32 s54, s79, s29
	s_mov_b32 m0, s54
	ds_read_b128 v[188:191], v155 offset:49152
	ds_read_b128 v[192:195], v155 offset:50176
	ds_read_b128 v[196:199], v155 offset:51200
	ds_read_b128 v[200:203], v155 offset:52224
	ds_read_b128 v[204:207], v155 offset:53248
	ds_read_b128 v[208:211], v155 offset:54272
	ds_read_b128 v[212:215], v155 offset:55296
	ds_read_b128 v[216:219], v155 offset:56320
	global_load_lds_dwordx4 v134, s[98:99]
	s_add_i32 m0, s54, 0x2000
	s_add_u32 s42, s42, 0x80080
	s_addc_u32 s43, s43, 0
	s_add_i32 s54, s80, s29
	global_load_lds_dwordx4 v130, s[98:99]
	s_mov_b32 m0, s54
	s_nop 0
	global_load_lds_dwordx4 v134, s[42:43]
	s_add_i32 m0, s54, 0x2000
	s_nop 0
	global_load_lds_dwordx4 v130, s[42:43]
	s_mov_b32 m0, s64
	s_nop 0
	global_load_lds_dwordx4 v136, s[100:101]
	s_mov_b32 m0, s65
	s_nop 0
	global_load_lds_dwordx4 v132, s[100:101]
	s_waitcnt vmcnt(8)
	s_waitcnt lgkmcnt(0)
	s_setprio 1
	s_barrier
	v_mfma_f32_16x16x32_bf16 v[62:65], v[146:149], v[188:191], v[62:65]
	v_mfma_f32_16x16x32_bf16 v[54:57], v[160:163], v[188:191], v[54:57]
	v_mfma_f32_16x16x32_bf16 v[46:49], v[146:149], v[196:199], v[46:49]
	v_mfma_f32_16x16x32_bf16 v[38:41], v[160:163], v[196:199], v[38:41]
	v_mfma_f32_16x16x32_bf16 v[30:33], v[146:149], v[204:207], v[30:33]
	v_mfma_f32_16x16x32_bf16 v[22:25], v[160:163], v[204:207], v[22:25]
	v_mfma_f32_16x16x32_bf16 v[14:17], v[146:149], v[212:215], v[14:17]
	v_mfma_f32_16x16x32_bf16 v[6:9], v[160:163], v[212:215], v[6:9]
	v_mfma_f32_16x16x32_bf16 v[62:65], v[156:159], v[192:195], v[62:65]
	v_mfma_f32_16x16x32_bf16 v[54:57], v[164:167], v[192:195], v[54:57]
	v_mfma_f32_16x16x32_bf16 v[46:49], v[156:159], v[200:203], v[46:49]
	v_mfma_f32_16x16x32_bf16 v[38:41], v[164:167], v[200:203], v[38:41]
	v_mfma_f32_16x16x32_bf16 v[30:33], v[156:159], v[208:211], v[30:33]
	v_mfma_f32_16x16x32_bf16 v[22:25], v[164:167], v[208:211], v[22:25]
	v_mfma_f32_16x16x32_bf16 v[14:17], v[156:159], v[216:219], v[14:17]
	v_mfma_f32_16x16x32_bf16 v[6:9], v[164:167], v[216:219], v[6:9]
	s_setprio 0
	s_setprio 1
	v_mfma_f32_16x16x32_bf16 v[58:61], v[168:171], v[188:191], v[58:61]
	v_mfma_f32_16x16x32_bf16 v[50:53], v[180:183], v[188:191], v[50:53]
	v_mfma_f32_16x16x32_bf16 v[42:45], v[168:171], v[196:199], v[42:45]
	v_mfma_f32_16x16x32_bf16 v[34:37], v[180:183], v[196:199], v[34:37]
	v_mfma_f32_16x16x32_bf16 v[26:29], v[168:171], v[204:207], v[26:29]
	v_mfma_f32_16x16x32_bf16 v[18:21], v[180:183], v[204:207], v[18:21]
	v_mfma_f32_16x16x32_bf16 v[10:13], v[168:171], v[212:215], v[10:13]
	v_mfma_f32_16x16x32_bf16 v[2:5], v[180:183], v[212:215], v[2:5]
	v_mfma_f32_16x16x32_bf16 v[58:61], v[172:175], v[192:195], v[58:61]
	v_mfma_f32_16x16x32_bf16 v[50:53], v[184:187], v[192:195], v[50:53]
	v_mfma_f32_16x16x32_bf16 v[42:45], v[172:175], v[200:203], v[42:45]
	v_mfma_f32_16x16x32_bf16 v[34:37], v[184:187], v[200:203], v[34:37]
	v_mfma_f32_16x16x32_bf16 v[26:29], v[172:175], v[208:211], v[26:29]
	v_mfma_f32_16x16x32_bf16 v[18:21], v[184:187], v[208:211], v[18:21]
	v_mfma_f32_16x16x32_bf16 v[10:13], v[172:175], v[216:219], v[10:13]
	v_mfma_f32_16x16x32_bf16 v[2:5], v[184:187], v[216:219], v[2:5]
	s_barrier
	s_setprio 0
	s_add_i32 s78, s78, 2
	s_add_u32 s40, s40, 0x100
	s_addc_u32 s41, s41, 0
	s_add_u32 s76, s76, 0x100
	s_addc_u32 s77, s77, 0
	s_cmp_gt_u32 s78, 29
.LBB0_293:
	ds_read_b128 v[146:149], v153
	ds_read_b128 v[156:159], v153 offset:1024
	ds_read_b128 v[160:163], v153 offset:2048
	ds_read_b128 v[164:167], v153 offset:3072
	ds_read_b128 v[168:171], v154
	ds_read_b128 v[172:175], v154 offset:1024
	ds_read_b128 v[180:183], v154 offset:2048
	ds_read_b128 v[184:187], v154 offset:3072
	s_add_u32 s42, s40, 0xfff80080
	s_addc_u32 s43, s41, -1
	s_cmp_eq_u32 s78, 28
	s_cselect_b32 s55, s13, s43
	s_cselect_b32 s54, s74, s42
	s_cselect_b32 s43, s11, s77
	s_cselect_b32 s42, s75, s76
	s_add_i32 m0, s35, 0xc000
	ds_read_b128 v[188:191], v155
	ds_read_b128 v[192:195], v155 offset:1024
	ds_read_b128 v[196:199], v155 offset:2048
	ds_read_b128 v[200:203], v155 offset:3072
	ds_read_b128 v[204:207], v155 offset:4096
	ds_read_b128 v[208:211], v155 offset:5120
	ds_read_b128 v[212:215], v155 offset:6144
	ds_read_b128 v[216:219], v155 offset:7168
	global_load_lds_dwordx4 v138, s[40:41]
	s_add_i32 m0, s35, 0xe000
	s_nop 0
	global_load_lds_dwordx4 v140, s[40:41]
	s_waitcnt vmcnt(8)
	s_waitcnt lgkmcnt(0)
	s_setprio 1
	s_barrier
	v_mfma_f32_16x16x32_bf16 v[126:129], v[146:149], v[188:191], v[126:129]
	v_mfma_f32_16x16x32_bf16 v[118:121], v[160:163], v[188:191], v[118:121]
	v_mfma_f32_16x16x32_bf16 v[110:113], v[146:149], v[196:199], v[110:113]
	v_mfma_f32_16x16x32_bf16 v[102:105], v[160:163], v[196:199], v[102:105]
	v_mfma_f32_16x16x32_bf16 v[94:97], v[146:149], v[204:207], v[94:97]
	v_mfma_f32_16x16x32_bf16 v[86:89], v[160:163], v[204:207], v[86:89]
	v_mfma_f32_16x16x32_bf16 v[78:81], v[146:149], v[212:215], v[78:81]
	v_mfma_f32_16x16x32_bf16 v[70:73], v[160:163], v[212:215], v[70:73]
	v_mfma_f32_16x16x32_bf16 v[126:129], v[156:159], v[192:195], v[126:129]
	v_mfma_f32_16x16x32_bf16 v[118:121], v[164:167], v[192:195], v[118:121]
	v_mfma_f32_16x16x32_bf16 v[110:113], v[156:159], v[200:203], v[110:113]
	v_mfma_f32_16x16x32_bf16 v[102:105], v[164:167], v[200:203], v[102:105]
	v_mfma_f32_16x16x32_bf16 v[94:97], v[156:159], v[208:211], v[94:97]
	v_mfma_f32_16x16x32_bf16 v[86:89], v[164:167], v[208:211], v[86:89]
	v_mfma_f32_16x16x32_bf16 v[78:81], v[156:159], v[216:219], v[78:81]
	v_mfma_f32_16x16x32_bf16 v[70:73], v[164:167], v[216:219], v[70:73]
	s_setprio 0
	s_setprio 1
	v_mfma_f32_16x16x32_bf16 v[122:125], v[168:171], v[188:191], v[122:125]
	v_mfma_f32_16x16x32_bf16 v[114:117], v[180:183], v[188:191], v[114:117]
	v_mfma_f32_16x16x32_bf16 v[106:109], v[168:171], v[196:199], v[106:109]
	v_mfma_f32_16x16x32_bf16 v[98:101], v[180:183], v[196:199], v[98:101]
	v_mfma_f32_16x16x32_bf16 v[90:93], v[168:171], v[204:207], v[90:93]
	v_mfma_f32_16x16x32_bf16 v[82:85], v[180:183], v[204:207], v[82:85]
	v_mfma_f32_16x16x32_bf16 v[74:77], v[168:171], v[212:215], v[74:77]
	v_mfma_f32_16x16x32_bf16 v[66:69], v[180:183], v[212:215], v[66:69]
	v_mfma_f32_16x16x32_bf16 v[122:125], v[172:175], v[192:195], v[122:125]
	v_mfma_f32_16x16x32_bf16 v[114:117], v[184:187], v[192:195], v[114:117]
	v_mfma_f32_16x16x32_bf16 v[106:109], v[172:175], v[200:203], v[106:109]
	v_mfma_f32_16x16x32_bf16 v[98:101], v[184:187], v[200:203], v[98:101]
	v_mfma_f32_16x16x32_bf16 v[90:93], v[172:175], v[208:211], v[90:93]
	v_mfma_f32_16x16x32_bf16 v[82:85], v[184:187], v[208:211], v[82:85]
	v_mfma_f32_16x16x32_bf16 v[74:77], v[172:175], v[216:219], v[74:77]
	v_mfma_f32_16x16x32_bf16 v[66:69], v[184:187], v[216:219], v[66:69]
	s_barrier
	s_setprio 0
	s_add_i32 s79, s70, s29
	s_add_u32 s98, s42, 0x80
	s_addc_u32 s99, s43, 0
	s_mov_b32 m0, s79
	ds_read_b128 v[188:191], v155 offset:16384
	ds_read_b128 v[192:195], v155 offset:17408
	ds_read_b128 v[196:199], v155 offset:18432
	ds_read_b128 v[200:203], v155 offset:19456
	ds_read_b128 v[204:207], v155 offset:20480
	ds_read_b128 v[208:211], v155 offset:21504
	ds_read_b128 v[212:215], v155 offset:22528
	ds_read_b128 v[216:219], v155 offset:23552
	global_load_lds_dwordx4 v134, s[42:43]
	s_add_i32 m0, s79, 0x2000
	s_add_u32 s80, s42, 0x80000
	s_addc_u32 s81, s43, 0
	s_add_i32 s79, s71, s29
	global_load_lds_dwordx4 v130, s[42:43]
	s_mov_b32 m0, s79
	s_nop 0
	global_load_lds_dwordx4 v134, s[80:81]
	s_add_i32 m0, s79, 0x2000
	s_nop 0
	global_load_lds_dwordx4 v130, s[80:81]
	s_add_u32 s100, s54, 0x80
	s_addc_u32 s101, s55, 0
	s_mov_b32 m0, s35
	s_nop 0
	global_load_lds_dwordx4 v136, s[54:55]
	s_mov_b32 m0, s57
	s_nop 0
	global_load_lds_dwordx4 v132, s[54:55]
	s_waitcnt vmcnt(8)
	s_waitcnt lgkmcnt(0)
	s_setprio 1
	s_barrier
	v_mfma_f32_16x16x32_bf16 v[62:65], v[146:149], v[188:191], v[62:65]
	v_mfma_f32_16x16x32_bf16 v[54:57], v[160:163], v[188:191], v[54:57]
	v_mfma_f32_16x16x32_bf16 v[46:49], v[146:149], v[196:199], v[46:49]
	v_mfma_f32_16x16x32_bf16 v[38:41], v[160:163], v[196:199], v[38:41]
	v_mfma_f32_16x16x32_bf16 v[30:33], v[146:149], v[204:207], v[30:33]
	v_mfma_f32_16x16x32_bf16 v[22:25], v[160:163], v[204:207], v[22:25]
	v_mfma_f32_16x16x32_bf16 v[14:17], v[146:149], v[212:215], v[14:17]
	v_mfma_f32_16x16x32_bf16 v[6:9], v[160:163], v[212:215], v[6:9]
	v_mfma_f32_16x16x32_bf16 v[62:65], v[156:159], v[192:195], v[62:65]
	v_mfma_f32_16x16x32_bf16 v[54:57], v[164:167], v[192:195], v[54:57]
	v_mfma_f32_16x16x32_bf16 v[46:49], v[156:159], v[200:203], v[46:49]
	v_mfma_f32_16x16x32_bf16 v[38:41], v[164:167], v[200:203], v[38:41]
	v_mfma_f32_16x16x32_bf16 v[30:33], v[156:159], v[208:211], v[30:33]
	v_mfma_f32_16x16x32_bf16 v[22:25], v[164:167], v[208:211], v[22:25]
	v_mfma_f32_16x16x32_bf16 v[14:17], v[156:159], v[216:219], v[14:17]
	v_mfma_f32_16x16x32_bf16 v[6:9], v[164:167], v[216:219], v[6:9]
	s_setprio 0
	s_setprio 1
	v_mfma_f32_16x16x32_bf16 v[58:61], v[168:171], v[188:191], v[58:61]
	v_mfma_f32_16x16x32_bf16 v[50:53], v[180:183], v[188:191], v[50:53]
	v_mfma_f32_16x16x32_bf16 v[42:45], v[168:171], v[196:199], v[42:45]
	v_mfma_f32_16x16x32_bf16 v[34:37], v[180:183], v[196:199], v[34:37]
	v_mfma_f32_16x16x32_bf16 v[26:29], v[168:171], v[204:207], v[26:29]
	v_mfma_f32_16x16x32_bf16 v[18:21], v[180:183], v[204:207], v[18:21]
	v_mfma_f32_16x16x32_bf16 v[10:13], v[168:171], v[212:215], v[10:13]
	v_mfma_f32_16x16x32_bf16 v[2:5], v[180:183], v[212:215], v[2:5]
	v_mfma_f32_16x16x32_bf16 v[58:61], v[172:175], v[192:195], v[58:61]
	v_mfma_f32_16x16x32_bf16 v[50:53], v[184:187], v[192:195], v[50:53]
	v_mfma_f32_16x16x32_bf16 v[42:45], v[172:175], v[200:203], v[42:45]
	v_mfma_f32_16x16x32_bf16 v[34:37], v[184:187], v[200:203], v[34:37]
	v_mfma_f32_16x16x32_bf16 v[26:29], v[172:175], v[208:211], v[26:29]
	v_mfma_f32_16x16x32_bf16 v[18:21], v[184:187], v[208:211], v[18:21]
	v_mfma_f32_16x16x32_bf16 v[10:13], v[172:175], v[216:219], v[10:13]
	v_mfma_f32_16x16x32_bf16 v[2:5], v[184:187], v[216:219], v[2:5]
	s_barrier
	s_setprio 0
	s_add_i32 s79, 0, 0x18000
	s_add_i32 s80, 0, 0x1c000
	ds_read_b128 v[146:149], v153 offset:32768
	ds_read_b128 v[156:159], v153 offset:33792
	ds_read_b128 v[160:163], v153 offset:34816
	ds_read_b128 v[164:167], v153 offset:35840
	ds_read_b128 v[168:171], v154 offset:32768
	ds_read_b128 v[172:175], v154 offset:33792
	ds_read_b128 v[180:183], v154 offset:34816
	ds_read_b128 v[184:187], v154 offset:35840
	s_add_u32 s54, s54, 0x80000
	s_addc_u32 s55, s55, 0
	s_mov_b32 m0, s58
	ds_read_b128 v[188:191], v155 offset:32768
	ds_read_b128 v[192:195], v155 offset:33792
	ds_read_b128 v[196:199], v155 offset:34816
	ds_read_b128 v[200:203], v155 offset:35840
	ds_read_b128 v[204:207], v155 offset:36864
	ds_read_b128 v[208:211], v155 offset:37888
	ds_read_b128 v[212:215], v155 offset:38912
	ds_read_b128 v[216:219], v155 offset:39936
	global_load_lds_dwordx4 v136, s[54:55]
	s_mov_b32 m0, s59
	s_nop 0
	global_load_lds_dwordx4 v132, s[54:55]
	s_waitcnt vmcnt(8)
	s_waitcnt lgkmcnt(0)
	s_setprio 1
	s_barrier
	v_mfma_f32_16x16x32_bf16 v[126:129], v[146:149], v[188:191], v[126:129]
	v_mfma_f32_16x16x32_bf16 v[118:121], v[160:163], v[188:191], v[118:121]
	v_mfma_f32_16x16x32_bf16 v[110:113], v[146:149], v[196:199], v[110:113]
	v_mfma_f32_16x16x32_bf16 v[102:105], v[160:163], v[196:199], v[102:105]
	v_mfma_f32_16x16x32_bf16 v[94:97], v[146:149], v[204:207], v[94:97]
	v_mfma_f32_16x16x32_bf16 v[86:89], v[160:163], v[204:207], v[86:89]
	v_mfma_f32_16x16x32_bf16 v[78:81], v[146:149], v[212:215], v[78:81]
	v_mfma_f32_16x16x32_bf16 v[70:73], v[160:163], v[212:215], v[70:73]
	v_mfma_f32_16x16x32_bf16 v[126:129], v[156:159], v[192:195], v[126:129]
	v_mfma_f32_16x16x32_bf16 v[118:121], v[164:167], v[192:195], v[118:121]
	v_mfma_f32_16x16x32_bf16 v[110:113], v[156:159], v[200:203], v[110:113]
	v_mfma_f32_16x16x32_bf16 v[102:105], v[164:167], v[200:203], v[102:105]
	v_mfma_f32_16x16x32_bf16 v[94:97], v[156:159], v[208:211], v[94:97]
	v_mfma_f32_16x16x32_bf16 v[86:89], v[164:167], v[208:211], v[86:89]
	v_mfma_f32_16x16x32_bf16 v[78:81], v[156:159], v[216:219], v[78:81]
	v_mfma_f32_16x16x32_bf16 v[70:73], v[164:167], v[216:219], v[70:73]
	s_setprio 0
	s_setprio 1
	v_mfma_f32_16x16x32_bf16 v[122:125], v[168:171], v[188:191], v[122:125]
	v_mfma_f32_16x16x32_bf16 v[114:117], v[180:183], v[188:191], v[114:117]
	v_mfma_f32_16x16x32_bf16 v[106:109], v[168:171], v[196:199], v[106:109]
	v_mfma_f32_16x16x32_bf16 v[98:101], v[180:183], v[196:199], v[98:101]
	v_mfma_f32_16x16x32_bf16 v[90:93], v[168:171], v[204:207], v[90:93]
	v_mfma_f32_16x16x32_bf16 v[82:85], v[180:183], v[204:207], v[82:85]
	v_mfma_f32_16x16x32_bf16 v[74:77], v[168:171], v[212:215], v[74:77]
	v_mfma_f32_16x16x32_bf16 v[66:69], v[180:183], v[212:215], v[66:69]
	v_mfma_f32_16x16x32_bf16 v[122:125], v[172:175], v[192:195], v[122:125]
	v_mfma_f32_16x16x32_bf16 v[114:117], v[184:187], v[192:195], v[114:117]
	v_mfma_f32_16x16x32_bf16 v[106:109], v[172:175], v[200:203], v[106:109]
	v_mfma_f32_16x16x32_bf16 v[98:101], v[184:187], v[200:203], v[98:101]
	v_mfma_f32_16x16x32_bf16 v[90:93], v[172:175], v[208:211], v[90:93]
	v_mfma_f32_16x16x32_bf16 v[82:85], v[184:187], v[208:211], v[82:85]
	v_mfma_f32_16x16x32_bf16 v[74:77], v[172:175], v[216:219], v[74:77]
	v_mfma_f32_16x16x32_bf16 v[66:69], v[184:187], v[216:219], v[66:69]
	s_barrier
	s_setprio 0
	s_add_i32 s54, s79, s29
	s_mov_b32 m0, s54
	ds_read_b128 v[188:191], v155 offset:49152
	ds_read_b128 v[192:195], v155 offset:50176
	ds_read_b128 v[196:199], v155 offset:51200
	ds_read_b128 v[200:203], v155 offset:52224
	ds_read_b128 v[204:207], v155 offset:53248
	ds_read_b128 v[208:211], v155 offset:54272
	ds_read_b128 v[212:215], v155 offset:55296
	ds_read_b128 v[216:219], v155 offset:56320
	global_load_lds_dwordx4 v134, s[98:99]
	s_add_i32 m0, s54, 0x2000
	s_add_u32 s42, s42, 0x80080
	s_addc_u32 s43, s43, 0
	s_add_i32 s54, s80, s29
	global_load_lds_dwordx4 v130, s[98:99]
	s_mov_b32 m0, s54
	s_nop 0
	global_load_lds_dwordx4 v134, s[42:43]
	s_add_i32 m0, s54, 0x2000
	s_nop 0
	global_load_lds_dwordx4 v130, s[42:43]
	s_mov_b32 m0, s64
	s_nop 0
	global_load_lds_dwordx4 v136, s[100:101]
	s_mov_b32 m0, s65
	s_nop 0
	global_load_lds_dwordx4 v132, s[100:101]
	s_add_i32 s78, s78, 2
	s_add_u32 s40, s40, 0x100
	s_addc_u32 s41, s41, 0
	s_add_u32 s76, s76, 0x100
	s_addc_u32 s77, s77, 0
	s_cmp_gt_u32 s78, 29
	s_waitcnt vmcnt(8)
	s_waitcnt lgkmcnt(0)
	s_setprio 1
	s_barrier
	v_mfma_f32_16x16x32_bf16 v[62:65], v[146:149], v[188:191], v[62:65]
	v_mfma_f32_16x16x32_bf16 v[54:57], v[160:163], v[188:191], v[54:57]
	v_mfma_f32_16x16x32_bf16 v[46:49], v[146:149], v[196:199], v[46:49]
	v_mfma_f32_16x16x32_bf16 v[38:41], v[160:163], v[196:199], v[38:41]
	v_mfma_f32_16x16x32_bf16 v[30:33], v[146:149], v[204:207], v[30:33]
	v_mfma_f32_16x16x32_bf16 v[22:25], v[160:163], v[204:207], v[22:25]
	v_mfma_f32_16x16x32_bf16 v[14:17], v[146:149], v[212:215], v[14:17]
	v_mfma_f32_16x16x32_bf16 v[6:9], v[160:163], v[212:215], v[6:9]
	v_mfma_f32_16x16x32_bf16 v[62:65], v[156:159], v[192:195], v[62:65]
	v_mfma_f32_16x16x32_bf16 v[54:57], v[164:167], v[192:195], v[54:57]
	v_mfma_f32_16x16x32_bf16 v[46:49], v[156:159], v[200:203], v[46:49]
	v_mfma_f32_16x16x32_bf16 v[38:41], v[164:167], v[200:203], v[38:41]
	v_mfma_f32_16x16x32_bf16 v[30:33], v[156:159], v[208:211], v[30:33]
	v_mfma_f32_16x16x32_bf16 v[22:25], v[164:167], v[208:211], v[22:25]
	v_mfma_f32_16x16x32_bf16 v[14:17], v[156:159], v[216:219], v[14:17]
	v_mfma_f32_16x16x32_bf16 v[6:9], v[164:167], v[216:219], v[6:9]
	s_setprio 0
	s_setprio 1
	v_mfma_f32_16x16x32_bf16 v[58:61], v[168:171], v[188:191], v[58:61]
	v_mfma_f32_16x16x32_bf16 v[50:53], v[180:183], v[188:191], v[50:53]
	v_mfma_f32_16x16x32_bf16 v[42:45], v[168:171], v[196:199], v[42:45]
	v_mfma_f32_16x16x32_bf16 v[34:37], v[180:183], v[196:199], v[34:37]
	v_mfma_f32_16x16x32_bf16 v[26:29], v[168:171], v[204:207], v[26:29]
	v_mfma_f32_16x16x32_bf16 v[18:21], v[180:183], v[204:207], v[18:21]
	v_mfma_f32_16x16x32_bf16 v[10:13], v[168:171], v[212:215], v[10:13]
	v_mfma_f32_16x16x32_bf16 v[2:5], v[180:183], v[212:215], v[2:5]
	v_mfma_f32_16x16x32_bf16 v[58:61], v[172:175], v[192:195], v[58:61]
	v_mfma_f32_16x16x32_bf16 v[50:53], v[184:187], v[192:195], v[50:53]
	v_mfma_f32_16x16x32_bf16 v[42:45], v[172:175], v[200:203], v[42:45]
	v_mfma_f32_16x16x32_bf16 v[34:37], v[184:187], v[200:203], v[34:37]
	v_mfma_f32_16x16x32_bf16 v[26:29], v[172:175], v[208:211], v[26:29]
	v_mfma_f32_16x16x32_bf16 v[18:21], v[184:187], v[208:211], v[18:21]
	v_mfma_f32_16x16x32_bf16 v[10:13], v[172:175], v[216:219], v[10:13]
	v_mfma_f32_16x16x32_bf16 v[2:5], v[184:187], v[216:219], v[2:5]
	s_barrier
	s_setprio 0
	s_cbranch_scc0 .LBB0_293
	s_and_b64 vcc, exec, s[8:9]
	s_cbranch_vccz .LBB0_296
	s_barrier

.LBB0_378:
	s_add_u32 s12, s58, 0x160080
	s_addc_u32 s13, s59, 0
	s_add_u32 s81, s56, 0x100
	s_addc_u32 s82, s57, 0
	s_mov_b32 s83, -2
	ds_read_b128 v[130:133], v208
	ds_read_b128 v[134:137], v208 offset:1024
	ds_read_b128 v[138:141], v208 offset:2048
	ds_read_b128 v[142:145], v208 offset:3072
	ds_read_b128 v[146:149], v209
	ds_read_b128 v[150:153], v209 offset:1024
	ds_read_b128 v[154:157], v209 offset:2048
	ds_read_b128 v[158:161], v209 offset:3072
	s_add_u32 s56, s12, 0xffea0080
	s_addc_u32 s57, s13, -1
	s_cmpk_eq_i32 s83, 0x54
	s_cselect_b32 s59, s43, s57
	s_cselect_b32 s58, s42, s56
	s_cselect_b32 s57, s55, s82
	s_cselect_b32 s56, s54, s81
	s_add_i32 m0, s31, 0xc000
	ds_read_b128 v[162:165], v210
	ds_read_b128 v[166:169], v210 offset:1024
	ds_read_b128 v[170:173], v210 offset:2048
	ds_read_b128 v[174:177], v210 offset:3072
	ds_read_b128 v[196:199], v210 offset:4096
	ds_read_b128 v[200:203], v210 offset:5120
	ds_read_b128 v[212:215], v210 offset:6144
	ds_read_b128 v[216:219], v210 offset:7168
	global_load_lds_dwordx4 v188, s[12:13]
	s_add_i32 m0, s31, 0xe000
	s_nop 0
	global_load_lds_dwordx4 v190, s[12:13]
	s_waitcnt vmcnt(8)
	s_waitcnt lgkmcnt(0)
	s_setprio 1
	s_barrier
	v_mfma_f32_16x16x32_bf16 v[126:129], v[130:133], v[162:165], 0
	v_mfma_f32_16x16x32_bf16 v[122:125], v[138:141], v[162:165], 0
	v_mfma_f32_16x16x32_bf16 v[110:113], v[130:133], v[170:173], 0
	v_mfma_f32_16x16x32_bf16 v[106:109], v[138:141], v[170:173], 0
	v_mfma_f32_16x16x32_bf16 v[94:97], v[130:133], v[196:199], 0
	v_mfma_f32_16x16x32_bf16 v[90:93], v[138:141], v[196:199], 0
	v_mfma_f32_16x16x32_bf16 v[78:81], v[130:133], v[212:215], 0
	v_mfma_f32_16x16x32_bf16 v[74:77], v[138:141], v[212:215], 0
	v_mfma_f32_16x16x32_bf16 v[126:129], v[134:137], v[166:169], v[126:129]
	v_mfma_f32_16x16x32_bf16 v[122:125], v[142:145], v[166:169], v[122:125]
	v_mfma_f32_16x16x32_bf16 v[110:113], v[134:137], v[174:177], v[110:113]
	v_mfma_f32_16x16x32_bf16 v[106:109], v[142:145], v[174:177], v[106:109]
	v_mfma_f32_16x16x32_bf16 v[94:97], v[134:137], v[200:203], v[94:97]
	v_mfma_f32_16x16x32_bf16 v[90:93], v[142:145], v[200:203], v[90:93]
	v_mfma_f32_16x16x32_bf16 v[78:81], v[134:137], v[216:219], v[78:81]
	v_mfma_f32_16x16x32_bf16 v[74:77], v[142:145], v[216:219], v[74:77]
	s_setprio 0
	s_setprio 1
	v_mfma_f32_16x16x32_bf16 v[118:121], v[146:149], v[162:165], 0
	v_mfma_f32_16x16x32_bf16 v[114:117], v[154:157], v[162:165], 0
	v_mfma_f32_16x16x32_bf16 v[102:105], v[146:149], v[170:173], 0
	v_mfma_f32_16x16x32_bf16 v[98:101], v[154:157], v[170:173], 0
	v_mfma_f32_16x16x32_bf16 v[86:89], v[146:149], v[196:199], 0
	v_mfma_f32_16x16x32_bf16 v[82:85], v[154:157], v[196:199], 0
	v_mfma_f32_16x16x32_bf16 v[70:73], v[146:149], v[212:215], 0
	v_mfma_f32_16x16x32_bf16 v[66:69], v[154:157], v[212:215], 0
	v_mfma_f32_16x16x32_bf16 v[118:121], v[150:153], v[166:169], v[118:121]
	v_mfma_f32_16x16x32_bf16 v[114:117], v[158:161], v[166:169], v[114:117]
	v_mfma_f32_16x16x32_bf16 v[102:105], v[150:153], v[174:177], v[102:105]
	v_mfma_f32_16x16x32_bf16 v[98:101], v[158:161], v[174:177], v[98:101]
	v_mfma_f32_16x16x32_bf16 v[86:89], v[150:153], v[200:203], v[86:89]
	v_mfma_f32_16x16x32_bf16 v[82:85], v[158:161], v[200:203], v[82:85]
	v_mfma_f32_16x16x32_bf16 v[70:73], v[150:153], v[216:219], v[70:73]
	v_mfma_f32_16x16x32_bf16 v[66:69], v[158:161], v[216:219], v[66:69]
	s_barrier
	s_setprio 0
	s_add_i32 s85, s75, s29
	s_add_u32 s98, s56, 0x80
	s_addc_u32 s99, s57, 0
	s_mov_b32 m0, s85
	ds_read_b128 v[162:165], v210 offset:16384
	ds_read_b128 v[166:169], v210 offset:17408
	ds_read_b128 v[170:173], v210 offset:18432
	ds_read_b128 v[174:177], v210 offset:19456
	ds_read_b128 v[196:199], v210 offset:20480
	ds_read_b128 v[200:203], v210 offset:21504
	ds_read_b128 v[212:215], v210 offset:22528
	ds_read_b128 v[216:219], v210 offset:23552
	global_load_lds_dwordx4 v182, s[56:57]
	s_add_i32 m0, s85, 0x2000
	s_add_u32 s88, s56, 0x160000
	s_addc_u32 s89, s57, 0
	s_add_i32 s85, s76, s29
	global_load_lds_dwordx4 v186, s[56:57]
	s_mov_b32 m0, s85
	s_nop 0
	global_load_lds_dwordx4 v182, s[88:89]
	s_add_i32 m0, s85, 0x2000
	s_nop 0
	global_load_lds_dwordx4 v186, s[88:89]
	s_add_u32 s100, s58, 0x80
	s_addc_u32 s101, s59, 0
	s_mov_b32 m0, s31
	s_nop 0
	global_load_lds_dwordx4 v180, s[58:59]
	s_mov_b32 m0, s64
	s_nop 0
	global_load_lds_dwordx4 v184, s[58:59]
	s_waitcnt vmcnt(8)
	s_waitcnt lgkmcnt(0)
	s_setprio 1
	s_barrier
	v_mfma_f32_16x16x32_bf16 v[62:65], v[130:133], v[162:165], 0
	v_mfma_f32_16x16x32_bf16 v[58:61], v[138:141], v[162:165], 0
	v_mfma_f32_16x16x32_bf16 v[46:49], v[130:133], v[170:173], 0
	v_mfma_f32_16x16x32_bf16 v[42:45], v[138:141], v[170:173], 0
	v_mfma_f32_16x16x32_bf16 v[30:33], v[130:133], v[196:199], 0
	v_mfma_f32_16x16x32_bf16 v[26:29], v[138:141], v[196:199], 0
	v_mfma_f32_16x16x32_bf16 v[14:17], v[130:133], v[212:215], 0
	v_mfma_f32_16x16x32_bf16 v[10:13], v[138:141], v[212:215], 0
	v_mfma_f32_16x16x32_bf16 v[62:65], v[134:137], v[166:169], v[62:65]
	v_mfma_f32_16x16x32_bf16 v[58:61], v[142:145], v[166:169], v[58:61]
	v_mfma_f32_16x16x32_bf16 v[46:49], v[134:137], v[174:177], v[46:49]
	v_mfma_f32_16x16x32_bf16 v[42:45], v[142:145], v[174:177], v[42:45]
	v_mfma_f32_16x16x32_bf16 v[30:33], v[134:137], v[200:203], v[30:33]
	v_mfma_f32_16x16x32_bf16 v[26:29], v[142:145], v[200:203], v[26:29]
	v_mfma_f32_16x16x32_bf16 v[14:17], v[134:137], v[216:219], v[14:17]
	v_mfma_f32_16x16x32_bf16 v[10:13], v[142:145], v[216:219], v[10:13]
	s_setprio 0
	s_setprio 1
	v_mfma_f32_16x16x32_bf16 v[54:57], v[146:149], v[162:165], 0
	v_mfma_f32_16x16x32_bf16 v[50:53], v[154:157], v[162:165], 0
	v_mfma_f32_16x16x32_bf16 v[38:41], v[146:149], v[170:173], 0
	v_mfma_f32_16x16x32_bf16 v[34:37], v[154:157], v[170:173], 0
	v_mfma_f32_16x16x32_bf16 v[22:25], v[146:149], v[196:199], 0
	v_mfma_f32_16x16x32_bf16 v[18:21], v[154:157], v[196:199], 0
	v_mfma_f32_16x16x32_bf16 v[6:9], v[146:149], v[212:215], 0
	v_mfma_f32_16x16x32_bf16 v[2:5], v[154:157], v[212:215], 0
	v_mfma_f32_16x16x32_bf16 v[54:57], v[150:153], v[166:169], v[54:57]
	v_mfma_f32_16x16x32_bf16 v[50:53], v[158:161], v[166:169], v[50:53]
	v_mfma_f32_16x16x32_bf16 v[38:41], v[150:153], v[174:177], v[38:41]
	v_mfma_f32_16x16x32_bf16 v[34:37], v[158:161], v[174:177], v[34:37]
	v_mfma_f32_16x16x32_bf16 v[22:25], v[150:153], v[200:203], v[22:25]
	v_mfma_f32_16x16x32_bf16 v[18:21], v[158:161], v[200:203], v[18:21]
	v_mfma_f32_16x16x32_bf16 v[6:9], v[150:153], v[216:219], v[6:9]
	v_mfma_f32_16x16x32_bf16 v[2:5], v[158:161], v[216:219], v[2:5]
	s_barrier
	s_setprio 0
	s_add_i32 s85, 0, 0x18000
	s_add_i32 s87, 0, 0x1c000
	ds_read_b128 v[130:133], v208 offset:32768
	ds_read_b128 v[134:137], v208 offset:33792
	ds_read_b128 v[138:141], v208 offset:34816
	ds_read_b128 v[142:145], v208 offset:35840
	ds_read_b128 v[146:149], v209 offset:32768
	ds_read_b128 v[150:153], v209 offset:33792
	ds_read_b128 v[154:157], v209 offset:34816
	ds_read_b128 v[158:161], v209 offset:35840
	s_add_u32 s58, s58, 0x160000
	s_addc_u32 s59, s59, 0
	s_mov_b32 m0, s65
	ds_read_b128 v[162:165], v210 offset:32768
	ds_read_b128 v[166:169], v210 offset:33792
	ds_read_b128 v[170:173], v210 offset:34816
	ds_read_b128 v[174:177], v210 offset:35840
	ds_read_b128 v[196:199], v210 offset:36864
	ds_read_b128 v[200:203], v210 offset:37888
	ds_read_b128 v[212:215], v210 offset:38912
	ds_read_b128 v[216:219], v210 offset:39936
	global_load_lds_dwordx4 v180, s[58:59]
	s_mov_b32 m0, s66
	s_nop 0
	global_load_lds_dwordx4 v184, s[58:59]
	s_waitcnt vmcnt(8)
	s_waitcnt lgkmcnt(0)
	s_setprio 1
	s_barrier
	v_mfma_f32_16x16x32_bf16 v[126:129], v[130:133], v[162:165], v[126:129]
	v_mfma_f32_16x16x32_bf16 v[122:125], v[138:141], v[162:165], v[122:125]
	v_mfma_f32_16x16x32_bf16 v[110:113], v[130:133], v[170:173], v[110:113]
	v_mfma_f32_16x16x32_bf16 v[106:109], v[138:141], v[170:173], v[106:109]
	v_mfma_f32_16x16x32_bf16 v[94:97], v[130:133], v[196:199], v[94:97]
	v_mfma_f32_16x16x32_bf16 v[90:93], v[138:141], v[196:199], v[90:93]
	v_mfma_f32_16x16x32_bf16 v[78:81], v[130:133], v[212:215], v[78:81]
	v_mfma_f32_16x16x32_bf16 v[74:77], v[138:141], v[212:215], v[74:77]
	v_mfma_f32_16x16x32_bf16 v[126:129], v[134:137], v[166:169], v[126:129]
	v_mfma_f32_16x16x32_bf16 v[122:125], v[142:145], v[166:169], v[122:125]
	v_mfma_f32_16x16x32_bf16 v[110:113], v[134:137], v[174:177], v[110:113]
	v_mfma_f32_16x16x32_bf16 v[106:109], v[142:145], v[174:177], v[106:109]
	v_mfma_f32_16x16x32_bf16 v[94:97], v[134:137], v[200:203], v[94:97]
	v_mfma_f32_16x16x32_bf16 v[90:93], v[142:145], v[200:203], v[90:93]
	v_mfma_f32_16x16x32_bf16 v[78:81], v[134:137], v[216:219], v[78:81]
	v_mfma_f32_16x16x32_bf16 v[74:77], v[142:145], v[216:219], v[74:77]
	s_setprio 0
	s_setprio 1
	v_mfma_f32_16x16x32_bf16 v[118:121], v[146:149], v[162:165], v[118:121]
	v_mfma_f32_16x16x32_bf16 v[114:117], v[154:157], v[162:165], v[114:117]
	v_mfma_f32_16x16x32_bf16 v[102:105], v[146:149], v[170:173], v[102:105]
	v_mfma_f32_16x16x32_bf16 v[98:101], v[154:157], v[170:173], v[98:101]
	v_mfma_f32_16x16x32_bf16 v[86:89], v[146:149], v[196:199], v[86:89]
	v_mfma_f32_16x16x32_bf16 v[82:85], v[154:157], v[196:199], v[82:85]
	v_mfma_f32_16x16x32_bf16 v[70:73], v[146:149], v[212:215], v[70:73]
	v_mfma_f32_16x16x32_bf16 v[66:69], v[154:157], v[212:215], v[66:69]
	v_mfma_f32_16x16x32_bf16 v[118:121], v[150:153], v[166:169], v[118:121]
	v_mfma_f32_16x16x32_bf16 v[114:117], v[158:161], v[166:169], v[114:117]
	v_mfma_f32_16x16x32_bf16 v[102:105], v[150:153], v[174:177], v[102:105]
	v_mfma_f32_16x16x32_bf16 v[98:101], v[158:161], v[174:177], v[98:101]
	v_mfma_f32_16x16x32_bf16 v[86:89], v[150:153], v[200:203], v[86:89]
	v_mfma_f32_16x16x32_bf16 v[82:85], v[158:161], v[200:203], v[82:85]
	v_mfma_f32_16x16x32_bf16 v[70:73], v[150:153], v[216:219], v[70:73]
	v_mfma_f32_16x16x32_bf16 v[66:69], v[158:161], v[216:219], v[66:69]
	s_barrier
	s_setprio 0
	s_add_i32 s58, s85, s29
	s_mov_b32 m0, s58
	ds_read_b128 v[162:165], v210 offset:49152
	ds_read_b128 v[166:169], v210 offset:50176
	ds_read_b128 v[170:173], v210 offset:51200
	ds_read_b128 v[174:177], v210 offset:52224
	ds_read_b128 v[196:199], v210 offset:53248
	ds_read_b128 v[200:203], v210 offset:54272
	ds_read_b128 v[212:215], v210 offset:55296
	ds_read_b128 v[216:219], v210 offset:56320
	global_load_lds_dwordx4 v182, s[98:99]
	s_add_i32 m0, s58, 0x2000
	s_add_u32 s56, s56, 0x160080
	s_addc_u32 s57, s57, 0
	s_add_i32 s58, s87, s29
	global_load_lds_dwordx4 v186, s[98:99]
	s_mov_b32 m0, s58
	s_nop 0
	global_load_lds_dwordx4 v182, s[56:57]
	s_add_i32 m0, s58, 0x2000
	s_nop 0
	global_load_lds_dwordx4 v186, s[56:57]
	s_mov_b32 m0, s71
	s_nop 0
	global_load_lds_dwordx4 v180, s[100:101]
	s_mov_b32 m0, s72
	s_nop 0
	global_load_lds_dwordx4 v184, s[100:101]
	s_waitcnt vmcnt(8)
	s_waitcnt lgkmcnt(0)
	s_setprio 1
	s_barrier
	v_mfma_f32_16x16x32_bf16 v[62:65], v[130:133], v[162:165], v[62:65]
	v_mfma_f32_16x16x32_bf16 v[58:61], v[138:141], v[162:165], v[58:61]
	v_mfma_f32_16x16x32_bf16 v[46:49], v[130:133], v[170:173], v[46:49]
	v_mfma_f32_16x16x32_bf16 v[42:45], v[138:141], v[170:173], v[42:45]
	v_mfma_f32_16x16x32_bf16 v[30:33], v[130:133], v[196:199], v[30:33]
	v_mfma_f32_16x16x32_bf16 v[26:29], v[138:141], v[196:199], v[26:29]
	v_mfma_f32_16x16x32_bf16 v[14:17], v[130:133], v[212:215], v[14:17]
	v_mfma_f32_16x16x32_bf16 v[10:13], v[138:141], v[212:215], v[10:13]
	v_mfma_f32_16x16x32_bf16 v[62:65], v[134:137], v[166:169], v[62:65]
	v_mfma_f32_16x16x32_bf16 v[58:61], v[142:145], v[166:169], v[58:61]
	v_mfma_f32_16x16x32_bf16 v[46:49], v[134:137], v[174:177], v[46:49]
	v_mfma_f32_16x16x32_bf16 v[42:45], v[142:145], v[174:177], v[42:45]
	v_mfma_f32_16x16x32_bf16 v[30:33], v[134:137], v[200:203], v[30:33]
	v_mfma_f32_16x16x32_bf16 v[26:29], v[142:145], v[200:203], v[26:29]
	v_mfma_f32_16x16x32_bf16 v[14:17], v[134:137], v[216:219], v[14:17]
	v_mfma_f32_16x16x32_bf16 v[10:13], v[142:145], v[216:219], v[10:13]
	s_setprio 0
	s_setprio 1
	v_mfma_f32_16x16x32_bf16 v[54:57], v[146:149], v[162:165], v[54:57]
	v_mfma_f32_16x16x32_bf16 v[50:53], v[154:157], v[162:165], v[50:53]
	v_mfma_f32_16x16x32_bf16 v[38:41], v[146:149], v[170:173], v[38:41]
	v_mfma_f32_16x16x32_bf16 v[34:37], v[154:157], v[170:173], v[34:37]
	v_mfma_f32_16x16x32_bf16 v[22:25], v[146:149], v[196:199], v[22:25]
	v_mfma_f32_16x16x32_bf16 v[18:21], v[154:157], v[196:199], v[18:21]
	v_mfma_f32_16x16x32_bf16 v[6:9], v[146:149], v[212:215], v[6:9]
	v_mfma_f32_16x16x32_bf16 v[2:5], v[154:157], v[212:215], v[2:5]
	v_mfma_f32_16x16x32_bf16 v[54:57], v[150:153], v[166:169], v[54:57]
	v_mfma_f32_16x16x32_bf16 v[50:53], v[158:161], v[166:169], v[50:53]
	v_mfma_f32_16x16x32_bf16 v[38:41], v[150:153], v[174:177], v[38:41]
	v_mfma_f32_16x16x32_bf16 v[34:37], v[158:161], v[174:177], v[34:37]
	v_mfma_f32_16x16x32_bf16 v[22:25], v[150:153], v[200:203], v[22:25]
	v_mfma_f32_16x16x32_bf16 v[18:21], v[158:161], v[200:203], v[18:21]
	v_mfma_f32_16x16x32_bf16 v[6:9], v[150:153], v[216:219], v[6:9]
	v_mfma_f32_16x16x32_bf16 v[2:5], v[158:161], v[216:219], v[2:5]
	s_barrier
	s_setprio 0
	s_add_i32 s83, s83, 2
	s_add_u32 s12, s12, 0x100
	s_addc_u32 s13, s13, 0
	s_add_u32 s81, s81, 0x100
	s_addc_u32 s82, s82, 0
	s_cmpk_gt_u32 s83, 0x55
.LBB0_379:
	ds_read_b128 v[130:133], v208
	ds_read_b128 v[134:137], v208 offset:1024
	ds_read_b128 v[138:141], v208 offset:2048
	ds_read_b128 v[142:145], v208 offset:3072
	ds_read_b128 v[146:149], v209
	ds_read_b128 v[150:153], v209 offset:1024
	ds_read_b128 v[154:157], v209 offset:2048
	ds_read_b128 v[158:161], v209 offset:3072
	s_add_u32 s56, s12, 0xffea0080
	s_addc_u32 s57, s13, -1
	s_cmpk_eq_i32 s83, 0x54
	s_cselect_b32 s59, s43, s57
	s_cselect_b32 s58, s42, s56
	s_cselect_b32 s57, s55, s82
	s_cselect_b32 s56, s54, s81
	s_add_i32 m0, s31, 0xc000
	ds_read_b128 v[162:165], v210
	ds_read_b128 v[166:169], v210 offset:1024
	ds_read_b128 v[170:173], v210 offset:2048
	ds_read_b128 v[174:177], v210 offset:3072
	ds_read_b128 v[196:199], v210 offset:4096
	ds_read_b128 v[200:203], v210 offset:5120
	ds_read_b128 v[212:215], v210 offset:6144
	ds_read_b128 v[216:219], v210 offset:7168
	global_load_lds_dwordx4 v188, s[12:13]
	s_add_i32 m0, s31, 0xe000
	s_nop 0
	global_load_lds_dwordx4 v190, s[12:13]
	s_waitcnt vmcnt(8)
	s_waitcnt lgkmcnt(0)
	s_setprio 1
	s_barrier
	v_mfma_f32_16x16x32_bf16 v[126:129], v[130:133], v[162:165], v[126:129]
	v_mfma_f32_16x16x32_bf16 v[122:125], v[138:141], v[162:165], v[122:125]
	v_mfma_f32_16x16x32_bf16 v[110:113], v[130:133], v[170:173], v[110:113]
	v_mfma_f32_16x16x32_bf16 v[106:109], v[138:141], v[170:173], v[106:109]
	v_mfma_f32_16x16x32_bf16 v[94:97], v[130:133], v[196:199], v[94:97]
	v_mfma_f32_16x16x32_bf16 v[90:93], v[138:141], v[196:199], v[90:93]
	v_mfma_f32_16x16x32_bf16 v[78:81], v[130:133], v[212:215], v[78:81]
	v_mfma_f32_16x16x32_bf16 v[74:77], v[138:141], v[212:215], v[74:77]
	v_mfma_f32_16x16x32_bf16 v[126:129], v[134:137], v[166:169], v[126:129]
	v_mfma_f32_16x16x32_bf16 v[122:125], v[142:145], v[166:169], v[122:125]
	v_mfma_f32_16x16x32_bf16 v[110:113], v[134:137], v[174:177], v[110:113]
	v_mfma_f32_16x16x32_bf16 v[106:109], v[142:145], v[174:177], v[106:109]
	v_mfma_f32_16x16x32_bf16 v[94:97], v[134:137], v[200:203], v[94:97]
	v_mfma_f32_16x16x32_bf16 v[90:93], v[142:145], v[200:203], v[90:93]
	v_mfma_f32_16x16x32_bf16 v[78:81], v[134:137], v[216:219], v[78:81]
	v_mfma_f32_16x16x32_bf16 v[74:77], v[142:145], v[216:219], v[74:77]
	s_setprio 0
	s_setprio 1
	v_mfma_f32_16x16x32_bf16 v[118:121], v[146:149], v[162:165], v[118:121]
	v_mfma_f32_16x16x32_bf16 v[114:117], v[154:157], v[162:165], v[114:117]
	v_mfma_f32_16x16x32_bf16 v[102:105], v[146:149], v[170:173], v[102:105]
	v_mfma_f32_16x16x32_bf16 v[98:101], v[154:157], v[170:173], v[98:101]
	v_mfma_f32_16x16x32_bf16 v[86:89], v[146:149], v[196:199], v[86:89]
	v_mfma_f32_16x16x32_bf16 v[82:85], v[154:157], v[196:199], v[82:85]
	v_mfma_f32_16x16x32_bf16 v[70:73], v[146:149], v[212:215], v[70:73]
	v_mfma_f32_16x16x32_bf16 v[66:69], v[154:157], v[212:215], v[66:69]
	v_mfma_f32_16x16x32_bf16 v[118:121], v[150:153], v[166:169], v[118:121]
	v_mfma_f32_16x16x32_bf16 v[114:117], v[158:161], v[166:169], v[114:117]
	v_mfma_f32_16x16x32_bf16 v[102:105], v[150:153], v[174:177], v[102:105]
	v_mfma_f32_16x16x32_bf16 v[98:101], v[158:161], v[174:177], v[98:101]
	v_mfma_f32_16x16x32_bf16 v[86:89], v[150:153], v[200:203], v[86:89]
	v_mfma_f32_16x16x32_bf16 v[82:85], v[158:161], v[200:203], v[82:85]
	v_mfma_f32_16x16x32_bf16 v[70:73], v[150:153], v[216:219], v[70:73]
	v_mfma_f32_16x16x32_bf16 v[66:69], v[158:161], v[216:219], v[66:69]
	s_barrier
	s_setprio 0
	s_add_i32 s85, s75, s29
	s_add_u32 s98, s56, 0x80
	s_addc_u32 s99, s57, 0
	s_mov_b32 m0, s85
	ds_read_b128 v[162:165], v210 offset:16384
	ds_read_b128 v[166:169], v210 offset:17408
	ds_read_b128 v[170:173], v210 offset:18432
	ds_read_b128 v[174:177], v210 offset:19456
	ds_read_b128 v[196:199], v210 offset:20480
	ds_read_b128 v[200:203], v210 offset:21504
	ds_read_b128 v[212:215], v210 offset:22528
	ds_read_b128 v[216:219], v210 offset:23552
	global_load_lds_dwordx4 v182, s[56:57]
	s_add_i32 m0, s85, 0x2000
	s_add_u32 s88, s56, 0x160000
	s_addc_u32 s89, s57, 0
	s_add_i32 s85, s76, s29
	global_load_lds_dwordx4 v186, s[56:57]
	s_mov_b32 m0, s85
	s_nop 0
	global_load_lds_dwordx4 v182, s[88:89]
	s_add_i32 m0, s85, 0x2000
	s_nop 0
	global_load_lds_dwordx4 v186, s[88:89]
	s_add_u32 s100, s58, 0x80
	s_addc_u32 s101, s59, 0
	s_mov_b32 m0, s31
	s_nop 0
	global_load_lds_dwordx4 v180, s[58:59]
	s_mov_b32 m0, s64
	s_nop 0
	global_load_lds_dwordx4 v184, s[58:59]
	s_waitcnt vmcnt(8)
	s_waitcnt lgkmcnt(0)
	s_setprio 1
	s_barrier
	v_mfma_f32_16x16x32_bf16 v[62:65], v[130:133], v[162:165], v[62:65]
	v_mfma_f32_16x16x32_bf16 v[58:61], v[138:141], v[162:165], v[58:61]
	v_mfma_f32_16x16x32_bf16 v[46:49], v[130:133], v[170:173], v[46:49]
	v_mfma_f32_16x16x32_bf16 v[42:45], v[138:141], v[170:173], v[42:45]
	v_mfma_f32_16x16x32_bf16 v[30:33], v[130:133], v[196:199], v[30:33]
	v_mfma_f32_16x16x32_bf16 v[26:29], v[138:141], v[196:199], v[26:29]
	v_mfma_f32_16x16x32_bf16 v[14:17], v[130:133], v[212:215], v[14:17]
	v_mfma_f32_16x16x32_bf16 v[10:13], v[138:141], v[212:215], v[10:13]
	v_mfma_f32_16x16x32_bf16 v[62:65], v[134:137], v[166:169], v[62:65]
	v_mfma_f32_16x16x32_bf16 v[58:61], v[142:145], v[166:169], v[58:61]
	v_mfma_f32_16x16x32_bf16 v[46:49], v[134:137], v[174:177], v[46:49]
	v_mfma_f32_16x16x32_bf16 v[42:45], v[142:145], v[174:177], v[42:45]
	v_mfma_f32_16x16x32_bf16 v[30:33], v[134:137], v[200:203], v[30:33]
	v_mfma_f32_16x16x32_bf16 v[26:29], v[142:145], v[200:203], v[26:29]
	v_mfma_f32_16x16x32_bf16 v[14:17], v[134:137], v[216:219], v[14:17]
	v_mfma_f32_16x16x32_bf16 v[10:13], v[142:145], v[216:219], v[10:13]
	s_setprio 0
	s_setprio 1
	v_mfma_f32_16x16x32_bf16 v[54:57], v[146:149], v[162:165], v[54:57]
	v_mfma_f32_16x16x32_bf16 v[50:53], v[154:157], v[162:165], v[50:53]
	v_mfma_f32_16x16x32_bf16 v[38:41], v[146:149], v[170:173], v[38:41]
	v_mfma_f32_16x16x32_bf16 v[34:37], v[154:157], v[170:173], v[34:37]
	v_mfma_f32_16x16x32_bf16 v[22:25], v[146:149], v[196:199], v[22:25]
	v_mfma_f32_16x16x32_bf16 v[18:21], v[154:157], v[196:199], v[18:21]
	v_mfma_f32_16x16x32_bf16 v[6:9], v[146:149], v[212:215], v[6:9]
	v_mfma_f32_16x16x32_bf16 v[2:5], v[154:157], v[212:215], v[2:5]
	v_mfma_f32_16x16x32_bf16 v[54:57], v[150:153], v[166:169], v[54:57]
	v_mfma_f32_16x16x32_bf16 v[50:53], v[158:161], v[166:169], v[50:53]
	v_mfma_f32_16x16x32_bf16 v[38:41], v[150:153], v[174:177], v[38:41]
	v_mfma_f32_16x16x32_bf16 v[34:37], v[158:161], v[174:177], v[34:37]
	v_mfma_f32_16x16x32_bf16 v[22:25], v[150:153], v[200:203], v[22:25]
	v_mfma_f32_16x16x32_bf16 v[18:21], v[158:161], v[200:203], v[18:21]
	v_mfma_f32_16x16x32_bf16 v[6:9], v[150:153], v[216:219], v[6:9]
	v_mfma_f32_16x16x32_bf16 v[2:5], v[158:161], v[216:219], v[2:5]
	s_barrier
	s_setprio 0
	s_add_i32 s85, 0, 0x18000
	s_add_i32 s87, 0, 0x1c000
	ds_read_b128 v[130:133], v208 offset:32768
	ds_read_b128 v[134:137], v208 offset:33792
	ds_read_b128 v[138:141], v208 offset:34816
	ds_read_b128 v[142:145], v208 offset:35840
	ds_read_b128 v[146:149], v209 offset:32768
	ds_read_b128 v[150:153], v209 offset:33792
	ds_read_b128 v[154:157], v209 offset:34816
	ds_read_b128 v[158:161], v209 offset:35840
	s_add_u32 s58, s58, 0x160000
	s_addc_u32 s59, s59, 0
	s_mov_b32 m0, s65
	ds_read_b128 v[162:165], v210 offset:32768
	ds_read_b128 v[166:169], v210 offset:33792
	ds_read_b128 v[170:173], v210 offset:34816
	ds_read_b128 v[174:177], v210 offset:35840
	ds_read_b128 v[196:199], v210 offset:36864
	ds_read_b128 v[200:203], v210 offset:37888
	ds_read_b128 v[212:215], v210 offset:38912
	ds_read_b128 v[216:219], v210 offset:39936
	global_load_lds_dwordx4 v180, s[58:59]
	v_lshl_add_u64 v[226:227], s[58:59], 0, v[184:185]
	s_mov_b32 m0, s66
	s_nop 0
	global_load_lds_dwordx4 v[226:227], off
	s_waitcnt vmcnt(8)
	s_waitcnt lgkmcnt(0)
	s_setprio 1
	s_barrier
	v_mfma_f32_16x16x32_bf16 v[126:129], v[130:133], v[162:165], v[126:129]
	v_mfma_f32_16x16x32_bf16 v[122:125], v[138:141], v[162:165], v[122:125]
	v_mfma_f32_16x16x32_bf16 v[110:113], v[130:133], v[170:173], v[110:113]
	v_mfma_f32_16x16x32_bf16 v[106:109], v[138:141], v[170:173], v[106:109]
	v_mfma_f32_16x16x32_bf16 v[94:97], v[130:133], v[196:199], v[94:97]
	v_mfma_f32_16x16x32_bf16 v[90:93], v[138:141], v[196:199], v[90:93]
	v_mfma_f32_16x16x32_bf16 v[78:81], v[130:133], v[212:215], v[78:81]
	v_mfma_f32_16x16x32_bf16 v[74:77], v[138:141], v[212:215], v[74:77]
	v_mfma_f32_16x16x32_bf16 v[126:129], v[134:137], v[166:169], v[126:129]
	v_mfma_f32_16x16x32_bf16 v[122:125], v[142:145], v[166:169], v[122:125]
	v_mfma_f32_16x16x32_bf16 v[110:113], v[134:137], v[174:177], v[110:113]
	v_mfma_f32_16x16x32_bf16 v[106:109], v[142:145], v[174:177], v[106:109]
	v_mfma_f32_16x16x32_bf16 v[94:97], v[134:137], v[200:203], v[94:97]
	v_mfma_f32_16x16x32_bf16 v[90:93], v[142:145], v[200:203], v[90:93]
	v_mfma_f32_16x16x32_bf16 v[78:81], v[134:137], v[216:219], v[78:81]
	v_mfma_f32_16x16x32_bf16 v[74:77], v[142:145], v[216:219], v[74:77]
	s_setprio 0
	s_setprio 1
	v_mfma_f32_16x16x32_bf16 v[118:121], v[146:149], v[162:165], v[118:121]
	v_mfma_f32_16x16x32_bf16 v[114:117], v[154:157], v[162:165], v[114:117]
	v_mfma_f32_16x16x32_bf16 v[102:105], v[146:149], v[170:173], v[102:105]
	v_mfma_f32_16x16x32_bf16 v[98:101], v[154:157], v[170:173], v[98:101]
	v_mfma_f32_16x16x32_bf16 v[86:89], v[146:149], v[196:199], v[86:89]
	v_mfma_f32_16x16x32_bf16 v[82:85], v[154:157], v[196:199], v[82:85]
	v_mfma_f32_16x16x32_bf16 v[70:73], v[146:149], v[212:215], v[70:73]
	v_mfma_f32_16x16x32_bf16 v[66:69], v[154:157], v[212:215], v[66:69]
	v_mfma_f32_16x16x32_bf16 v[118:121], v[150:153], v[166:169], v[118:121]
	v_mfma_f32_16x16x32_bf16 v[114:117], v[158:161], v[166:169], v[114:117]
	v_mfma_f32_16x16x32_bf16 v[102:105], v[150:153], v[174:177], v[102:105]
	v_mfma_f32_16x16x32_bf16 v[98:101], v[158:161], v[174:177], v[98:101]
	v_mfma_f32_16x16x32_bf16 v[86:89], v[150:153], v[200:203], v[86:89]
	v_mfma_f32_16x16x32_bf16 v[82:85], v[158:161], v[200:203], v[82:85]
	v_mfma_f32_16x16x32_bf16 v[70:73], v[150:153], v[216:219], v[70:73]
	v_mfma_f32_16x16x32_bf16 v[66:69], v[158:161], v[216:219], v[66:69]
	s_barrier
	s_setprio 0
	s_add_i32 s58, s85, s29
	s_mov_b32 m0, s58
	ds_read_b128 v[162:165], v210 offset:49152
	ds_read_b128 v[166:169], v210 offset:50176
	ds_read_b128 v[170:173], v210 offset:51200
	ds_read_b128 v[174:177], v210 offset:52224
	ds_read_b128 v[196:199], v210 offset:53248
	ds_read_b128 v[200:203], v210 offset:54272
	ds_read_b128 v[212:215], v210 offset:55296
	ds_read_b128 v[216:219], v210 offset:56320
	global_load_lds_dwordx4 v182, s[98:99]
	s_add_i32 m0, s58, 0x2000
	s_add_u32 s56, s56, 0x160080
	s_addc_u32 s57, s57, 0
	s_add_i32 s58, s87, s29
	global_load_lds_dwordx4 v186, s[98:99]
	s_mov_b32 m0, s58
	s_nop 0
	global_load_lds_dwordx4 v182, s[56:57]
	s_add_i32 m0, s58, 0x2000
	s_nop 0
	global_load_lds_dwordx4 v186, s[56:57]
	s_mov_b32 m0, s71
	s_nop 0
	global_load_lds_dwordx4 v180, s[100:101]
	s_mov_b32 m0, s72
	s_nop 0
	global_load_lds_dwordx4 v184, s[100:101]
	s_add_i32 s83, s83, 2
	s_add_u32 s12, s12, 0x100
	s_addc_u32 s13, s13, 0
	s_add_u32 s81, s81, 0x100
	s_addc_u32 s82, s82, 0
	s_cmpk_gt_u32 s83, 0x55
	s_waitcnt vmcnt(8)
	s_waitcnt lgkmcnt(0)
	s_setprio 1
	s_barrier
	v_mfma_f32_16x16x32_bf16 v[62:65], v[130:133], v[162:165], v[62:65]
	v_mfma_f32_16x16x32_bf16 v[58:61], v[138:141], v[162:165], v[58:61]
	v_mfma_f32_16x16x32_bf16 v[46:49], v[130:133], v[170:173], v[46:49]
	v_mfma_f32_16x16x32_bf16 v[42:45], v[138:141], v[170:173], v[42:45]
	v_mfma_f32_16x16x32_bf16 v[30:33], v[130:133], v[196:199], v[30:33]
	v_mfma_f32_16x16x32_bf16 v[26:29], v[138:141], v[196:199], v[26:29]
	v_mfma_f32_16x16x32_bf16 v[14:17], v[130:133], v[212:215], v[14:17]
	v_mfma_f32_16x16x32_bf16 v[10:13], v[138:141], v[212:215], v[10:13]
	v_mfma_f32_16x16x32_bf16 v[62:65], v[134:137], v[166:169], v[62:65]
	v_mfma_f32_16x16x32_bf16 v[58:61], v[142:145], v[166:169], v[58:61]
	v_mfma_f32_16x16x32_bf16 v[46:49], v[134:137], v[174:177], v[46:49]
	v_mfma_f32_16x16x32_bf16 v[42:45], v[142:145], v[174:177], v[42:45]
	v_mfma_f32_16x16x32_bf16 v[30:33], v[134:137], v[200:203], v[30:33]
	v_mfma_f32_16x16x32_bf16 v[26:29], v[142:145], v[200:203], v[26:29]
	v_mfma_f32_16x16x32_bf16 v[14:17], v[134:137], v[216:219], v[14:17]
	v_mfma_f32_16x16x32_bf16 v[10:13], v[142:145], v[216:219], v[10:13]
	s_setprio 0
	s_setprio 1
	v_mfma_f32_16x16x32_bf16 v[54:57], v[146:149], v[162:165], v[54:57]
	v_mfma_f32_16x16x32_bf16 v[50:53], v[154:157], v[162:165], v[50:53]
	v_mfma_f32_16x16x32_bf16 v[38:41], v[146:149], v[170:173], v[38:41]
	v_mfma_f32_16x16x32_bf16 v[34:37], v[154:157], v[170:173], v[34:37]
	v_mfma_f32_16x16x32_bf16 v[22:25], v[146:149], v[196:199], v[22:25]
	v_mfma_f32_16x16x32_bf16 v[18:21], v[154:157], v[196:199], v[18:21]
	v_mfma_f32_16x16x32_bf16 v[6:9], v[146:149], v[212:215], v[6:9]
	v_mfma_f32_16x16x32_bf16 v[2:5], v[154:157], v[212:215], v[2:5]
	v_mfma_f32_16x16x32_bf16 v[54:57], v[150:153], v[166:169], v[54:57]
	v_mfma_f32_16x16x32_bf16 v[50:53], v[158:161], v[166:169], v[50:53]
	v_mfma_f32_16x16x32_bf16 v[38:41], v[150:153], v[174:177], v[38:41]
	v_mfma_f32_16x16x32_bf16 v[34:37], v[158:161], v[174:177], v[34:37]
	v_mfma_f32_16x16x32_bf16 v[22:25], v[150:153], v[200:203], v[22:25]
	v_mfma_f32_16x16x32_bf16 v[18:21], v[158:161], v[200:203], v[18:21]
	v_mfma_f32_16x16x32_bf16 v[6:9], v[150:153], v[216:219], v[6:9]
	v_mfma_f32_16x16x32_bf16 v[2:5], v[158:161], v[216:219], v[2:5]
	s_barrier
	s_setprio 0
	s_cbranch_scc0 .LBB0_379
	s_and_b64 vcc, exec, s[34:35]
	s_cbranch_vccz .LBB0_382
	s_barrier

.LBB0_468:
	s_ashr_i32 s11, s10, 31
	s_lshl_b64 s[70:71], s[10:11], 20
	s_add_u32 s70, s89, s70
	s_addc_u32 s71, s90, s71
	s_and_b64 s[72:73], s[4:5], exec
	s_cselect_b32 s11, s71, s1
	s_cselect_b32 s76, s70, s0
	s_ashr_i32 s69, s68, 31
	s_lshl_b64 s[72:73], s[68:69], 20
	s_add_u32 s72, s91, s72
	s_addc_u32 s73, s92, s73
	s_and_b64 s[74:75], s[4:5], exec
	s_cselect_b32 s69, s73, s9
	s_cselect_b32 s77, s72, s8
	s_add_u32 s0, s0, 0x80080
	s_addc_u32 s1, s1, 0
	s_add_u32 s78, s8, 0x100
	s_addc_u32 s79, s9, 0
	s_mov_b32 s80, -2
	ds_read_b128 v[78:81], v204
	ds_read_b128 v[138:141], v204 offset:1024
	ds_read_b128 v[142:145], v204 offset:2048
	ds_read_b128 v[146:149], v204 offset:3072
	ds_read_b128 v[170:173], v205
	ds_read_b128 v[174:177], v205 offset:1024
	ds_read_b128 v[180:183], v205 offset:2048
	ds_read_b128 v[210:213], v205 offset:3072
	s_add_u32 s8, s0, 0xfff80080
	s_addc_u32 s9, s1, -1
	s_cmp_eq_u32 s80, 28
	s_cselect_b32 s75, s11, s9
	s_cselect_b32 s74, s76, s8
	s_cselect_b32 s9, s69, s79
	s_cselect_b32 s8, s77, s78
	s_add_i32 m0, s94, 0xc000
	ds_read_b128 v[214:217], v206
	ds_read_b128 v[218:221], v206 offset:1024
	ds_read_b128 v[222:225], v206 offset:2048
	ds_read_b128 v[226:229], v206 offset:3072
	ds_read_b128 v[230:233], v206 offset:4096
	ds_read_b128 v[234:237], v206 offset:5120
	ds_read_b128 v[238:241], v206 offset:6144
	ds_read_b128 v[242:245], v206 offset:7168
	global_load_lds_dwordx4 v162, s[0:1]
	s_add_i32 m0, s94, 0xe000
	s_nop 0
	global_load_lds_dwordx4 v164, s[0:1]
	s_waitcnt vmcnt(8)
	s_waitcnt lgkmcnt(0)
	s_setprio 1
	s_barrier
	v_mfma_f32_16x16x32_bf16 v[66:69], v[78:81], v[214:217], 0
	v_mfma_f32_16x16x32_bf16 v[62:65], v[142:145], v[214:217], 0
	v_mfma_f32_16x16x32_bf16 v[58:61], v[78:81], v[222:225], 0
	v_mfma_f32_16x16x32_bf16 v[54:57], v[142:145], v[222:225], 0
	v_mfma_f32_16x16x32_bf16 v[46:49], v[78:81], v[230:233], 0
	v_mfma_f32_16x16x32_bf16 v[42:45], v[142:145], v[230:233], 0
	v_mfma_f32_16x16x32_bf16 v[38:41], v[78:81], v[238:241], 0
	v_mfma_f32_16x16x32_bf16 v[34:37], v[142:145], v[238:241], 0
	v_mfma_f32_16x16x32_bf16 v[66:69], v[138:141], v[218:221], v[66:69]
	v_mfma_f32_16x16x32_bf16 v[62:65], v[146:149], v[218:221], v[62:65]
	v_mfma_f32_16x16x32_bf16 v[58:61], v[138:141], v[226:229], v[58:61]
	v_mfma_f32_16x16x32_bf16 v[54:57], v[146:149], v[226:229], v[54:57]
	v_mfma_f32_16x16x32_bf16 v[46:49], v[138:141], v[234:237], v[46:49]
	v_mfma_f32_16x16x32_bf16 v[42:45], v[146:149], v[234:237], v[42:45]
	v_mfma_f32_16x16x32_bf16 v[38:41], v[138:141], v[242:245], v[38:41]
	v_mfma_f32_16x16x32_bf16 v[34:37], v[146:149], v[242:245], v[34:37]
	s_setprio 0
	s_setprio 1
	v_mfma_f32_16x16x32_bf16 v[134:137], v[170:173], v[214:217], 0
	v_mfma_f32_16x16x32_bf16 v[130:133], v[180:183], v[214:217], 0
	v_mfma_f32_16x16x32_bf16 v[126:129], v[170:173], v[222:225], 0
	v_mfma_f32_16x16x32_bf16 v[122:125], v[180:183], v[222:225], 0
	v_mfma_f32_16x16x32_bf16 v[118:121], v[170:173], v[230:233], 0
	v_mfma_f32_16x16x32_bf16 v[114:117], v[180:183], v[230:233], 0
	v_mfma_f32_16x16x32_bf16 v[110:113], v[170:173], v[238:241], 0
	v_mfma_f32_16x16x32_bf16 v[106:109], v[180:183], v[238:241], 0
	v_mfma_f32_16x16x32_bf16 v[134:137], v[174:177], v[218:221], v[134:137]
	v_mfma_f32_16x16x32_bf16 v[130:133], v[210:213], v[218:221], v[130:133]
	v_mfma_f32_16x16x32_bf16 v[126:129], v[174:177], v[226:229], v[126:129]
	v_mfma_f32_16x16x32_bf16 v[122:125], v[210:213], v[226:229], v[122:125]
	v_mfma_f32_16x16x32_bf16 v[118:121], v[174:177], v[234:237], v[118:121]
	v_mfma_f32_16x16x32_bf16 v[114:117], v[210:213], v[234:237], v[114:117]
	v_mfma_f32_16x16x32_bf16 v[110:113], v[174:177], v[242:245], v[110:113]
	v_mfma_f32_16x16x32_bf16 v[106:109], v[210:213], v[242:245], v[106:109]
	s_barrier
	s_setprio 0
	s_add_i32 s81, s53, s93
	s_add_u32 s98, s8, 0x80
	s_addc_u32 s99, s9, 0
	s_mov_b32 m0, s81
	ds_read_b128 v[214:217], v206 offset:16384
	ds_read_b128 v[218:221], v206 offset:17408
	ds_read_b128 v[222:225], v206 offset:18432
	ds_read_b128 v[226:229], v206 offset:19456
	ds_read_b128 v[230:233], v206 offset:20480
	ds_read_b128 v[234:237], v206 offset:21504
	ds_read_b128 v[238:241], v206 offset:22528
	ds_read_b128 v[242:245], v206 offset:23552
	global_load_lds_dwordx4 v152, s[8:9]
	s_add_i32 m0, s81, 0x2000
	s_add_u32 s82, s8, 0x80000
	s_addc_u32 s83, s9, 0
	s_add_i32 s81, s54, s93
	global_load_lds_dwordx4 v156, s[8:9]
	s_mov_b32 m0, s81
	s_nop 0
	global_load_lds_dwordx4 v152, s[82:83]
	s_add_i32 m0, s81, 0x2000
	s_nop 0
	global_load_lds_dwordx4 v156, s[82:83]
	s_add_u32 s100, s74, 0x80
	s_addc_u32 s101, s75, 0
	s_mov_b32 m0, s94
	s_nop 0
	global_load_lds_dwordx4 v150, s[74:75]
	s_mov_b32 m0, s95
	s_nop 0
	global_load_lds_dwordx4 v154, s[74:75]
	s_waitcnt vmcnt(8)
	s_waitcnt lgkmcnt(0)
	s_setprio 1
	s_barrier
	v_mfma_f32_16x16x32_bf16 v[30:33], v[78:81], v[214:217], 0
	v_mfma_f32_16x16x32_bf16 v[26:29], v[142:145], v[214:217], 0
	v_mfma_f32_16x16x32_bf16 v[22:25], v[78:81], v[222:225], 0
	v_mfma_f32_16x16x32_bf16 v[18:21], v[142:145], v[222:225], 0
	v_mfma_f32_16x16x32_bf16 v[14:17], v[78:81], v[230:233], 0
	v_mfma_f32_16x16x32_bf16 v[10:13], v[142:145], v[230:233], 0
	v_mfma_f32_16x16x32_bf16 v[6:9], v[78:81], v[238:241], 0
	v_mfma_f32_16x16x32_bf16 v[2:5], v[142:145], v[238:241], 0
	v_mfma_f32_16x16x32_bf16 v[30:33], v[138:141], v[218:221], v[30:33]
	v_mfma_f32_16x16x32_bf16 v[26:29], v[146:149], v[218:221], v[26:29]
	v_mfma_f32_16x16x32_bf16 v[22:25], v[138:141], v[226:229], v[22:25]
	v_mfma_f32_16x16x32_bf16 v[18:21], v[146:149], v[226:229], v[18:21]
	v_mfma_f32_16x16x32_bf16 v[14:17], v[138:141], v[234:237], v[14:17]
	v_mfma_f32_16x16x32_bf16 v[10:13], v[146:149], v[234:237], v[10:13]
	v_mfma_f32_16x16x32_bf16 v[6:9], v[138:141], v[242:245], v[6:9]
	v_mfma_f32_16x16x32_bf16 v[2:5], v[146:149], v[242:245], v[2:5]
	s_setprio 0
	s_setprio 1
	v_mfma_f32_16x16x32_bf16 v[98:101], v[180:183], v[214:217], 0
	v_mfma_f32_16x16x32_bf16 v[94:97], v[170:173], v[222:225], 0
	v_mfma_f32_16x16x32_bf16 v[90:93], v[180:183], v[222:225], 0
	v_mfma_f32_16x16x32_bf16 v[86:89], v[170:173], v[230:233], 0
	v_mfma_f32_16x16x32_bf16 v[82:85], v[180:183], v[230:233], 0
	v_mfma_f32_16x16x32_bf16 v[74:77], v[170:173], v[238:241], 0
	v_mfma_f32_16x16x32_bf16 v[70:73], v[180:183], v[238:241], 0
	v_mfma_f32_16x16x32_bf16 v[78:81], v[170:173], v[214:217], 0
	v_mfma_f32_16x16x32_bf16 v[98:101], v[210:213], v[218:221], v[98:101]
	v_mfma_f32_16x16x32_bf16 v[94:97], v[174:177], v[226:229], v[94:97]
	v_mfma_f32_16x16x32_bf16 v[90:93], v[210:213], v[226:229], v[90:93]
	v_mfma_f32_16x16x32_bf16 v[86:89], v[174:177], v[234:237], v[86:89]
	v_mfma_f32_16x16x32_bf16 v[82:85], v[210:213], v[234:237], v[82:85]
	v_mfma_f32_16x16x32_bf16 v[74:77], v[174:177], v[242:245], v[74:77]
	v_mfma_f32_16x16x32_bf16 v[70:73], v[210:213], v[242:245], v[70:73]
	v_mfma_f32_16x16x32_bf16 v[78:81], v[174:177], v[218:221], v[78:81]
	s_barrier
	s_setprio 0
	s_add_i32 s81, 0, 0x18000
	s_add_i32 s82, 0, 0x1c000
	ds_read_b128 v[102:105], v204 offset:32768
	ds_read_b128 v[138:141], v204 offset:33792
	ds_read_b128 v[142:145], v204 offset:34816
	ds_read_b128 v[146:149], v204 offset:35840
	ds_read_b128 v[170:173], v205 offset:32768
	ds_read_b128 v[174:177], v205 offset:33792
	ds_read_b128 v[180:183], v205 offset:34816
	ds_read_b128 v[210:213], v205 offset:35840
	s_add_u32 s74, s74, 0x80000
	s_addc_u32 s75, s75, 0
	s_mov_b32 m0, s96
	ds_read_b128 v[214:217], v206 offset:32768
	ds_read_b128 v[218:221], v206 offset:33792
	ds_read_b128 v[222:225], v206 offset:34816
	ds_read_b128 v[226:229], v206 offset:35840
	ds_read_b128 v[230:233], v206 offset:36864
	ds_read_b128 v[234:237], v206 offset:37888
	ds_read_b128 v[238:241], v206 offset:38912
	ds_read_b128 v[242:245], v206 offset:39936
	global_load_lds_dwordx4 v150, s[74:75]
	s_mov_b32 m0, s97
	s_nop 0
	global_load_lds_dwordx4 v154, s[74:75]
	s_waitcnt vmcnt(8)
	s_waitcnt lgkmcnt(0)
	s_setprio 1
	s_barrier
	v_mfma_f32_16x16x32_bf16 v[66:69], v[102:105], v[214:217], v[66:69]
	v_mfma_f32_16x16x32_bf16 v[62:65], v[142:145], v[214:217], v[62:65]
	v_mfma_f32_16x16x32_bf16 v[58:61], v[102:105], v[222:225], v[58:61]
	v_mfma_f32_16x16x32_bf16 v[54:57], v[142:145], v[222:225], v[54:57]
	v_mfma_f32_16x16x32_bf16 v[46:49], v[102:105], v[230:233], v[46:49]
	v_mfma_f32_16x16x32_bf16 v[42:45], v[142:145], v[230:233], v[42:45]
	v_mfma_f32_16x16x32_bf16 v[38:41], v[102:105], v[238:241], v[38:41]
	v_mfma_f32_16x16x32_bf16 v[34:37], v[142:145], v[238:241], v[34:37]
	v_mfma_f32_16x16x32_bf16 v[66:69], v[138:141], v[218:221], v[66:69]
	v_mfma_f32_16x16x32_bf16 v[62:65], v[146:149], v[218:221], v[62:65]
	v_mfma_f32_16x16x32_bf16 v[58:61], v[138:141], v[226:229], v[58:61]
	v_mfma_f32_16x16x32_bf16 v[54:57], v[146:149], v[226:229], v[54:57]
	v_mfma_f32_16x16x32_bf16 v[46:49], v[138:141], v[234:237], v[46:49]
	v_mfma_f32_16x16x32_bf16 v[42:45], v[146:149], v[234:237], v[42:45]
	v_mfma_f32_16x16x32_bf16 v[38:41], v[138:141], v[242:245], v[38:41]
	v_mfma_f32_16x16x32_bf16 v[34:37], v[146:149], v[242:245], v[34:37]
	s_setprio 0
	s_setprio 1
	v_mfma_f32_16x16x32_bf16 v[134:137], v[170:173], v[214:217], v[134:137]
	v_mfma_f32_16x16x32_bf16 v[130:133], v[180:183], v[214:217], v[130:133]
	v_mfma_f32_16x16x32_bf16 v[126:129], v[170:173], v[222:225], v[126:129]
	v_mfma_f32_16x16x32_bf16 v[122:125], v[180:183], v[222:225], v[122:125]
	v_mfma_f32_16x16x32_bf16 v[118:121], v[170:173], v[230:233], v[118:121]
	v_mfma_f32_16x16x32_bf16 v[114:117], v[180:183], v[230:233], v[114:117]
	v_mfma_f32_16x16x32_bf16 v[110:113], v[170:173], v[238:241], v[110:113]
	v_mfma_f32_16x16x32_bf16 v[106:109], v[180:183], v[238:241], v[106:109]
	v_mfma_f32_16x16x32_bf16 v[134:137], v[174:177], v[218:221], v[134:137]
	v_mfma_f32_16x16x32_bf16 v[130:133], v[210:213], v[218:221], v[130:133]
	v_mfma_f32_16x16x32_bf16 v[126:129], v[174:177], v[226:229], v[126:129]
	v_mfma_f32_16x16x32_bf16 v[122:125], v[210:213], v[226:229], v[122:125]
	v_mfma_f32_16x16x32_bf16 v[118:121], v[174:177], v[234:237], v[118:121]
	v_mfma_f32_16x16x32_bf16 v[114:117], v[210:213], v[234:237], v[114:117]
	v_mfma_f32_16x16x32_bf16 v[110:113], v[174:177], v[242:245], v[110:113]
	v_mfma_f32_16x16x32_bf16 v[106:109], v[210:213], v[242:245], v[106:109]
	s_barrier
	s_setprio 0
	s_add_i32 s74, s81, s93
	s_mov_b32 m0, s74
	ds_read_b128 v[214:217], v206 offset:49152
	ds_read_b128 v[218:221], v206 offset:50176
	ds_read_b128 v[222:225], v206 offset:51200
	ds_read_b128 v[226:229], v206 offset:52224
	ds_read_b128 v[230:233], v206 offset:53248
	ds_read_b128 v[234:237], v206 offset:54272
	ds_read_b128 v[238:241], v206 offset:55296
	ds_read_b128 v[242:245], v206 offset:56320
	global_load_lds_dwordx4 v152, s[98:99]
	s_add_i32 m0, s74, 0x2000
	s_add_u32 s8, s8, 0x80080
	s_addc_u32 s9, s9, 0
	s_add_i32 s74, s82, s93
	global_load_lds_dwordx4 v156, s[98:99]
	s_mov_b32 m0, s74
	s_nop 0
	global_load_lds_dwordx4 v152, s[8:9]
	s_add_i32 m0, s74, 0x2000
	s_nop 0
	global_load_lds_dwordx4 v156, s[8:9]
	s_mov_b32 m0, s85
	s_nop 0
	global_load_lds_dwordx4 v150, s[100:101]
	s_mov_b32 m0, s18
	s_nop 0
	global_load_lds_dwordx4 v154, s[100:101]
	s_waitcnt vmcnt(8)
	s_waitcnt lgkmcnt(0)
	s_setprio 1
	s_barrier
	v_mfma_f32_16x16x32_bf16 v[30:33], v[102:105], v[214:217], v[30:33]
	v_mfma_f32_16x16x32_bf16 v[26:29], v[142:145], v[214:217], v[26:29]
	v_mfma_f32_16x16x32_bf16 v[22:25], v[102:105], v[222:225], v[22:25]
	v_mfma_f32_16x16x32_bf16 v[18:21], v[142:145], v[222:225], v[18:21]
	v_mfma_f32_16x16x32_bf16 v[14:17], v[102:105], v[230:233], v[14:17]
	v_mfma_f32_16x16x32_bf16 v[10:13], v[142:145], v[230:233], v[10:13]
	v_mfma_f32_16x16x32_bf16 v[6:9], v[102:105], v[238:241], v[6:9]
	v_mfma_f32_16x16x32_bf16 v[2:5], v[142:145], v[238:241], v[2:5]
	v_mfma_f32_16x16x32_bf16 v[30:33], v[138:141], v[218:221], v[30:33]
	v_mfma_f32_16x16x32_bf16 v[26:29], v[146:149], v[218:221], v[26:29]
	v_mfma_f32_16x16x32_bf16 v[22:25], v[138:141], v[226:229], v[22:25]
	v_mfma_f32_16x16x32_bf16 v[18:21], v[146:149], v[226:229], v[18:21]
	v_mfma_f32_16x16x32_bf16 v[14:17], v[138:141], v[234:237], v[14:17]
	v_mfma_f32_16x16x32_bf16 v[10:13], v[146:149], v[234:237], v[10:13]
	v_mfma_f32_16x16x32_bf16 v[6:9], v[138:141], v[242:245], v[6:9]
	v_mfma_f32_16x16x32_bf16 v[2:5], v[146:149], v[242:245], v[2:5]
	s_setprio 0
	s_setprio 1
	v_mfma_f32_16x16x32_bf16 v[78:81], v[170:173], v[214:217], v[78:81]
	v_mfma_f32_16x16x32_bf16 v[102:105], v[174:177], v[218:221], v[78:81]
	v_mfma_f32_16x16x32_bf16 v[78:81], v[180:183], v[214:217], v[98:101]
	v_mfma_f32_16x16x32_bf16 v[98:101], v[210:213], v[218:221], v[78:81]
	v_mfma_f32_16x16x32_bf16 v[78:81], v[170:173], v[222:225], v[94:97]
	v_mfma_f32_16x16x32_bf16 v[94:97], v[174:177], v[226:229], v[78:81]
	v_mfma_f32_16x16x32_bf16 v[78:81], v[180:183], v[222:225], v[90:93]
	v_mfma_f32_16x16x32_bf16 v[90:93], v[210:213], v[226:229], v[78:81]
	v_mfma_f32_16x16x32_bf16 v[78:81], v[170:173], v[230:233], v[86:89]
	v_mfma_f32_16x16x32_bf16 v[86:89], v[174:177], v[234:237], v[78:81]
	v_mfma_f32_16x16x32_bf16 v[78:81], v[180:183], v[230:233], v[82:85]
	v_mfma_f32_16x16x32_bf16 v[74:77], v[170:173], v[238:241], v[74:77]
	v_mfma_f32_16x16x32_bf16 v[70:73], v[180:183], v[238:241], v[70:73]
	v_mfma_f32_16x16x32_bf16 v[82:85], v[210:213], v[234:237], v[78:81]
	v_mfma_f32_16x16x32_bf16 v[74:77], v[174:177], v[242:245], v[74:77]
	v_mfma_f32_16x16x32_bf16 v[70:73], v[210:213], v[242:245], v[70:73]
	s_barrier
	s_setprio 0
	s_add_i32 s80, s80, 2
	s_add_u32 s0, s0, 0x100
	s_addc_u32 s1, s1, 0
	s_add_u32 s78, s78, 0x100
	s_addc_u32 s79, s79, 0
	s_cmp_gt_u32 s80, 29
.LBB0_469:
	ds_read_b128 v[78:81], v204
	ds_read_b128 v[138:141], v204 offset:1024
	ds_read_b128 v[142:145], v204 offset:2048
	ds_read_b128 v[146:149], v204 offset:3072
	ds_read_b128 v[170:173], v205
	ds_read_b128 v[174:177], v205 offset:1024
	ds_read_b128 v[180:183], v205 offset:2048
	ds_read_b128 v[210:213], v205 offset:3072
	s_add_u32 s8, s0, 0xfff80080
	s_addc_u32 s9, s1, -1
	s_cmp_eq_u32 s80, 28
	s_cselect_b32 s75, s11, s9
	s_cselect_b32 s74, s76, s8
	s_cselect_b32 s9, s69, s79
	s_cselect_b32 s8, s77, s78
	s_add_i32 m0, s94, 0xc000
	ds_read_b128 v[214:217], v206
	ds_read_b128 v[218:221], v206 offset:1024
	ds_read_b128 v[222:225], v206 offset:2048
	ds_read_b128 v[226:229], v206 offset:3072
	ds_read_b128 v[230:233], v206 offset:4096
	ds_read_b128 v[234:237], v206 offset:5120
	ds_read_b128 v[238:241], v206 offset:6144
	ds_read_b128 v[242:245], v206 offset:7168
	global_load_lds_dwordx4 v162, s[0:1]
	s_add_i32 m0, s94, 0xe000
	s_nop 0
	global_load_lds_dwordx4 v164, s[0:1]
	s_waitcnt vmcnt(8)
	s_waitcnt lgkmcnt(0)
	s_setprio 1
	s_barrier
	v_mfma_f32_16x16x32_bf16 v[66:69], v[78:81], v[214:217], v[66:69]
	v_mfma_f32_16x16x32_bf16 v[62:65], v[142:145], v[214:217], v[62:65]
	v_mfma_f32_16x16x32_bf16 v[58:61], v[78:81], v[222:225], v[58:61]
	v_mfma_f32_16x16x32_bf16 v[54:57], v[142:145], v[222:225], v[54:57]
	v_mfma_f32_16x16x32_bf16 v[46:49], v[78:81], v[230:233], v[46:49]
	v_mfma_f32_16x16x32_bf16 v[42:45], v[142:145], v[230:233], v[42:45]
	v_mfma_f32_16x16x32_bf16 v[38:41], v[78:81], v[238:241], v[38:41]
	v_mfma_f32_16x16x32_bf16 v[34:37], v[142:145], v[238:241], v[34:37]
	v_mfma_f32_16x16x32_bf16 v[66:69], v[138:141], v[218:221], v[66:69]
	v_mfma_f32_16x16x32_bf16 v[62:65], v[146:149], v[218:221], v[62:65]
	v_mfma_f32_16x16x32_bf16 v[58:61], v[138:141], v[226:229], v[58:61]
	v_mfma_f32_16x16x32_bf16 v[54:57], v[146:149], v[226:229], v[54:57]
	v_mfma_f32_16x16x32_bf16 v[46:49], v[138:141], v[234:237], v[46:49]
	v_mfma_f32_16x16x32_bf16 v[42:45], v[146:149], v[234:237], v[42:45]
	v_mfma_f32_16x16x32_bf16 v[38:41], v[138:141], v[242:245], v[38:41]
	v_mfma_f32_16x16x32_bf16 v[34:37], v[146:149], v[242:245], v[34:37]
	s_setprio 0
	s_setprio 1
	v_mfma_f32_16x16x32_bf16 v[134:137], v[170:173], v[214:217], v[134:137]
	v_mfma_f32_16x16x32_bf16 v[130:133], v[180:183], v[214:217], v[130:133]
	v_mfma_f32_16x16x32_bf16 v[126:129], v[170:173], v[222:225], v[126:129]
	v_mfma_f32_16x16x32_bf16 v[122:125], v[180:183], v[222:225], v[122:125]
	v_mfma_f32_16x16x32_bf16 v[118:121], v[170:173], v[230:233], v[118:121]
	v_mfma_f32_16x16x32_bf16 v[114:117], v[180:183], v[230:233], v[114:117]
	v_mfma_f32_16x16x32_bf16 v[110:113], v[170:173], v[238:241], v[110:113]
	v_mfma_f32_16x16x32_bf16 v[106:109], v[180:183], v[238:241], v[106:109]
	v_mfma_f32_16x16x32_bf16 v[134:137], v[174:177], v[218:221], v[134:137]
	v_mfma_f32_16x16x32_bf16 v[130:133], v[210:213], v[218:221], v[130:133]
	v_mfma_f32_16x16x32_bf16 v[126:129], v[174:177], v[226:229], v[126:129]
	v_mfma_f32_16x16x32_bf16 v[122:125], v[210:213], v[226:229], v[122:125]
	v_mfma_f32_16x16x32_bf16 v[118:121], v[174:177], v[234:237], v[118:121]
	v_mfma_f32_16x16x32_bf16 v[114:117], v[210:213], v[234:237], v[114:117]
	v_mfma_f32_16x16x32_bf16 v[110:113], v[174:177], v[242:245], v[110:113]
	v_mfma_f32_16x16x32_bf16 v[106:109], v[210:213], v[242:245], v[106:109]
	s_barrier
	s_setprio 0
	s_add_i32 s81, s53, s93
	s_add_u32 s98, s8, 0x80
	s_addc_u32 s99, s9, 0
	s_mov_b32 m0, s81
	ds_read_b128 v[214:217], v206 offset:16384
	ds_read_b128 v[218:221], v206 offset:17408
	ds_read_b128 v[222:225], v206 offset:18432
	ds_read_b128 v[226:229], v206 offset:19456
	ds_read_b128 v[230:233], v206 offset:20480
	ds_read_b128 v[234:237], v206 offset:21504
	ds_read_b128 v[238:241], v206 offset:22528
	ds_read_b128 v[242:245], v206 offset:23552
	global_load_lds_dwordx4 v152, s[8:9]
	s_add_i32 m0, s81, 0x2000
	s_add_u32 s82, s8, 0x80000
	s_addc_u32 s83, s9, 0
	s_add_i32 s81, s54, s93
	global_load_lds_dwordx4 v156, s[8:9]
	s_mov_b32 m0, s81
	s_nop 0
	global_load_lds_dwordx4 v152, s[82:83]
	s_add_i32 m0, s81, 0x2000
	s_nop 0
	global_load_lds_dwordx4 v156, s[82:83]
	s_add_u32 s100, s74, 0x80
	s_addc_u32 s101, s75, 0
	s_mov_b32 m0, s94
	s_nop 0
	global_load_lds_dwordx4 v150, s[74:75]
	s_mov_b32 m0, s95
	s_nop 0
	global_load_lds_dwordx4 v154, s[74:75]
	s_waitcnt vmcnt(8)
	s_waitcnt lgkmcnt(0)
	s_setprio 1
	s_barrier
	v_mfma_f32_16x16x32_bf16 v[30:33], v[78:81], v[214:217], v[30:33]
	v_mfma_f32_16x16x32_bf16 v[26:29], v[142:145], v[214:217], v[26:29]
	v_mfma_f32_16x16x32_bf16 v[22:25], v[78:81], v[222:225], v[22:25]
	v_mfma_f32_16x16x32_bf16 v[18:21], v[142:145], v[222:225], v[18:21]
	v_mfma_f32_16x16x32_bf16 v[14:17], v[78:81], v[230:233], v[14:17]
	v_mfma_f32_16x16x32_bf16 v[10:13], v[142:145], v[230:233], v[10:13]
	v_mfma_f32_16x16x32_bf16 v[6:9], v[78:81], v[238:241], v[6:9]
	v_mfma_f32_16x16x32_bf16 v[2:5], v[142:145], v[238:241], v[2:5]
	v_mfma_f32_16x16x32_bf16 v[30:33], v[138:141], v[218:221], v[30:33]
	v_mfma_f32_16x16x32_bf16 v[26:29], v[146:149], v[218:221], v[26:29]
	v_mfma_f32_16x16x32_bf16 v[22:25], v[138:141], v[226:229], v[22:25]
	v_mfma_f32_16x16x32_bf16 v[18:21], v[146:149], v[226:229], v[18:21]
	v_mfma_f32_16x16x32_bf16 v[14:17], v[138:141], v[234:237], v[14:17]
	v_mfma_f32_16x16x32_bf16 v[10:13], v[146:149], v[234:237], v[10:13]
	v_mfma_f32_16x16x32_bf16 v[6:9], v[138:141], v[242:245], v[6:9]
	v_mfma_f32_16x16x32_bf16 v[2:5], v[146:149], v[242:245], v[2:5]
	s_setprio 0
	s_setprio 1
	v_mfma_f32_16x16x32_bf16 v[98:101], v[180:183], v[214:217], v[98:101]
	v_mfma_f32_16x16x32_bf16 v[94:97], v[170:173], v[222:225], v[94:97]
	v_mfma_f32_16x16x32_bf16 v[90:93], v[180:183], v[222:225], v[90:93]
	v_mfma_f32_16x16x32_bf16 v[86:89], v[170:173], v[230:233], v[86:89]
	v_mfma_f32_16x16x32_bf16 v[82:85], v[180:183], v[230:233], v[82:85]
	v_mfma_f32_16x16x32_bf16 v[74:77], v[170:173], v[238:241], v[74:77]
	v_mfma_f32_16x16x32_bf16 v[70:73], v[180:183], v[238:241], v[70:73]
	v_mfma_f32_16x16x32_bf16 v[78:81], v[170:173], v[214:217], v[102:105]
	v_mfma_f32_16x16x32_bf16 v[98:101], v[210:213], v[218:221], v[98:101]
	v_mfma_f32_16x16x32_bf16 v[94:97], v[174:177], v[226:229], v[94:97]
	v_mfma_f32_16x16x32_bf16 v[90:93], v[210:213], v[226:229], v[90:93]
	v_mfma_f32_16x16x32_bf16 v[86:89], v[174:177], v[234:237], v[86:89]
	v_mfma_f32_16x16x32_bf16 v[82:85], v[210:213], v[234:237], v[82:85]
	v_mfma_f32_16x16x32_bf16 v[74:77], v[174:177], v[242:245], v[74:77]
	v_mfma_f32_16x16x32_bf16 v[70:73], v[210:213], v[242:245], v[70:73]
	v_mfma_f32_16x16x32_bf16 v[78:81], v[174:177], v[218:221], v[78:81]
	s_barrier
	s_setprio 0
	s_add_i32 s81, 0, 0x18000
	s_add_i32 s82, 0, 0x1c000
	ds_read_b128 v[102:105], v204 offset:32768
	ds_read_b128 v[138:141], v204 offset:33792
	ds_read_b128 v[142:145], v204 offset:34816
	ds_read_b128 v[146:149], v204 offset:35840
	ds_read_b128 v[170:173], v205 offset:32768
	ds_read_b128 v[174:177], v205 offset:33792
	ds_read_b128 v[180:183], v205 offset:34816
	ds_read_b128 v[210:213], v205 offset:35840
	s_add_u32 s74, s74, 0x80000
	s_addc_u32 s75, s75, 0
	s_mov_b32 m0, s96
	ds_read_b128 v[214:217], v206 offset:32768
	ds_read_b128 v[218:221], v206 offset:33792
	ds_read_b128 v[222:225], v206 offset:34816
	ds_read_b128 v[226:229], v206 offset:35840
	ds_read_b128 v[230:233], v206 offset:36864
	ds_read_b128 v[234:237], v206 offset:37888
	ds_read_b128 v[238:241], v206 offset:38912
	ds_read_b128 v[242:245], v206 offset:39936
	global_load_lds_dwordx4 v150, s[74:75]
	s_mov_b32 m0, s97
	s_nop 0
	global_load_lds_dwordx4 v154, s[74:75]
	s_waitcnt vmcnt(8)
	s_waitcnt lgkmcnt(0)
	s_setprio 1
	s_barrier
	v_mfma_f32_16x16x32_bf16 v[66:69], v[102:105], v[214:217], v[66:69]
	v_mfma_f32_16x16x32_bf16 v[62:65], v[142:145], v[214:217], v[62:65]
	v_mfma_f32_16x16x32_bf16 v[58:61], v[102:105], v[222:225], v[58:61]
	v_mfma_f32_16x16x32_bf16 v[54:57], v[142:145], v[222:225], v[54:57]
	v_mfma_f32_16x16x32_bf16 v[46:49], v[102:105], v[230:233], v[46:49]
	v_mfma_f32_16x16x32_bf16 v[42:45], v[142:145], v[230:233], v[42:45]
	v_mfma_f32_16x16x32_bf16 v[38:41], v[102:105], v[238:241], v[38:41]
	v_mfma_f32_16x16x32_bf16 v[34:37], v[142:145], v[238:241], v[34:37]
	v_mfma_f32_16x16x32_bf16 v[66:69], v[138:141], v[218:221], v[66:69]
	v_mfma_f32_16x16x32_bf16 v[62:65], v[146:149], v[218:221], v[62:65]
	v_mfma_f32_16x16x32_bf16 v[58:61], v[138:141], v[226:229], v[58:61]
	v_mfma_f32_16x16x32_bf16 v[54:57], v[146:149], v[226:229], v[54:57]
	v_mfma_f32_16x16x32_bf16 v[46:49], v[138:141], v[234:237], v[46:49]
	v_mfma_f32_16x16x32_bf16 v[42:45], v[146:149], v[234:237], v[42:45]
	v_mfma_f32_16x16x32_bf16 v[38:41], v[138:141], v[242:245], v[38:41]
	v_mfma_f32_16x16x32_bf16 v[34:37], v[146:149], v[242:245], v[34:37]
	s_setprio 0
	s_setprio 1
	v_mfma_f32_16x16x32_bf16 v[134:137], v[170:173], v[214:217], v[134:137]
	v_mfma_f32_16x16x32_bf16 v[130:133], v[180:183], v[214:217], v[130:133]
	v_mfma_f32_16x16x32_bf16 v[126:129], v[170:173], v[222:225], v[126:129]
	v_mfma_f32_16x16x32_bf16 v[122:125], v[180:183], v[222:225], v[122:125]
	v_mfma_f32_16x16x32_bf16 v[118:121], v[170:173], v[230:233], v[118:121]
	v_mfma_f32_16x16x32_bf16 v[114:117], v[180:183], v[230:233], v[114:117]
	v_mfma_f32_16x16x32_bf16 v[110:113], v[170:173], v[238:241], v[110:113]
	v_mfma_f32_16x16x32_bf16 v[106:109], v[180:183], v[238:241], v[106:109]
	v_mfma_f32_16x16x32_bf16 v[134:137], v[174:177], v[218:221], v[134:137]
	v_mfma_f32_16x16x32_bf16 v[130:133], v[210:213], v[218:221], v[130:133]
	v_mfma_f32_16x16x32_bf16 v[126:129], v[174:177], v[226:229], v[126:129]
	v_mfma_f32_16x16x32_bf16 v[122:125], v[210:213], v[226:229], v[122:125]
	v_mfma_f32_16x16x32_bf16 v[118:121], v[174:177], v[234:237], v[118:121]
	v_mfma_f32_16x16x32_bf16 v[114:117], v[210:213], v[234:237], v[114:117]
	v_mfma_f32_16x16x32_bf16 v[110:113], v[174:177], v[242:245], v[110:113]
	v_mfma_f32_16x16x32_bf16 v[106:109], v[210:213], v[242:245], v[106:109]
	s_barrier
	s_setprio 0
	s_add_i32 s74, s81, s93
	s_mov_b32 m0, s74
	ds_read_b128 v[214:217], v206 offset:49152
	ds_read_b128 v[218:221], v206 offset:50176
	ds_read_b128 v[222:225], v206 offset:51200
	ds_read_b128 v[226:229], v206 offset:52224
	ds_read_b128 v[230:233], v206 offset:53248
	ds_read_b128 v[234:237], v206 offset:54272
	ds_read_b128 v[238:241], v206 offset:55296
	ds_read_b128 v[242:245], v206 offset:56320
	global_load_lds_dwordx4 v152, s[98:99]
	s_add_i32 m0, s74, 0x2000
	s_add_u32 s8, s8, 0x80080
	s_addc_u32 s9, s9, 0
	s_add_i32 s74, s82, s93
	global_load_lds_dwordx4 v156, s[98:99]
	s_mov_b32 m0, s74
	s_nop 0
	global_load_lds_dwordx4 v152, s[8:9]
	s_add_i32 m0, s74, 0x2000
	s_nop 0
	global_load_lds_dwordx4 v156, s[8:9]
	s_mov_b32 m0, s85
	s_nop 0
	global_load_lds_dwordx4 v150, s[100:101]
	s_mov_b32 m0, s18
	s_nop 0
	global_load_lds_dwordx4 v154, s[100:101]
	s_add_i32 s80, s80, 2
	s_add_u32 s0, s0, 0x100
	s_addc_u32 s1, s1, 0
	s_add_u32 s78, s78, 0x100
	s_addc_u32 s79, s79, 0
	s_cmp_gt_u32 s80, 29
	s_waitcnt vmcnt(8)
	s_waitcnt lgkmcnt(0)
	s_setprio 1
	s_barrier
	v_mfma_f32_16x16x32_bf16 v[30:33], v[102:105], v[214:217], v[30:33]
	v_mfma_f32_16x16x32_bf16 v[26:29], v[142:145], v[214:217], v[26:29]
	v_mfma_f32_16x16x32_bf16 v[22:25], v[102:105], v[222:225], v[22:25]
	v_mfma_f32_16x16x32_bf16 v[18:21], v[142:145], v[222:225], v[18:21]
	v_mfma_f32_16x16x32_bf16 v[14:17], v[102:105], v[230:233], v[14:17]
	v_mfma_f32_16x16x32_bf16 v[10:13], v[142:145], v[230:233], v[10:13]
	v_mfma_f32_16x16x32_bf16 v[6:9], v[102:105], v[238:241], v[6:9]
	v_mfma_f32_16x16x32_bf16 v[2:5], v[142:145], v[238:241], v[2:5]
	v_mfma_f32_16x16x32_bf16 v[30:33], v[138:141], v[218:221], v[30:33]
	v_mfma_f32_16x16x32_bf16 v[26:29], v[146:149], v[218:221], v[26:29]
	v_mfma_f32_16x16x32_bf16 v[22:25], v[138:141], v[226:229], v[22:25]
	v_mfma_f32_16x16x32_bf16 v[18:21], v[146:149], v[226:229], v[18:21]
	v_mfma_f32_16x16x32_bf16 v[14:17], v[138:141], v[234:237], v[14:17]
	v_mfma_f32_16x16x32_bf16 v[10:13], v[146:149], v[234:237], v[10:13]
	v_mfma_f32_16x16x32_bf16 v[6:9], v[138:141], v[242:245], v[6:9]
	v_mfma_f32_16x16x32_bf16 v[2:5], v[146:149], v[242:245], v[2:5]
	s_setprio 0
	s_setprio 1
	v_mfma_f32_16x16x32_bf16 v[78:81], v[170:173], v[214:217], v[78:81]
	v_mfma_f32_16x16x32_bf16 v[102:105], v[174:177], v[218:221], v[78:81]
	v_mfma_f32_16x16x32_bf16 v[78:81], v[180:183], v[214:217], v[98:101]
	v_mfma_f32_16x16x32_bf16 v[98:101], v[210:213], v[218:221], v[78:81]
	v_mfma_f32_16x16x32_bf16 v[78:81], v[170:173], v[222:225], v[94:97]
	v_mfma_f32_16x16x32_bf16 v[94:97], v[174:177], v[226:229], v[78:81]
	v_mfma_f32_16x16x32_bf16 v[78:81], v[180:183], v[222:225], v[90:93]
	v_mfma_f32_16x16x32_bf16 v[90:93], v[210:213], v[226:229], v[78:81]
	v_mfma_f32_16x16x32_bf16 v[78:81], v[170:173], v[230:233], v[86:89]
	v_mfma_f32_16x16x32_bf16 v[86:89], v[174:177], v[234:237], v[78:81]
	v_mfma_f32_16x16x32_bf16 v[78:81], v[180:183], v[230:233], v[82:85]
	v_mfma_f32_16x16x32_bf16 v[74:77], v[170:173], v[238:241], v[74:77]
	v_mfma_f32_16x16x32_bf16 v[70:73], v[180:183], v[238:241], v[70:73]
	v_mfma_f32_16x16x32_bf16 v[82:85], v[210:213], v[234:237], v[78:81]
	v_mfma_f32_16x16x32_bf16 v[74:77], v[174:177], v[242:245], v[74:77]
	v_mfma_f32_16x16x32_bf16 v[70:73], v[210:213], v[242:245], v[70:73]
	s_barrier
	s_setprio 0
	s_cbranch_scc0 .LBB0_469
	s_and_b64 vcc, exec, s[58:59]
	s_cbranch_vccz .LBB0_472
	s_barrier

.LBB0_700:
	s_ashr_i32 s37, s36, 31
	s_lshl_b64 s[40:41], s[36:37], 20
	s_add_u32 s40, s18, s40
	s_addc_u32 s41, s19, s41
	s_and_b64 s[42:43], s[16:17], exec
	s_cselect_b32 s37, s41, s55
	s_cselect_b32 s75, s40, s54
	s_ashr_i32 s35, s34, 31
	s_lshl_b64 s[42:43], s[34:35], 20
	s_add_u32 s42, s28, s42
	s_addc_u32 s43, s29, s43
	s_and_b64 s[58:59], s[16:17], exec
	s_cselect_b32 s35, s43, s57
	s_cselect_b32 s76, s42, s56
	s_add_u32 s54, s54, 0x80080
	s_addc_u32 s55, s55, 0
	s_add_u32 s77, s56, 0x100
	s_addc_u32 s78, s57, 0
	s_mov_b32 s79, -2
	ds_read_b128 v[144:147], v141
	ds_read_b128 v[158:161], v141 offset:1024
	ds_read_b128 v[162:165], v141 offset:2048
	ds_read_b128 v[166:169], v141 offset:3072
	ds_read_b128 v[170:173], v142
	ds_read_b128 v[174:177], v142 offset:1024
	ds_read_b128 v[180:183], v142 offset:2048
	ds_read_b128 v[190:193], v142 offset:3072
	s_add_u32 s56, s54, 0xfff80080
	s_addc_u32 s57, s55, -1
	s_cmp_eq_u32 s79, 28
	s_cselect_b32 s59, s37, s57
	s_cselect_b32 s58, s75, s56
	s_cselect_b32 s57, s35, s78
	s_cselect_b32 s56, s76, s77
	s_add_i32 m0, s53, 0xc000
	ds_read_b128 v[194:197], v143
	ds_read_b128 v[198:201], v143 offset:1024
	ds_read_b128 v[202:205], v143 offset:2048
	ds_read_b128 v[206:209], v143 offset:3072
	ds_read_b128 v[210:213], v143 offset:4096
	ds_read_b128 v[214:217], v143 offset:5120
	ds_read_b128 v[218:221], v143 offset:6144
	ds_read_b128 v[222:225], v143 offset:7168
	global_load_lds_dwordx4 v130, s[54:55]
	s_add_i32 m0, s53, 0xe000
	s_nop 0
	global_load_lds_dwordx4 v132, s[54:55]
	s_waitcnt vmcnt(8)
	s_waitcnt lgkmcnt(0)
	s_setprio 1
	s_barrier
	v_mfma_f32_16x16x32_bf16 v[126:129], v[144:147], v[194:197], 0
	v_mfma_f32_16x16x32_bf16 v[122:125], v[162:165], v[194:197], 0
	v_mfma_f32_16x16x32_bf16 v[114:117], v[144:147], v[202:205], 0
	v_mfma_f32_16x16x32_bf16 v[106:109], v[162:165], v[202:205], 0
	v_mfma_f32_16x16x32_bf16 v[98:101], v[144:147], v[210:213], 0
	v_mfma_f32_16x16x32_bf16 v[90:93], v[162:165], v[210:213], 0
	v_mfma_f32_16x16x32_bf16 v[82:85], v[144:147], v[218:221], 0
	v_mfma_f32_16x16x32_bf16 v[74:77], v[162:165], v[218:221], 0
	v_mfma_f32_16x16x32_bf16 v[126:129], v[158:161], v[198:201], v[126:129]
	v_mfma_f32_16x16x32_bf16 v[122:125], v[166:169], v[198:201], v[122:125]
	v_mfma_f32_16x16x32_bf16 v[114:117], v[158:161], v[206:209], v[114:117]
	v_mfma_f32_16x16x32_bf16 v[106:109], v[166:169], v[206:209], v[106:109]
	v_mfma_f32_16x16x32_bf16 v[98:101], v[158:161], v[214:217], v[98:101]
	v_mfma_f32_16x16x32_bf16 v[90:93], v[166:169], v[214:217], v[90:93]
	v_mfma_f32_16x16x32_bf16 v[82:85], v[158:161], v[222:225], v[82:85]
	v_mfma_f32_16x16x32_bf16 v[74:77], v[166:169], v[222:225], v[74:77]
	s_setprio 0
	s_setprio 1
	v_mfma_f32_16x16x32_bf16 v[118:121], v[170:173], v[194:197], 0
	v_mfma_f32_16x16x32_bf16 v[110:113], v[180:183], v[194:197], 0
	v_mfma_f32_16x16x32_bf16 v[102:105], v[170:173], v[202:205], 0
	v_mfma_f32_16x16x32_bf16 v[94:97], v[180:183], v[202:205], 0
	v_mfma_f32_16x16x32_bf16 v[86:89], v[170:173], v[210:213], 0
	v_mfma_f32_16x16x32_bf16 v[78:81], v[180:183], v[210:213], 0
	v_mfma_f32_16x16x32_bf16 v[70:73], v[170:173], v[218:221], 0
	v_mfma_f32_16x16x32_bf16 v[66:69], v[180:183], v[218:221], 0
	v_mfma_f32_16x16x32_bf16 v[118:121], v[174:177], v[198:201], v[118:121]
	v_mfma_f32_16x16x32_bf16 v[110:113], v[190:193], v[198:201], v[110:113]
	v_mfma_f32_16x16x32_bf16 v[102:105], v[174:177], v[206:209], v[102:105]
	v_mfma_f32_16x16x32_bf16 v[94:97], v[190:193], v[206:209], v[94:97]
	v_mfma_f32_16x16x32_bf16 v[86:89], v[174:177], v[214:217], v[86:89]
	v_mfma_f32_16x16x32_bf16 v[78:81], v[190:193], v[214:217], v[78:81]
	v_mfma_f32_16x16x32_bf16 v[70:73], v[174:177], v[222:225], v[70:73]
	v_mfma_f32_16x16x32_bf16 v[66:69], v[190:193], v[222:225], v[66:69]
	s_barrier
	s_setprio 0
	s_add_i32 s80, s68, s60
	s_add_u32 s98, s56, 0x80
	s_addc_u32 s99, s57, 0
	s_mov_b32 m0, s80
	ds_read_b128 v[194:197], v143 offset:16384
	ds_read_b128 v[198:201], v143 offset:17408
	ds_read_b128 v[202:205], v143 offset:18432
	ds_read_b128 v[206:209], v143 offset:19456
	ds_read_b128 v[210:213], v143 offset:20480
	ds_read_b128 v[214:217], v143 offset:21504
	ds_read_b128 v[218:221], v143 offset:22528
	ds_read_b128 v[222:225], v143 offset:23552
	global_load_lds_dwordx4 v152, s[56:57]
	s_add_i32 m0, s80, 0x2000
	s_add_u32 s80, s56, 0x80000
	s_addc_u32 s81, s57, 0
	s_add_i32 s82, s69, s60
	global_load_lds_dwordx4 v156, s[56:57]
	s_mov_b32 m0, s82
	s_nop 0
	global_load_lds_dwordx4 v152, s[80:81]
	s_add_i32 m0, s82, 0x2000
	s_nop 0
	global_load_lds_dwordx4 v156, s[80:81]
	s_add_u32 s100, s58, 0x80
	s_addc_u32 s101, s59, 0
	s_mov_b32 m0, s53
	s_nop 0
	global_load_lds_dwordx4 v150, s[58:59]
	s_mov_b32 m0, s61
	s_nop 0
	global_load_lds_dwordx4 v154, s[58:59]
	s_waitcnt vmcnt(8)
	s_waitcnt lgkmcnt(0)
	s_setprio 1
	s_barrier
	v_mfma_f32_16x16x32_bf16 v[62:65], v[144:147], v[194:197], 0
	v_mfma_f32_16x16x32_bf16 v[58:61], v[162:165], v[194:197], 0
	v_mfma_f32_16x16x32_bf16 v[50:53], v[144:147], v[202:205], 0
	v_mfma_f32_16x16x32_bf16 v[42:45], v[162:165], v[202:205], 0
	v_mfma_f32_16x16x32_bf16 v[34:37], v[144:147], v[210:213], 0
	v_mfma_f32_16x16x32_bf16 v[26:29], v[162:165], v[210:213], 0
	v_mfma_f32_16x16x32_bf16 v[18:21], v[144:147], v[218:221], 0
	v_mfma_f32_16x16x32_bf16 v[10:13], v[162:165], v[218:221], 0
	v_mfma_f32_16x16x32_bf16 v[62:65], v[158:161], v[198:201], v[62:65]
	v_mfma_f32_16x16x32_bf16 v[58:61], v[166:169], v[198:201], v[58:61]
	v_mfma_f32_16x16x32_bf16 v[50:53], v[158:161], v[206:209], v[50:53]
	v_mfma_f32_16x16x32_bf16 v[42:45], v[166:169], v[206:209], v[42:45]
	v_mfma_f32_16x16x32_bf16 v[34:37], v[158:161], v[214:217], v[34:37]
	v_mfma_f32_16x16x32_bf16 v[26:29], v[166:169], v[214:217], v[26:29]
	v_mfma_f32_16x16x32_bf16 v[18:21], v[158:161], v[222:225], v[18:21]
	v_mfma_f32_16x16x32_bf16 v[10:13], v[166:169], v[222:225], v[10:13]
	s_setprio 0
	s_setprio 1
	v_mfma_f32_16x16x32_bf16 v[54:57], v[170:173], v[194:197], 0
	v_mfma_f32_16x16x32_bf16 v[46:49], v[180:183], v[194:197], 0
	v_mfma_f32_16x16x32_bf16 v[38:41], v[170:173], v[202:205], 0
	v_mfma_f32_16x16x32_bf16 v[30:33], v[180:183], v[202:205], 0
	v_mfma_f32_16x16x32_bf16 v[22:25], v[170:173], v[210:213], 0
	v_mfma_f32_16x16x32_bf16 v[14:17], v[180:183], v[210:213], 0
	v_mfma_f32_16x16x32_bf16 v[6:9], v[170:173], v[218:221], 0
	v_mfma_f32_16x16x32_bf16 v[2:5], v[180:183], v[218:221], 0
	v_mfma_f32_16x16x32_bf16 v[54:57], v[174:177], v[198:201], v[54:57]
	v_mfma_f32_16x16x32_bf16 v[46:49], v[190:193], v[198:201], v[46:49]
	v_mfma_f32_16x16x32_bf16 v[38:41], v[174:177], v[206:209], v[38:41]
	v_mfma_f32_16x16x32_bf16 v[30:33], v[190:193], v[206:209], v[30:33]
	v_mfma_f32_16x16x32_bf16 v[22:25], v[174:177], v[214:217], v[22:25]
	v_mfma_f32_16x16x32_bf16 v[14:17], v[190:193], v[214:217], v[14:17]
	v_mfma_f32_16x16x32_bf16 v[6:9], v[174:177], v[222:225], v[6:9]
	v_mfma_f32_16x16x32_bf16 v[2:5], v[190:193], v[222:225], v[2:5]
	s_barrier
	s_setprio 0
	s_add_i32 s80, 0, 0x18000
	s_add_i32 s81, 0, 0x1c000
	ds_read_b128 v[144:147], v141 offset:32768
	ds_read_b128 v[158:161], v141 offset:33792
	ds_read_b128 v[162:165], v141 offset:34816
	ds_read_b128 v[166:169], v141 offset:35840
	ds_read_b128 v[170:173], v142 offset:32768
	ds_read_b128 v[174:177], v142 offset:33792
	ds_read_b128 v[180:183], v142 offset:34816
	ds_read_b128 v[190:193], v142 offset:35840
	s_add_u32 s58, s58, 0x80000
	s_addc_u32 s59, s59, 0
	s_mov_b32 m0, s62
	ds_read_b128 v[194:197], v143 offset:32768
	ds_read_b128 v[198:201], v143 offset:33792
	ds_read_b128 v[202:205], v143 offset:34816
	ds_read_b128 v[206:209], v143 offset:35840
	ds_read_b128 v[210:213], v143 offset:36864
	ds_read_b128 v[214:217], v143 offset:37888
	ds_read_b128 v[218:221], v143 offset:38912
	ds_read_b128 v[222:225], v143 offset:39936
	global_load_lds_dwordx4 v150, s[58:59]
	s_mov_b32 m0, s63
	s_nop 0
	global_load_lds_dwordx4 v154, s[58:59]
	s_waitcnt vmcnt(8)
	s_waitcnt lgkmcnt(0)
	s_setprio 1
	s_barrier
	v_mfma_f32_16x16x32_bf16 v[126:129], v[144:147], v[194:197], v[126:129]
	v_mfma_f32_16x16x32_bf16 v[122:125], v[162:165], v[194:197], v[122:125]
	v_mfma_f32_16x16x32_bf16 v[114:117], v[144:147], v[202:205], v[114:117]
	v_mfma_f32_16x16x32_bf16 v[106:109], v[162:165], v[202:205], v[106:109]
	v_mfma_f32_16x16x32_bf16 v[98:101], v[144:147], v[210:213], v[98:101]
	v_mfma_f32_16x16x32_bf16 v[90:93], v[162:165], v[210:213], v[90:93]
	v_mfma_f32_16x16x32_bf16 v[82:85], v[144:147], v[218:221], v[82:85]
	v_mfma_f32_16x16x32_bf16 v[74:77], v[162:165], v[218:221], v[74:77]
	v_mfma_f32_16x16x32_bf16 v[126:129], v[158:161], v[198:201], v[126:129]
	v_mfma_f32_16x16x32_bf16 v[122:125], v[166:169], v[198:201], v[122:125]
	v_mfma_f32_16x16x32_bf16 v[114:117], v[158:161], v[206:209], v[114:117]
	v_mfma_f32_16x16x32_bf16 v[106:109], v[166:169], v[206:209], v[106:109]
	v_mfma_f32_16x16x32_bf16 v[98:101], v[158:161], v[214:217], v[98:101]
	v_mfma_f32_16x16x32_bf16 v[90:93], v[166:169], v[214:217], v[90:93]
	v_mfma_f32_16x16x32_bf16 v[82:85], v[158:161], v[222:225], v[82:85]
	v_mfma_f32_16x16x32_bf16 v[74:77], v[166:169], v[222:225], v[74:77]
	s_setprio 0
	s_setprio 1
	v_mfma_f32_16x16x32_bf16 v[118:121], v[170:173], v[194:197], v[118:121]
	v_mfma_f32_16x16x32_bf16 v[110:113], v[180:183], v[194:197], v[110:113]
	v_mfma_f32_16x16x32_bf16 v[102:105], v[170:173], v[202:205], v[102:105]
	v_mfma_f32_16x16x32_bf16 v[94:97], v[180:183], v[202:205], v[94:97]
	v_mfma_f32_16x16x32_bf16 v[86:89], v[170:173], v[210:213], v[86:89]
	v_mfma_f32_16x16x32_bf16 v[78:81], v[180:183], v[210:213], v[78:81]
	v_mfma_f32_16x16x32_bf16 v[70:73], v[170:173], v[218:221], v[70:73]
	v_mfma_f32_16x16x32_bf16 v[66:69], v[180:183], v[218:221], v[66:69]
	v_mfma_f32_16x16x32_bf16 v[118:121], v[174:177], v[198:201], v[118:121]
	v_mfma_f32_16x16x32_bf16 v[110:113], v[190:193], v[198:201], v[110:113]
	v_mfma_f32_16x16x32_bf16 v[102:105], v[174:177], v[206:209], v[102:105]
	v_mfma_f32_16x16x32_bf16 v[94:97], v[190:193], v[206:209], v[94:97]
	v_mfma_f32_16x16x32_bf16 v[86:89], v[174:177], v[214:217], v[86:89]
	v_mfma_f32_16x16x32_bf16 v[78:81], v[190:193], v[214:217], v[78:81]
	v_mfma_f32_16x16x32_bf16 v[70:73], v[174:177], v[222:225], v[70:73]
	v_mfma_f32_16x16x32_bf16 v[66:69], v[190:193], v[222:225], v[66:69]
	s_barrier
	s_setprio 0
	s_add_i32 s58, s80, s60
	s_mov_b32 m0, s58
	ds_read_b128 v[194:197], v143 offset:49152
	ds_read_b128 v[198:201], v143 offset:50176
	ds_read_b128 v[202:205], v143 offset:51200
	ds_read_b128 v[206:209], v143 offset:52224
	ds_read_b128 v[210:213], v143 offset:53248
	ds_read_b128 v[214:217], v143 offset:54272
	ds_read_b128 v[218:221], v143 offset:55296
	ds_read_b128 v[222:225], v143 offset:56320
	global_load_lds_dwordx4 v152, s[98:99]
	s_add_i32 m0, s58, 0x2000
	s_add_u32 s56, s56, 0x80080
	s_addc_u32 s57, s57, 0
	s_add_i32 s58, s81, s60
	global_load_lds_dwordx4 v156, s[98:99]
	s_mov_b32 m0, s58
	s_nop 0
	global_load_lds_dwordx4 v152, s[56:57]
	s_add_i32 m0, s58, 0x2000
	s_nop 0
	global_load_lds_dwordx4 v156, s[56:57]
	s_mov_b32 m0, s65
	s_nop 0
	global_load_lds_dwordx4 v150, s[100:101]
	s_mov_b32 m0, s66
	s_nop 0
	global_load_lds_dwordx4 v154, s[100:101]
	s_waitcnt vmcnt(8)
	s_waitcnt lgkmcnt(0)
	s_setprio 1
	s_barrier
	v_mfma_f32_16x16x32_bf16 v[62:65], v[144:147], v[194:197], v[62:65]
	v_mfma_f32_16x16x32_bf16 v[58:61], v[162:165], v[194:197], v[58:61]
	v_mfma_f32_16x16x32_bf16 v[50:53], v[144:147], v[202:205], v[50:53]
	v_mfma_f32_16x16x32_bf16 v[42:45], v[162:165], v[202:205], v[42:45]
	v_mfma_f32_16x16x32_bf16 v[34:37], v[144:147], v[210:213], v[34:37]
	v_mfma_f32_16x16x32_bf16 v[26:29], v[162:165], v[210:213], v[26:29]
	v_mfma_f32_16x16x32_bf16 v[18:21], v[144:147], v[218:221], v[18:21]
	v_mfma_f32_16x16x32_bf16 v[10:13], v[162:165], v[218:221], v[10:13]
	v_mfma_f32_16x16x32_bf16 v[62:65], v[158:161], v[198:201], v[62:65]
	v_mfma_f32_16x16x32_bf16 v[58:61], v[166:169], v[198:201], v[58:61]
	v_mfma_f32_16x16x32_bf16 v[50:53], v[158:161], v[206:209], v[50:53]
	v_mfma_f32_16x16x32_bf16 v[42:45], v[166:169], v[206:209], v[42:45]
	v_mfma_f32_16x16x32_bf16 v[34:37], v[158:161], v[214:217], v[34:37]
	v_mfma_f32_16x16x32_bf16 v[26:29], v[166:169], v[214:217], v[26:29]
	v_mfma_f32_16x16x32_bf16 v[18:21], v[158:161], v[222:225], v[18:21]
	v_mfma_f32_16x16x32_bf16 v[10:13], v[166:169], v[222:225], v[10:13]
	s_setprio 0
	s_setprio 1
	v_mfma_f32_16x16x32_bf16 v[54:57], v[170:173], v[194:197], v[54:57]
	v_mfma_f32_16x16x32_bf16 v[46:49], v[180:183], v[194:197], v[46:49]
	v_mfma_f32_16x16x32_bf16 v[38:41], v[170:173], v[202:205], v[38:41]
	v_mfma_f32_16x16x32_bf16 v[30:33], v[180:183], v[202:205], v[30:33]
	v_mfma_f32_16x16x32_bf16 v[22:25], v[170:173], v[210:213], v[22:25]
	v_mfma_f32_16x16x32_bf16 v[14:17], v[180:183], v[210:213], v[14:17]
	v_mfma_f32_16x16x32_bf16 v[6:9], v[170:173], v[218:221], v[6:9]
	v_mfma_f32_16x16x32_bf16 v[2:5], v[180:183], v[218:221], v[2:5]
	v_mfma_f32_16x16x32_bf16 v[54:57], v[174:177], v[198:201], v[54:57]
	v_mfma_f32_16x16x32_bf16 v[46:49], v[190:193], v[198:201], v[46:49]
	v_mfma_f32_16x16x32_bf16 v[38:41], v[174:177], v[206:209], v[38:41]
	v_mfma_f32_16x16x32_bf16 v[30:33], v[190:193], v[206:209], v[30:33]
	v_mfma_f32_16x16x32_bf16 v[22:25], v[174:177], v[214:217], v[22:25]
	v_mfma_f32_16x16x32_bf16 v[14:17], v[190:193], v[214:217], v[14:17]
	v_mfma_f32_16x16x32_bf16 v[6:9], v[174:177], v[222:225], v[6:9]
	v_mfma_f32_16x16x32_bf16 v[2:5], v[190:193], v[222:225], v[2:5]
	s_barrier
	s_setprio 0
	s_add_i32 s79, s79, 2
	s_add_u32 s54, s54, 0x100
	s_addc_u32 s55, s55, 0
	s_add_u32 s77, s77, 0x100
	s_addc_u32 s78, s78, 0
	s_cmp_gt_u32 s79, 29
.LBB0_701:
	ds_read_b128 v[144:147], v141
	ds_read_b128 v[158:161], v141 offset:1024
	ds_read_b128 v[162:165], v141 offset:2048
	ds_read_b128 v[166:169], v141 offset:3072
	ds_read_b128 v[170:173], v142
	ds_read_b128 v[174:177], v142 offset:1024
	ds_read_b128 v[180:183], v142 offset:2048
	ds_read_b128 v[190:193], v142 offset:3072
	s_add_u32 s56, s54, 0xfff80080
	s_addc_u32 s57, s55, -1
	s_cmp_eq_u32 s79, 28
	s_cselect_b32 s59, s37, s57
	s_cselect_b32 s58, s75, s56
	s_cselect_b32 s57, s35, s78
	s_cselect_b32 s56, s76, s77
	s_add_i32 m0, s53, 0xc000
	ds_read_b128 v[194:197], v143
	ds_read_b128 v[198:201], v143 offset:1024
	ds_read_b128 v[202:205], v143 offset:2048
	ds_read_b128 v[206:209], v143 offset:3072
	ds_read_b128 v[210:213], v143 offset:4096
	ds_read_b128 v[214:217], v143 offset:5120
	ds_read_b128 v[218:221], v143 offset:6144
	ds_read_b128 v[222:225], v143 offset:7168
	global_load_lds_dwordx4 v130, s[54:55]
	s_add_i32 m0, s53, 0xe000
	s_nop 0
	global_load_lds_dwordx4 v132, s[54:55]
	s_waitcnt vmcnt(8)
	s_waitcnt lgkmcnt(0)
	s_setprio 1
	s_barrier
	v_mfma_f32_16x16x32_bf16 v[126:129], v[144:147], v[194:197], v[126:129]
	v_mfma_f32_16x16x32_bf16 v[122:125], v[162:165], v[194:197], v[122:125]
	v_mfma_f32_16x16x32_bf16 v[114:117], v[144:147], v[202:205], v[114:117]
	v_mfma_f32_16x16x32_bf16 v[106:109], v[162:165], v[202:205], v[106:109]
	v_mfma_f32_16x16x32_bf16 v[98:101], v[144:147], v[210:213], v[98:101]
	v_mfma_f32_16x16x32_bf16 v[90:93], v[162:165], v[210:213], v[90:93]
	v_mfma_f32_16x16x32_bf16 v[82:85], v[144:147], v[218:221], v[82:85]
	v_mfma_f32_16x16x32_bf16 v[74:77], v[162:165], v[218:221], v[74:77]
	v_mfma_f32_16x16x32_bf16 v[126:129], v[158:161], v[198:201], v[126:129]
	v_mfma_f32_16x16x32_bf16 v[122:125], v[166:169], v[198:201], v[122:125]
	v_mfma_f32_16x16x32_bf16 v[114:117], v[158:161], v[206:209], v[114:117]
	v_mfma_f32_16x16x32_bf16 v[106:109], v[166:169], v[206:209], v[106:109]
	v_mfma_f32_16x16x32_bf16 v[98:101], v[158:161], v[214:217], v[98:101]
	v_mfma_f32_16x16x32_bf16 v[90:93], v[166:169], v[214:217], v[90:93]
	v_mfma_f32_16x16x32_bf16 v[82:85], v[158:161], v[222:225], v[82:85]
	v_mfma_f32_16x16x32_bf16 v[74:77], v[166:169], v[222:225], v[74:77]
	s_setprio 0
	s_setprio 1
	v_mfma_f32_16x16x32_bf16 v[118:121], v[170:173], v[194:197], v[118:121]
	v_mfma_f32_16x16x32_bf16 v[110:113], v[180:183], v[194:197], v[110:113]
	v_mfma_f32_16x16x32_bf16 v[102:105], v[170:173], v[202:205], v[102:105]
	v_mfma_f32_16x16x32_bf16 v[94:97], v[180:183], v[202:205], v[94:97]
	v_mfma_f32_16x16x32_bf16 v[86:89], v[170:173], v[210:213], v[86:89]
	v_mfma_f32_16x16x32_bf16 v[78:81], v[180:183], v[210:213], v[78:81]
	v_mfma_f32_16x16x32_bf16 v[70:73], v[170:173], v[218:221], v[70:73]
	v_mfma_f32_16x16x32_bf16 v[66:69], v[180:183], v[218:221], v[66:69]
	v_mfma_f32_16x16x32_bf16 v[118:121], v[174:177], v[198:201], v[118:121]
	v_mfma_f32_16x16x32_bf16 v[110:113], v[190:193], v[198:201], v[110:113]
	v_mfma_f32_16x16x32_bf16 v[102:105], v[174:177], v[206:209], v[102:105]
	v_mfma_f32_16x16x32_bf16 v[94:97], v[190:193], v[206:209], v[94:97]
	v_mfma_f32_16x16x32_bf16 v[86:89], v[174:177], v[214:217], v[86:89]
	v_mfma_f32_16x16x32_bf16 v[78:81], v[190:193], v[214:217], v[78:81]
	v_mfma_f32_16x16x32_bf16 v[70:73], v[174:177], v[222:225], v[70:73]
	v_mfma_f32_16x16x32_bf16 v[66:69], v[190:193], v[222:225], v[66:69]
	s_barrier
	s_setprio 0
	s_add_i32 s80, s68, s60
	s_add_u32 s98, s56, 0x80
	s_addc_u32 s99, s57, 0
	s_mov_b32 m0, s80
	ds_read_b128 v[194:197], v143 offset:16384
	ds_read_b128 v[198:201], v143 offset:17408
	ds_read_b128 v[202:205], v143 offset:18432
	ds_read_b128 v[206:209], v143 offset:19456
	ds_read_b128 v[210:213], v143 offset:20480
	ds_read_b128 v[214:217], v143 offset:21504
	ds_read_b128 v[218:221], v143 offset:22528
	ds_read_b128 v[222:225], v143 offset:23552
	global_load_lds_dwordx4 v152, s[56:57]
	s_add_i32 m0, s80, 0x2000
	s_add_u32 s80, s56, 0x80000
	s_addc_u32 s81, s57, 0
	s_add_i32 s82, s69, s60
	global_load_lds_dwordx4 v156, s[56:57]
	s_mov_b32 m0, s82
	s_nop 0
	global_load_lds_dwordx4 v152, s[80:81]
	s_add_i32 m0, s82, 0x2000
	s_nop 0
	global_load_lds_dwordx4 v156, s[80:81]
	s_add_u32 s100, s58, 0x80
	s_addc_u32 s101, s59, 0
	s_mov_b32 m0, s53
	s_nop 0
	global_load_lds_dwordx4 v150, s[58:59]
	s_mov_b32 m0, s61
	s_nop 0
	global_load_lds_dwordx4 v154, s[58:59]
	s_waitcnt vmcnt(8)
	s_waitcnt lgkmcnt(0)
	s_setprio 1
	s_barrier
	v_mfma_f32_16x16x32_bf16 v[62:65], v[144:147], v[194:197], v[62:65]
	v_mfma_f32_16x16x32_bf16 v[58:61], v[162:165], v[194:197], v[58:61]
	v_mfma_f32_16x16x32_bf16 v[50:53], v[144:147], v[202:205], v[50:53]
	v_mfma_f32_16x16x32_bf16 v[42:45], v[162:165], v[202:205], v[42:45]
	v_mfma_f32_16x16x32_bf16 v[34:37], v[144:147], v[210:213], v[34:37]
	v_mfma_f32_16x16x32_bf16 v[26:29], v[162:165], v[210:213], v[26:29]
	v_mfma_f32_16x16x32_bf16 v[18:21], v[144:147], v[218:221], v[18:21]
	v_mfma_f32_16x16x32_bf16 v[10:13], v[162:165], v[218:221], v[10:13]
	v_mfma_f32_16x16x32_bf16 v[62:65], v[158:161], v[198:201], v[62:65]
	v_mfma_f32_16x16x32_bf16 v[58:61], v[166:169], v[198:201], v[58:61]
	v_mfma_f32_16x16x32_bf16 v[50:53], v[158:161], v[206:209], v[50:53]
	v_mfma_f32_16x16x32_bf16 v[42:45], v[166:169], v[206:209], v[42:45]
	v_mfma_f32_16x16x32_bf16 v[34:37], v[158:161], v[214:217], v[34:37]
	v_mfma_f32_16x16x32_bf16 v[26:29], v[166:169], v[214:217], v[26:29]
	v_mfma_f32_16x16x32_bf16 v[18:21], v[158:161], v[222:225], v[18:21]
	v_mfma_f32_16x16x32_bf16 v[10:13], v[166:169], v[222:225], v[10:13]
	s_setprio 0
	s_setprio 1
	v_mfma_f32_16x16x32_bf16 v[54:57], v[170:173], v[194:197], v[54:57]
	v_mfma_f32_16x16x32_bf16 v[46:49], v[180:183], v[194:197], v[46:49]
	v_mfma_f32_16x16x32_bf16 v[38:41], v[170:173], v[202:205], v[38:41]
	v_mfma_f32_16x16x32_bf16 v[30:33], v[180:183], v[202:205], v[30:33]
	v_mfma_f32_16x16x32_bf16 v[22:25], v[170:173], v[210:213], v[22:25]
	v_mfma_f32_16x16x32_bf16 v[14:17], v[180:183], v[210:213], v[14:17]
	v_mfma_f32_16x16x32_bf16 v[6:9], v[170:173], v[218:221], v[6:9]
	v_mfma_f32_16x16x32_bf16 v[2:5], v[180:183], v[218:221], v[2:5]
	v_mfma_f32_16x16x32_bf16 v[54:57], v[174:177], v[198:201], v[54:57]
	v_mfma_f32_16x16x32_bf16 v[46:49], v[190:193], v[198:201], v[46:49]
	v_mfma_f32_16x16x32_bf16 v[38:41], v[174:177], v[206:209], v[38:41]
	v_mfma_f32_16x16x32_bf16 v[30:33], v[190:193], v[206:209], v[30:33]
	v_mfma_f32_16x16x32_bf16 v[22:25], v[174:177], v[214:217], v[22:25]
	v_mfma_f32_16x16x32_bf16 v[14:17], v[190:193], v[214:217], v[14:17]
	v_mfma_f32_16x16x32_bf16 v[6:9], v[174:177], v[222:225], v[6:9]
	v_mfma_f32_16x16x32_bf16 v[2:5], v[190:193], v[222:225], v[2:5]
	s_barrier
	s_setprio 0
	s_add_i32 s80, 0, 0x18000
	s_add_i32 s81, 0, 0x1c000
	ds_read_b128 v[144:147], v141 offset:32768
	ds_read_b128 v[158:161], v141 offset:33792
	ds_read_b128 v[162:165], v141 offset:34816
	ds_read_b128 v[166:169], v141 offset:35840
	ds_read_b128 v[170:173], v142 offset:32768
	ds_read_b128 v[174:177], v142 offset:33792
	ds_read_b128 v[180:183], v142 offset:34816
	ds_read_b128 v[190:193], v142 offset:35840
	s_add_u32 s58, s58, 0x80000
	s_addc_u32 s59, s59, 0
	s_mov_b32 m0, s62
	ds_read_b128 v[194:197], v143 offset:32768
	ds_read_b128 v[198:201], v143 offset:33792
	ds_read_b128 v[202:205], v143 offset:34816
	ds_read_b128 v[206:209], v143 offset:35840
	ds_read_b128 v[210:213], v143 offset:36864
	ds_read_b128 v[214:217], v143 offset:37888
	ds_read_b128 v[218:221], v143 offset:38912
	ds_read_b128 v[222:225], v143 offset:39936
	global_load_lds_dwordx4 v150, s[58:59]
	s_mov_b32 m0, s63
	s_nop 0
	global_load_lds_dwordx4 v154, s[58:59]
	s_waitcnt vmcnt(8)
	s_waitcnt lgkmcnt(0)
	s_setprio 1
	s_barrier
	v_mfma_f32_16x16x32_bf16 v[126:129], v[144:147], v[194:197], v[126:129]
	v_mfma_f32_16x16x32_bf16 v[122:125], v[162:165], v[194:197], v[122:125]
	v_mfma_f32_16x16x32_bf16 v[114:117], v[144:147], v[202:205], v[114:117]
	v_mfma_f32_16x16x32_bf16 v[106:109], v[162:165], v[202:205], v[106:109]
	v_mfma_f32_16x16x32_bf16 v[98:101], v[144:147], v[210:213], v[98:101]
	v_mfma_f32_16x16x32_bf16 v[90:93], v[162:165], v[210:213], v[90:93]
	v_mfma_f32_16x16x32_bf16 v[82:85], v[144:147], v[218:221], v[82:85]
	v_mfma_f32_16x16x32_bf16 v[74:77], v[162:165], v[218:221], v[74:77]
	v_mfma_f32_16x16x32_bf16 v[126:129], v[158:161], v[198:201], v[126:129]
	v_mfma_f32_16x16x32_bf16 v[122:125], v[166:169], v[198:201], v[122:125]
	v_mfma_f32_16x16x32_bf16 v[114:117], v[158:161], v[206:209], v[114:117]
	v_mfma_f32_16x16x32_bf16 v[106:109], v[166:169], v[206:209], v[106:109]
	v_mfma_f32_16x16x32_bf16 v[98:101], v[158:161], v[214:217], v[98:101]
	v_mfma_f32_16x16x32_bf16 v[90:93], v[166:169], v[214:217], v[90:93]
	v_mfma_f32_16x16x32_bf16 v[82:85], v[158:161], v[222:225], v[82:85]
	v_mfma_f32_16x16x32_bf16 v[74:77], v[166:169], v[222:225], v[74:77]
	s_setprio 0
	s_setprio 1
	v_mfma_f32_16x16x32_bf16 v[118:121], v[170:173], v[194:197], v[118:121]
	v_mfma_f32_16x16x32_bf16 v[110:113], v[180:183], v[194:197], v[110:113]
	v_mfma_f32_16x16x32_bf16 v[102:105], v[170:173], v[202:205], v[102:105]
	v_mfma_f32_16x16x32_bf16 v[94:97], v[180:183], v[202:205], v[94:97]
	v_mfma_f32_16x16x32_bf16 v[86:89], v[170:173], v[210:213], v[86:89]
	v_mfma_f32_16x16x32_bf16 v[78:81], v[180:183], v[210:213], v[78:81]
	v_mfma_f32_16x16x32_bf16 v[70:73], v[170:173], v[218:221], v[70:73]
	v_mfma_f32_16x16x32_bf16 v[66:69], v[180:183], v[218:221], v[66:69]
	v_mfma_f32_16x16x32_bf16 v[118:121], v[174:177], v[198:201], v[118:121]
	v_mfma_f32_16x16x32_bf16 v[110:113], v[190:193], v[198:201], v[110:113]
	v_mfma_f32_16x16x32_bf16 v[102:105], v[174:177], v[206:209], v[102:105]
	v_mfma_f32_16x16x32_bf16 v[94:97], v[190:193], v[206:209], v[94:97]
	v_mfma_f32_16x16x32_bf16 v[86:89], v[174:177], v[214:217], v[86:89]
	v_mfma_f32_16x16x32_bf16 v[78:81], v[190:193], v[214:217], v[78:81]
	v_mfma_f32_16x16x32_bf16 v[70:73], v[174:177], v[222:225], v[70:73]
	v_mfma_f32_16x16x32_bf16 v[66:69], v[190:193], v[222:225], v[66:69]
	s_barrier
	s_setprio 0
	s_add_i32 s58, s80, s60
	s_mov_b32 m0, s58
	ds_read_b128 v[194:197], v143 offset:49152
	ds_read_b128 v[198:201], v143 offset:50176
	ds_read_b128 v[202:205], v143 offset:51200
	ds_read_b128 v[206:209], v143 offset:52224
	ds_read_b128 v[210:213], v143 offset:53248
	ds_read_b128 v[214:217], v143 offset:54272
	ds_read_b128 v[218:221], v143 offset:55296
	ds_read_b128 v[222:225], v143 offset:56320
	global_load_lds_dwordx4 v152, s[98:99]
	s_add_i32 m0, s58, 0x2000
	s_add_u32 s56, s56, 0x80080
	s_addc_u32 s57, s57, 0
	s_add_i32 s58, s81, s60
	global_load_lds_dwordx4 v156, s[98:99]
	s_mov_b32 m0, s58
	s_nop 0
	global_load_lds_dwordx4 v152, s[56:57]
	s_add_i32 m0, s58, 0x2000
	s_nop 0
	global_load_lds_dwordx4 v156, s[56:57]
	s_mov_b32 m0, s65
	s_nop 0
	global_load_lds_dwordx4 v150, s[100:101]
	s_mov_b32 m0, s66
	s_nop 0
	global_load_lds_dwordx4 v154, s[100:101]
	s_add_i32 s79, s79, 2
	s_add_u32 s54, s54, 0x100
	s_addc_u32 s55, s55, 0
	s_add_u32 s77, s77, 0x100
	s_addc_u32 s78, s78, 0
	s_cmp_gt_u32 s79, 29
	s_waitcnt vmcnt(8)
	s_waitcnt lgkmcnt(0)
	s_setprio 1
	s_barrier
	v_mfma_f32_16x16x32_bf16 v[62:65], v[144:147], v[194:197], v[62:65]
	v_mfma_f32_16x16x32_bf16 v[58:61], v[162:165], v[194:197], v[58:61]
	v_mfma_f32_16x16x32_bf16 v[50:53], v[144:147], v[202:205], v[50:53]
	v_mfma_f32_16x16x32_bf16 v[42:45], v[162:165], v[202:205], v[42:45]
	v_mfma_f32_16x16x32_bf16 v[34:37], v[144:147], v[210:213], v[34:37]
	v_mfma_f32_16x16x32_bf16 v[26:29], v[162:165], v[210:213], v[26:29]
	v_mfma_f32_16x16x32_bf16 v[18:21], v[144:147], v[218:221], v[18:21]
	v_mfma_f32_16x16x32_bf16 v[10:13], v[162:165], v[218:221], v[10:13]
	v_mfma_f32_16x16x32_bf16 v[62:65], v[158:161], v[198:201], v[62:65]
	v_mfma_f32_16x16x32_bf16 v[58:61], v[166:169], v[198:201], v[58:61]
	v_mfma_f32_16x16x32_bf16 v[50:53], v[158:161], v[206:209], v[50:53]
	v_mfma_f32_16x16x32_bf16 v[42:45], v[166:169], v[206:209], v[42:45]
	v_mfma_f32_16x16x32_bf16 v[34:37], v[158:161], v[214:217], v[34:37]
	v_mfma_f32_16x16x32_bf16 v[26:29], v[166:169], v[214:217], v[26:29]
	v_mfma_f32_16x16x32_bf16 v[18:21], v[158:161], v[222:225], v[18:21]
	v_mfma_f32_16x16x32_bf16 v[10:13], v[166:169], v[222:225], v[10:13]
	s_setprio 0
	s_setprio 1
	v_mfma_f32_16x16x32_bf16 v[54:57], v[170:173], v[194:197], v[54:57]
	v_mfma_f32_16x16x32_bf16 v[46:49], v[180:183], v[194:197], v[46:49]
	v_mfma_f32_16x16x32_bf16 v[38:41], v[170:173], v[202:205], v[38:41]
	v_mfma_f32_16x16x32_bf16 v[30:33], v[180:183], v[202:205], v[30:33]
	v_mfma_f32_16x16x32_bf16 v[22:25], v[170:173], v[210:213], v[22:25]
	v_mfma_f32_16x16x32_bf16 v[14:17], v[180:183], v[210:213], v[14:17]
	v_mfma_f32_16x16x32_bf16 v[6:9], v[170:173], v[218:221], v[6:9]
	v_mfma_f32_16x16x32_bf16 v[2:5], v[180:183], v[218:221], v[2:5]
	v_mfma_f32_16x16x32_bf16 v[54:57], v[174:177], v[198:201], v[54:57]
	v_mfma_f32_16x16x32_bf16 v[46:49], v[190:193], v[198:201], v[46:49]
	v_mfma_f32_16x16x32_bf16 v[38:41], v[174:177], v[206:209], v[38:41]
	v_mfma_f32_16x16x32_bf16 v[30:33], v[190:193], v[206:209], v[30:33]
	v_mfma_f32_16x16x32_bf16 v[22:25], v[174:177], v[214:217], v[22:25]
	v_mfma_f32_16x16x32_bf16 v[14:17], v[190:193], v[214:217], v[14:17]
	v_mfma_f32_16x16x32_bf16 v[6:9], v[174:177], v[222:225], v[6:9]
	v_mfma_f32_16x16x32_bf16 v[2:5], v[190:193], v[222:225], v[2:5]
	s_barrier
	s_setprio 0
	s_cbranch_scc0 .LBB0_701
	s_and_b64 vcc, exec, s[6:7]
	s_cbranch_vccz .LBB0_704
	s_barrier

.LBB0_724:
	s_ashr_i32 s37, s36, 31
	s_lshl_b64 s[40:41], s[36:37], 20
	s_add_u32 s40, s31, s40
	s_addc_u32 s41, s60, s41
	s_and_b64 s[42:43], s[16:17], exec
	s_cselect_b32 s37, s41, s55
	s_cselect_b32 s76, s40, s54
	s_ashr_i32 s35, s34, 31
	s_lshl_b64 s[42:43], s[34:35], 20
	s_add_u32 s42, s18, s42
	s_addc_u32 s43, s19, s43
	s_and_b64 s[58:59], s[16:17], exec
	s_cselect_b32 s35, s43, s57
	s_cselect_b32 s77, s42, s56
	s_add_u32 s54, s54, 0x80080
	s_addc_u32 s55, s55, 0
	s_add_u32 s78, s56, 0x100
	s_addc_u32 s79, s57, 0
	s_mov_b32 s80, -2
	ds_read_b128 v[142:145], v139
	ds_read_b128 v[146:149], v139 offset:1024
	ds_read_b128 v[158:161], v139 offset:2048
	ds_read_b128 v[162:165], v139 offset:3072
	ds_read_b128 v[166:169], v140
	ds_read_b128 v[170:173], v140 offset:1024
	ds_read_b128 v[174:177], v140 offset:2048
	ds_read_b128 v[180:183], v140 offset:3072
	s_add_u32 s56, s54, 0xfff80080
	s_addc_u32 s57, s55, -1
	s_cmp_eq_u32 s80, 28
	s_cselect_b32 s59, s37, s57
	s_cselect_b32 s58, s76, s56
	s_cselect_b32 s57, s35, s79
	s_cselect_b32 s56, s77, s78
	s_add_i32 m0, s53, 0xc000
	ds_read_b128 v[184:187], v141
	ds_read_b128 v[188:191], v141 offset:1024
	ds_read_b128 v[192:195], v141 offset:2048
	ds_read_b128 v[196:199], v141 offset:3072
	ds_read_b128 v[200:203], v141 offset:4096
	ds_read_b128 v[204:207], v141 offset:5120
	ds_read_b128 v[208:211], v141 offset:6144
	ds_read_b128 v[212:215], v141 offset:7168
	global_load_lds_dwordx4 v130, s[54:55]
	s_add_i32 m0, s53, 0xe000
	s_nop 0
	global_load_lds_dwordx4 v132, s[54:55]
	s_waitcnt vmcnt(8)
	s_waitcnt lgkmcnt(0)
	s_setprio 1
	s_barrier
	v_mfma_f32_16x16x32_bf16 v[126:129], v[142:145], v[184:187], 0
	v_mfma_f32_16x16x32_bf16 v[122:125], v[158:161], v[184:187], 0
	v_mfma_f32_16x16x32_bf16 v[114:117], v[142:145], v[192:195], 0
	v_mfma_f32_16x16x32_bf16 v[106:109], v[158:161], v[192:195], 0
	v_mfma_f32_16x16x32_bf16 v[98:101], v[142:145], v[200:203], 0
	v_mfma_f32_16x16x32_bf16 v[90:93], v[158:161], v[200:203], 0
	v_mfma_f32_16x16x32_bf16 v[82:85], v[142:145], v[208:211], 0
	v_mfma_f32_16x16x32_bf16 v[74:77], v[158:161], v[208:211], 0
	v_mfma_f32_16x16x32_bf16 v[126:129], v[146:149], v[188:191], v[126:129]
	v_mfma_f32_16x16x32_bf16 v[122:125], v[162:165], v[188:191], v[122:125]
	v_mfma_f32_16x16x32_bf16 v[114:117], v[146:149], v[196:199], v[114:117]
	v_mfma_f32_16x16x32_bf16 v[106:109], v[162:165], v[196:199], v[106:109]
	v_mfma_f32_16x16x32_bf16 v[98:101], v[146:149], v[204:207], v[98:101]
	v_mfma_f32_16x16x32_bf16 v[90:93], v[162:165], v[204:207], v[90:93]
	v_mfma_f32_16x16x32_bf16 v[82:85], v[146:149], v[212:215], v[82:85]
	v_mfma_f32_16x16x32_bf16 v[74:77], v[162:165], v[212:215], v[74:77]
	s_setprio 0
	s_setprio 1
	v_mfma_f32_16x16x32_bf16 v[118:121], v[166:169], v[184:187], 0
	v_mfma_f32_16x16x32_bf16 v[110:113], v[174:177], v[184:187], 0
	v_mfma_f32_16x16x32_bf16 v[102:105], v[166:169], v[192:195], 0
	v_mfma_f32_16x16x32_bf16 v[94:97], v[174:177], v[192:195], 0
	v_mfma_f32_16x16x32_bf16 v[86:89], v[166:169], v[200:203], 0
	v_mfma_f32_16x16x32_bf16 v[78:81], v[174:177], v[200:203], 0
	v_mfma_f32_16x16x32_bf16 v[70:73], v[166:169], v[208:211], 0
	v_mfma_f32_16x16x32_bf16 v[66:69], v[174:177], v[208:211], 0
	v_mfma_f32_16x16x32_bf16 v[118:121], v[170:173], v[188:191], v[118:121]
	v_mfma_f32_16x16x32_bf16 v[110:113], v[180:183], v[188:191], v[110:113]
	v_mfma_f32_16x16x32_bf16 v[102:105], v[170:173], v[196:199], v[102:105]
	v_mfma_f32_16x16x32_bf16 v[94:97], v[180:183], v[196:199], v[94:97]
	v_mfma_f32_16x16x32_bf16 v[86:89], v[170:173], v[204:207], v[86:89]
	v_mfma_f32_16x16x32_bf16 v[78:81], v[180:183], v[204:207], v[78:81]
	v_mfma_f32_16x16x32_bf16 v[70:73], v[170:173], v[212:215], v[70:73]
	v_mfma_f32_16x16x32_bf16 v[66:69], v[180:183], v[212:215], v[66:69]
	s_barrier
	s_setprio 0
	s_add_i32 s81, s69, s61
	s_add_u32 s98, s56, 0x80
	s_addc_u32 s99, s57, 0
	s_mov_b32 m0, s81
	ds_read_b128 v[184:187], v141 offset:16384
	ds_read_b128 v[188:191], v141 offset:17408
	ds_read_b128 v[192:195], v141 offset:18432
	ds_read_b128 v[196:199], v141 offset:19456
	ds_read_b128 v[200:203], v141 offset:20480
	ds_read_b128 v[204:207], v141 offset:21504
	ds_read_b128 v[208:211], v141 offset:22528
	ds_read_b128 v[212:215], v141 offset:23552
	global_load_lds_dwordx4 v152, s[56:57]
	s_add_i32 m0, s81, 0x2000
	s_add_u32 s82, s56, 0x80000
	s_addc_u32 s83, s57, 0
	s_add_i32 s81, s70, s61
	global_load_lds_dwordx4 v156, s[56:57]
	s_mov_b32 m0, s81
	s_nop 0
	global_load_lds_dwordx4 v152, s[82:83]
	s_add_i32 m0, s81, 0x2000
	s_nop 0
	global_load_lds_dwordx4 v156, s[82:83]
	s_add_u32 s100, s58, 0x80
	s_addc_u32 s101, s59, 0
	s_mov_b32 m0, s53
	s_nop 0
	global_load_lds_dwordx4 v150, s[58:59]
	s_mov_b32 m0, s62
	s_nop 0
	global_load_lds_dwordx4 v154, s[58:59]
	s_waitcnt vmcnt(8)
	s_waitcnt lgkmcnt(0)
	s_setprio 1
	s_barrier
	v_mfma_f32_16x16x32_bf16 v[62:65], v[142:145], v[184:187], 0
	v_mfma_f32_16x16x32_bf16 v[58:61], v[158:161], v[184:187], 0
	v_mfma_f32_16x16x32_bf16 v[50:53], v[142:145], v[192:195], 0
	v_mfma_f32_16x16x32_bf16 v[42:45], v[158:161], v[192:195], 0
	v_mfma_f32_16x16x32_bf16 v[34:37], v[142:145], v[200:203], 0
	v_mfma_f32_16x16x32_bf16 v[26:29], v[158:161], v[200:203], 0
	v_mfma_f32_16x16x32_bf16 v[18:21], v[142:145], v[208:211], 0
	v_mfma_f32_16x16x32_bf16 v[10:13], v[158:161], v[208:211], 0
	v_mfma_f32_16x16x32_bf16 v[62:65], v[146:149], v[188:191], v[62:65]
	v_mfma_f32_16x16x32_bf16 v[58:61], v[162:165], v[188:191], v[58:61]
	v_mfma_f32_16x16x32_bf16 v[50:53], v[146:149], v[196:199], v[50:53]
	v_mfma_f32_16x16x32_bf16 v[42:45], v[162:165], v[196:199], v[42:45]
	v_mfma_f32_16x16x32_bf16 v[34:37], v[146:149], v[204:207], v[34:37]
	v_mfma_f32_16x16x32_bf16 v[26:29], v[162:165], v[204:207], v[26:29]
	v_mfma_f32_16x16x32_bf16 v[18:21], v[146:149], v[212:215], v[18:21]
	v_mfma_f32_16x16x32_bf16 v[10:13], v[162:165], v[212:215], v[10:13]
	s_setprio 0
	s_setprio 1
	v_mfma_f32_16x16x32_bf16 v[54:57], v[166:169], v[184:187], 0
	v_mfma_f32_16x16x32_bf16 v[46:49], v[174:177], v[184:187], 0
	v_mfma_f32_16x16x32_bf16 v[38:41], v[166:169], v[192:195], 0
	v_mfma_f32_16x16x32_bf16 v[30:33], v[174:177], v[192:195], 0
	v_mfma_f32_16x16x32_bf16 v[22:25], v[166:169], v[200:203], 0
	v_mfma_f32_16x16x32_bf16 v[14:17], v[174:177], v[200:203], 0
	v_mfma_f32_16x16x32_bf16 v[6:9], v[166:169], v[208:211], 0
	v_mfma_f32_16x16x32_bf16 v[2:5], v[174:177], v[208:211], 0
	v_mfma_f32_16x16x32_bf16 v[54:57], v[170:173], v[188:191], v[54:57]
	v_mfma_f32_16x16x32_bf16 v[46:49], v[180:183], v[188:191], v[46:49]
	v_mfma_f32_16x16x32_bf16 v[38:41], v[170:173], v[196:199], v[38:41]
	v_mfma_f32_16x16x32_bf16 v[30:33], v[180:183], v[196:199], v[30:33]
	v_mfma_f32_16x16x32_bf16 v[22:25], v[170:173], v[204:207], v[22:25]
	v_mfma_f32_16x16x32_bf16 v[14:17], v[180:183], v[204:207], v[14:17]
	v_mfma_f32_16x16x32_bf16 v[6:9], v[170:173], v[212:215], v[6:9]
	v_mfma_f32_16x16x32_bf16 v[2:5], v[180:183], v[212:215], v[2:5]
	s_barrier
	s_setprio 0
	s_add_i32 s81, 0, 0x18000
	s_add_i32 s82, 0, 0x1c000
	ds_read_b128 v[142:145], v139 offset:32768
	ds_read_b128 v[146:149], v139 offset:33792
	ds_read_b128 v[158:161], v139 offset:34816
	ds_read_b128 v[162:165], v139 offset:35840
	ds_read_b128 v[166:169], v140 offset:32768
	ds_read_b128 v[170:173], v140 offset:33792
	ds_read_b128 v[174:177], v140 offset:34816
	ds_read_b128 v[180:183], v140 offset:35840
	s_add_u32 s58, s58, 0x80000
	s_addc_u32 s59, s59, 0
	s_mov_b32 m0, s63
	ds_read_b128 v[184:187], v141 offset:32768
	ds_read_b128 v[188:191], v141 offset:33792
	ds_read_b128 v[192:195], v141 offset:34816
	ds_read_b128 v[196:199], v141 offset:35840
	ds_read_b128 v[200:203], v141 offset:36864
	ds_read_b128 v[204:207], v141 offset:37888
	ds_read_b128 v[208:211], v141 offset:38912
	ds_read_b128 v[212:215], v141 offset:39936
	global_load_lds_dwordx4 v150, s[58:59]
	s_mov_b32 m0, s64
	s_nop 0
	global_load_lds_dwordx4 v154, s[58:59]
	s_waitcnt vmcnt(8)
	s_waitcnt lgkmcnt(0)
	s_setprio 1
	s_barrier
	v_mfma_f32_16x16x32_bf16 v[126:129], v[142:145], v[184:187], v[126:129]
	v_mfma_f32_16x16x32_bf16 v[122:125], v[158:161], v[184:187], v[122:125]
	v_mfma_f32_16x16x32_bf16 v[114:117], v[142:145], v[192:195], v[114:117]
	v_mfma_f32_16x16x32_bf16 v[106:109], v[158:161], v[192:195], v[106:109]
	v_mfma_f32_16x16x32_bf16 v[98:101], v[142:145], v[200:203], v[98:101]
	v_mfma_f32_16x16x32_bf16 v[90:93], v[158:161], v[200:203], v[90:93]
	v_mfma_f32_16x16x32_bf16 v[82:85], v[142:145], v[208:211], v[82:85]
	v_mfma_f32_16x16x32_bf16 v[74:77], v[158:161], v[208:211], v[74:77]
	v_mfma_f32_16x16x32_bf16 v[126:129], v[146:149], v[188:191], v[126:129]
	v_mfma_f32_16x16x32_bf16 v[122:125], v[162:165], v[188:191], v[122:125]
	v_mfma_f32_16x16x32_bf16 v[114:117], v[146:149], v[196:199], v[114:117]
	v_mfma_f32_16x16x32_bf16 v[106:109], v[162:165], v[196:199], v[106:109]
	v_mfma_f32_16x16x32_bf16 v[98:101], v[146:149], v[204:207], v[98:101]
	v_mfma_f32_16x16x32_bf16 v[90:93], v[162:165], v[204:207], v[90:93]
	v_mfma_f32_16x16x32_bf16 v[82:85], v[146:149], v[212:215], v[82:85]
	v_mfma_f32_16x16x32_bf16 v[74:77], v[162:165], v[212:215], v[74:77]
	s_setprio 0
	s_setprio 1
	v_mfma_f32_16x16x32_bf16 v[118:121], v[166:169], v[184:187], v[118:121]
	v_mfma_f32_16x16x32_bf16 v[110:113], v[174:177], v[184:187], v[110:113]
	v_mfma_f32_16x16x32_bf16 v[102:105], v[166:169], v[192:195], v[102:105]
	v_mfma_f32_16x16x32_bf16 v[94:97], v[174:177], v[192:195], v[94:97]
	v_mfma_f32_16x16x32_bf16 v[86:89], v[166:169], v[200:203], v[86:89]
	v_mfma_f32_16x16x32_bf16 v[78:81], v[174:177], v[200:203], v[78:81]
	v_mfma_f32_16x16x32_bf16 v[70:73], v[166:169], v[208:211], v[70:73]
	v_mfma_f32_16x16x32_bf16 v[66:69], v[174:177], v[208:211], v[66:69]
	v_mfma_f32_16x16x32_bf16 v[118:121], v[170:173], v[188:191], v[118:121]
	v_mfma_f32_16x16x32_bf16 v[110:113], v[180:183], v[188:191], v[110:113]
	v_mfma_f32_16x16x32_bf16 v[102:105], v[170:173], v[196:199], v[102:105]
	v_mfma_f32_16x16x32_bf16 v[94:97], v[180:183], v[196:199], v[94:97]
	v_mfma_f32_16x16x32_bf16 v[86:89], v[170:173], v[204:207], v[86:89]
	v_mfma_f32_16x16x32_bf16 v[78:81], v[180:183], v[204:207], v[78:81]
	v_mfma_f32_16x16x32_bf16 v[70:73], v[170:173], v[212:215], v[70:73]
	v_mfma_f32_16x16x32_bf16 v[66:69], v[180:183], v[212:215], v[66:69]
	s_barrier
	s_setprio 0
	s_add_i32 s58, s81, s61
	s_mov_b32 m0, s58
	ds_read_b128 v[184:187], v141 offset:49152
	ds_read_b128 v[188:191], v141 offset:50176
	ds_read_b128 v[192:195], v141 offset:51200
	ds_read_b128 v[196:199], v141 offset:52224
	ds_read_b128 v[200:203], v141 offset:53248
	ds_read_b128 v[204:207], v141 offset:54272
	ds_read_b128 v[208:211], v141 offset:55296
	ds_read_b128 v[212:215], v141 offset:56320
	global_load_lds_dwordx4 v152, s[98:99]
	s_add_i32 m0, s58, 0x2000
	s_add_u32 s56, s56, 0x80080
	s_addc_u32 s57, s57, 0
	s_add_i32 s58, s82, s61
	global_load_lds_dwordx4 v156, s[98:99]
	s_mov_b32 m0, s58
	s_nop 0
	global_load_lds_dwordx4 v152, s[56:57]
	s_add_i32 m0, s58, 0x2000
	s_nop 0
	global_load_lds_dwordx4 v156, s[56:57]
	s_mov_b32 m0, s66
	s_nop 0
	global_load_lds_dwordx4 v150, s[100:101]
	s_mov_b32 m0, s67
	s_nop 0
	global_load_lds_dwordx4 v154, s[100:101]
	s_waitcnt vmcnt(8)
	s_waitcnt lgkmcnt(0)
	s_setprio 1
	s_barrier
	v_mfma_f32_16x16x32_bf16 v[62:65], v[142:145], v[184:187], v[62:65]
	v_mfma_f32_16x16x32_bf16 v[58:61], v[158:161], v[184:187], v[58:61]
	v_mfma_f32_16x16x32_bf16 v[50:53], v[142:145], v[192:195], v[50:53]
	v_mfma_f32_16x16x32_bf16 v[42:45], v[158:161], v[192:195], v[42:45]
	v_mfma_f32_16x16x32_bf16 v[34:37], v[142:145], v[200:203], v[34:37]
	v_mfma_f32_16x16x32_bf16 v[26:29], v[158:161], v[200:203], v[26:29]
	v_mfma_f32_16x16x32_bf16 v[18:21], v[142:145], v[208:211], v[18:21]
	v_mfma_f32_16x16x32_bf16 v[10:13], v[158:161], v[208:211], v[10:13]
	v_mfma_f32_16x16x32_bf16 v[62:65], v[146:149], v[188:191], v[62:65]
	v_mfma_f32_16x16x32_bf16 v[58:61], v[162:165], v[188:191], v[58:61]
	v_mfma_f32_16x16x32_bf16 v[50:53], v[146:149], v[196:199], v[50:53]
	v_mfma_f32_16x16x32_bf16 v[42:45], v[162:165], v[196:199], v[42:45]
	v_mfma_f32_16x16x32_bf16 v[34:37], v[146:149], v[204:207], v[34:37]
	v_mfma_f32_16x16x32_bf16 v[26:29], v[162:165], v[204:207], v[26:29]
	v_mfma_f32_16x16x32_bf16 v[18:21], v[146:149], v[212:215], v[18:21]
	v_mfma_f32_16x16x32_bf16 v[10:13], v[162:165], v[212:215], v[10:13]
	s_setprio 0
	s_setprio 1
	v_mfma_f32_16x16x32_bf16 v[54:57], v[166:169], v[184:187], v[54:57]
	v_mfma_f32_16x16x32_bf16 v[46:49], v[174:177], v[184:187], v[46:49]
	v_mfma_f32_16x16x32_bf16 v[38:41], v[166:169], v[192:195], v[38:41]
	v_mfma_f32_16x16x32_bf16 v[30:33], v[174:177], v[192:195], v[30:33]
	v_mfma_f32_16x16x32_bf16 v[22:25], v[166:169], v[200:203], v[22:25]
	v_mfma_f32_16x16x32_bf16 v[14:17], v[174:177], v[200:203], v[14:17]
	v_mfma_f32_16x16x32_bf16 v[6:9], v[166:169], v[208:211], v[6:9]
	v_mfma_f32_16x16x32_bf16 v[2:5], v[174:177], v[208:211], v[2:5]
	v_mfma_f32_16x16x32_bf16 v[54:57], v[170:173], v[188:191], v[54:57]
	v_mfma_f32_16x16x32_bf16 v[46:49], v[180:183], v[188:191], v[46:49]
	v_mfma_f32_16x16x32_bf16 v[38:41], v[170:173], v[196:199], v[38:41]
	v_mfma_f32_16x16x32_bf16 v[30:33], v[180:183], v[196:199], v[30:33]
	v_mfma_f32_16x16x32_bf16 v[22:25], v[170:173], v[204:207], v[22:25]
	v_mfma_f32_16x16x32_bf16 v[14:17], v[180:183], v[204:207], v[14:17]
	v_mfma_f32_16x16x32_bf16 v[6:9], v[170:173], v[212:215], v[6:9]
	v_mfma_f32_16x16x32_bf16 v[2:5], v[180:183], v[212:215], v[2:5]
	s_barrier
	s_setprio 0
	s_add_i32 s80, s80, 2
	s_add_u32 s54, s54, 0x100
	s_addc_u32 s55, s55, 0
	s_add_u32 s78, s78, 0x100
	s_addc_u32 s79, s79, 0
	s_cmp_gt_u32 s80, 29
.LBB0_725:
	ds_read_b128 v[142:145], v139
	ds_read_b128 v[146:149], v139 offset:1024
	ds_read_b128 v[158:161], v139 offset:2048
	ds_read_b128 v[162:165], v139 offset:3072
	ds_read_b128 v[166:169], v140
	ds_read_b128 v[170:173], v140 offset:1024
	ds_read_b128 v[174:177], v140 offset:2048
	ds_read_b128 v[180:183], v140 offset:3072
	s_add_u32 s56, s54, 0xfff80080
	s_addc_u32 s57, s55, -1
	s_cmp_eq_u32 s80, 28
	s_cselect_b32 s59, s37, s57
	s_cselect_b32 s58, s76, s56
	s_cselect_b32 s57, s35, s79
	s_cselect_b32 s56, s77, s78
	s_add_i32 m0, s53, 0xc000
	ds_read_b128 v[184:187], v141
	ds_read_b128 v[188:191], v141 offset:1024
	ds_read_b128 v[192:195], v141 offset:2048
	ds_read_b128 v[196:199], v141 offset:3072
	ds_read_b128 v[200:203], v141 offset:4096
	ds_read_b128 v[204:207], v141 offset:5120
	ds_read_b128 v[208:211], v141 offset:6144
	ds_read_b128 v[212:215], v141 offset:7168
	global_load_lds_dwordx4 v130, s[54:55]
	s_add_i32 m0, s53, 0xe000
	s_nop 0
	global_load_lds_dwordx4 v132, s[54:55]
	s_waitcnt vmcnt(8)
	s_waitcnt lgkmcnt(0)
	s_setprio 1
	s_barrier
	v_mfma_f32_16x16x32_bf16 v[126:129], v[142:145], v[184:187], v[126:129]
	v_mfma_f32_16x16x32_bf16 v[122:125], v[158:161], v[184:187], v[122:125]
	v_mfma_f32_16x16x32_bf16 v[114:117], v[142:145], v[192:195], v[114:117]
	v_mfma_f32_16x16x32_bf16 v[106:109], v[158:161], v[192:195], v[106:109]
	v_mfma_f32_16x16x32_bf16 v[98:101], v[142:145], v[200:203], v[98:101]
	v_mfma_f32_16x16x32_bf16 v[90:93], v[158:161], v[200:203], v[90:93]
	v_mfma_f32_16x16x32_bf16 v[82:85], v[142:145], v[208:211], v[82:85]
	v_mfma_f32_16x16x32_bf16 v[74:77], v[158:161], v[208:211], v[74:77]
	v_mfma_f32_16x16x32_bf16 v[126:129], v[146:149], v[188:191], v[126:129]
	v_mfma_f32_16x16x32_bf16 v[122:125], v[162:165], v[188:191], v[122:125]
	v_mfma_f32_16x16x32_bf16 v[114:117], v[146:149], v[196:199], v[114:117]
	v_mfma_f32_16x16x32_bf16 v[106:109], v[162:165], v[196:199], v[106:109]
	v_mfma_f32_16x16x32_bf16 v[98:101], v[146:149], v[204:207], v[98:101]
	v_mfma_f32_16x16x32_bf16 v[90:93], v[162:165], v[204:207], v[90:93]
	v_mfma_f32_16x16x32_bf16 v[82:85], v[146:149], v[212:215], v[82:85]
	v_mfma_f32_16x16x32_bf16 v[74:77], v[162:165], v[212:215], v[74:77]
	s_setprio 0
	s_setprio 1
	v_mfma_f32_16x16x32_bf16 v[118:121], v[166:169], v[184:187], v[118:121]
	v_mfma_f32_16x16x32_bf16 v[110:113], v[174:177], v[184:187], v[110:113]
	v_mfma_f32_16x16x32_bf16 v[102:105], v[166:169], v[192:195], v[102:105]
	v_mfma_f32_16x16x32_bf16 v[94:97], v[174:177], v[192:195], v[94:97]
	v_mfma_f32_16x16x32_bf16 v[86:89], v[166:169], v[200:203], v[86:89]
	v_mfma_f32_16x16x32_bf16 v[78:81], v[174:177], v[200:203], v[78:81]
	v_mfma_f32_16x16x32_bf16 v[70:73], v[166:169], v[208:211], v[70:73]
	v_mfma_f32_16x16x32_bf16 v[66:69], v[174:177], v[208:211], v[66:69]
	v_mfma_f32_16x16x32_bf16 v[118:121], v[170:173], v[188:191], v[118:121]
	v_mfma_f32_16x16x32_bf16 v[110:113], v[180:183], v[188:191], v[110:113]
	v_mfma_f32_16x16x32_bf16 v[102:105], v[170:173], v[196:199], v[102:105]
	v_mfma_f32_16x16x32_bf16 v[94:97], v[180:183], v[196:199], v[94:97]
	v_mfma_f32_16x16x32_bf16 v[86:89], v[170:173], v[204:207], v[86:89]
	v_mfma_f32_16x16x32_bf16 v[78:81], v[180:183], v[204:207], v[78:81]
	v_mfma_f32_16x16x32_bf16 v[70:73], v[170:173], v[212:215], v[70:73]
	v_mfma_f32_16x16x32_bf16 v[66:69], v[180:183], v[212:215], v[66:69]
	s_barrier
	s_setprio 0
	s_add_i32 s81, s69, s61
	s_add_u32 s98, s56, 0x80
	s_addc_u32 s99, s57, 0
	s_mov_b32 m0, s81
	ds_read_b128 v[184:187], v141 offset:16384
	ds_read_b128 v[188:191], v141 offset:17408
	ds_read_b128 v[192:195], v141 offset:18432
	ds_read_b128 v[196:199], v141 offset:19456
	ds_read_b128 v[200:203], v141 offset:20480
	ds_read_b128 v[204:207], v141 offset:21504
	ds_read_b128 v[208:211], v141 offset:22528
	ds_read_b128 v[212:215], v141 offset:23552
	global_load_lds_dwordx4 v152, s[56:57]
	s_add_i32 m0, s81, 0x2000
	s_add_u32 s82, s56, 0x80000
	s_addc_u32 s83, s57, 0
	s_add_i32 s81, s70, s61
	global_load_lds_dwordx4 v156, s[56:57]
	s_mov_b32 m0, s81
	s_nop 0
	global_load_lds_dwordx4 v152, s[82:83]
	s_add_i32 m0, s81, 0x2000
	s_nop 0
	global_load_lds_dwordx4 v156, s[82:83]
	s_add_u32 s100, s58, 0x80
	s_addc_u32 s101, s59, 0
	s_mov_b32 m0, s53
	s_nop 0
	global_load_lds_dwordx4 v150, s[58:59]
	s_mov_b32 m0, s62
	s_nop 0
	global_load_lds_dwordx4 v154, s[58:59]
	s_waitcnt vmcnt(8)
	s_waitcnt lgkmcnt(0)
	s_setprio 1
	s_barrier
	v_mfma_f32_16x16x32_bf16 v[62:65], v[142:145], v[184:187], v[62:65]
	v_mfma_f32_16x16x32_bf16 v[58:61], v[158:161], v[184:187], v[58:61]
	v_mfma_f32_16x16x32_bf16 v[50:53], v[142:145], v[192:195], v[50:53]
	v_mfma_f32_16x16x32_bf16 v[42:45], v[158:161], v[192:195], v[42:45]
	v_mfma_f32_16x16x32_bf16 v[34:37], v[142:145], v[200:203], v[34:37]
	v_mfma_f32_16x16x32_bf16 v[26:29], v[158:161], v[200:203], v[26:29]
	v_mfma_f32_16x16x32_bf16 v[18:21], v[142:145], v[208:211], v[18:21]
	v_mfma_f32_16x16x32_bf16 v[10:13], v[158:161], v[208:211], v[10:13]
	v_mfma_f32_16x16x32_bf16 v[62:65], v[146:149], v[188:191], v[62:65]
	v_mfma_f32_16x16x32_bf16 v[58:61], v[162:165], v[188:191], v[58:61]
	v_mfma_f32_16x16x32_bf16 v[50:53], v[146:149], v[196:199], v[50:53]
	v_mfma_f32_16x16x32_bf16 v[42:45], v[162:165], v[196:199], v[42:45]
	v_mfma_f32_16x16x32_bf16 v[34:37], v[146:149], v[204:207], v[34:37]
	v_mfma_f32_16x16x32_bf16 v[26:29], v[162:165], v[204:207], v[26:29]
	v_mfma_f32_16x16x32_bf16 v[18:21], v[146:149], v[212:215], v[18:21]
	v_mfma_f32_16x16x32_bf16 v[10:13], v[162:165], v[212:215], v[10:13]
	s_setprio 0
	s_setprio 1
	v_mfma_f32_16x16x32_bf16 v[54:57], v[166:169], v[184:187], v[54:57]
	v_mfma_f32_16x16x32_bf16 v[46:49], v[174:177], v[184:187], v[46:49]
	v_mfma_f32_16x16x32_bf16 v[38:41], v[166:169], v[192:195], v[38:41]
	v_mfma_f32_16x16x32_bf16 v[30:33], v[174:177], v[192:195], v[30:33]
	v_mfma_f32_16x16x32_bf16 v[22:25], v[166:169], v[200:203], v[22:25]
	v_mfma_f32_16x16x32_bf16 v[14:17], v[174:177], v[200:203], v[14:17]
	v_mfma_f32_16x16x32_bf16 v[6:9], v[166:169], v[208:211], v[6:9]
	v_mfma_f32_16x16x32_bf16 v[2:5], v[174:177], v[208:211], v[2:5]
	v_mfma_f32_16x16x32_bf16 v[54:57], v[170:173], v[188:191], v[54:57]
	v_mfma_f32_16x16x32_bf16 v[46:49], v[180:183], v[188:191], v[46:49]
	v_mfma_f32_16x16x32_bf16 v[38:41], v[170:173], v[196:199], v[38:41]
	v_mfma_f32_16x16x32_bf16 v[30:33], v[180:183], v[196:199], v[30:33]
	v_mfma_f32_16x16x32_bf16 v[22:25], v[170:173], v[204:207], v[22:25]
	v_mfma_f32_16x16x32_bf16 v[14:17], v[180:183], v[204:207], v[14:17]
	v_mfma_f32_16x16x32_bf16 v[6:9], v[170:173], v[212:215], v[6:9]
	v_mfma_f32_16x16x32_bf16 v[2:5], v[180:183], v[212:215], v[2:5]
	s_barrier
	s_setprio 0
	s_add_i32 s81, 0, 0x18000
	s_add_i32 s82, 0, 0x1c000
	ds_read_b128 v[142:145], v139 offset:32768
	ds_read_b128 v[146:149], v139 offset:33792
	ds_read_b128 v[158:161], v139 offset:34816
	ds_read_b128 v[162:165], v139 offset:35840
	ds_read_b128 v[166:169], v140 offset:32768
	ds_read_b128 v[170:173], v140 offset:33792
	ds_read_b128 v[174:177], v140 offset:34816
	ds_read_b128 v[180:183], v140 offset:35840
	s_add_u32 s58, s58, 0x80000
	s_addc_u32 s59, s59, 0
	s_mov_b32 m0, s63
	ds_read_b128 v[184:187], v141 offset:32768
	ds_read_b128 v[188:191], v141 offset:33792
	ds_read_b128 v[192:195], v141 offset:34816
	ds_read_b128 v[196:199], v141 offset:35840
	ds_read_b128 v[200:203], v141 offset:36864
	ds_read_b128 v[204:207], v141 offset:37888
	ds_read_b128 v[208:211], v141 offset:38912
	ds_read_b128 v[212:215], v141 offset:39936
	global_load_lds_dwordx4 v150, s[58:59]
	s_mov_b32 m0, s64
	s_nop 0
	global_load_lds_dwordx4 v154, s[58:59]
	s_waitcnt vmcnt(8)
	s_waitcnt lgkmcnt(0)
	s_setprio 1
	s_barrier
	v_mfma_f32_16x16x32_bf16 v[126:129], v[142:145], v[184:187], v[126:129]
	v_mfma_f32_16x16x32_bf16 v[122:125], v[158:161], v[184:187], v[122:125]
	v_mfma_f32_16x16x32_bf16 v[114:117], v[142:145], v[192:195], v[114:117]
	v_mfma_f32_16x16x32_bf16 v[106:109], v[158:161], v[192:195], v[106:109]
	v_mfma_f32_16x16x32_bf16 v[98:101], v[142:145], v[200:203], v[98:101]
	v_mfma_f32_16x16x32_bf16 v[90:93], v[158:161], v[200:203], v[90:93]
	v_mfma_f32_16x16x32_bf16 v[82:85], v[142:145], v[208:211], v[82:85]
	v_mfma_f32_16x16x32_bf16 v[74:77], v[158:161], v[208:211], v[74:77]
	v_mfma_f32_16x16x32_bf16 v[126:129], v[146:149], v[188:191], v[126:129]
	v_mfma_f32_16x16x32_bf16 v[122:125], v[162:165], v[188:191], v[122:125]
	v_mfma_f32_16x16x32_bf16 v[114:117], v[146:149], v[196:199], v[114:117]
	v_mfma_f32_16x16x32_bf16 v[106:109], v[162:165], v[196:199], v[106:109]
	v_mfma_f32_16x16x32_bf16 v[98:101], v[146:149], v[204:207], v[98:101]
	v_mfma_f32_16x16x32_bf16 v[90:93], v[162:165], v[204:207], v[90:93]
	v_mfma_f32_16x16x32_bf16 v[82:85], v[146:149], v[212:215], v[82:85]
	v_mfma_f32_16x16x32_bf16 v[74:77], v[162:165], v[212:215], v[74:77]
	s_setprio 0
	s_setprio 1
	v_mfma_f32_16x16x32_bf16 v[118:121], v[166:169], v[184:187], v[118:121]
	v_mfma_f32_16x16x32_bf16 v[110:113], v[174:177], v[184:187], v[110:113]
	v_mfma_f32_16x16x32_bf16 v[102:105], v[166:169], v[192:195], v[102:105]
	v_mfma_f32_16x16x32_bf16 v[94:97], v[174:177], v[192:195], v[94:97]
	v_mfma_f32_16x16x32_bf16 v[86:89], v[166:169], v[200:203], v[86:89]
	v_mfma_f32_16x16x32_bf16 v[78:81], v[174:177], v[200:203], v[78:81]
	v_mfma_f32_16x16x32_bf16 v[70:73], v[166:169], v[208:211], v[70:73]
	v_mfma_f32_16x16x32_bf16 v[66:69], v[174:177], v[208:211], v[66:69]
	v_mfma_f32_16x16x32_bf16 v[118:121], v[170:173], v[188:191], v[118:121]
	v_mfma_f32_16x16x32_bf16 v[110:113], v[180:183], v[188:191], v[110:113]
	v_mfma_f32_16x16x32_bf16 v[102:105], v[170:173], v[196:199], v[102:105]
	v_mfma_f32_16x16x32_bf16 v[94:97], v[180:183], v[196:199], v[94:97]
	v_mfma_f32_16x16x32_bf16 v[86:89], v[170:173], v[204:207], v[86:89]
	v_mfma_f32_16x16x32_bf16 v[78:81], v[180:183], v[204:207], v[78:81]
	v_mfma_f32_16x16x32_bf16 v[70:73], v[170:173], v[212:215], v[70:73]
	v_mfma_f32_16x16x32_bf16 v[66:69], v[180:183], v[212:215], v[66:69]
	s_barrier
	s_setprio 0
	s_add_i32 s58, s81, s61
	s_mov_b32 m0, s58
	ds_read_b128 v[184:187], v141 offset:49152
	ds_read_b128 v[188:191], v141 offset:50176
	ds_read_b128 v[192:195], v141 offset:51200
	ds_read_b128 v[196:199], v141 offset:52224
	ds_read_b128 v[200:203], v141 offset:53248
	ds_read_b128 v[204:207], v141 offset:54272
	ds_read_b128 v[208:211], v141 offset:55296
	ds_read_b128 v[212:215], v141 offset:56320
	global_load_lds_dwordx4 v152, s[98:99]
	s_add_i32 m0, s58, 0x2000
	s_add_u32 s56, s56, 0x80080
	s_addc_u32 s57, s57, 0
	s_add_i32 s58, s82, s61
	global_load_lds_dwordx4 v156, s[98:99]
	s_mov_b32 m0, s58
	s_nop 0
	global_load_lds_dwordx4 v152, s[56:57]
	s_add_i32 m0, s58, 0x2000
	s_nop 0
	global_load_lds_dwordx4 v156, s[56:57]
	s_mov_b32 m0, s66
	s_nop 0
	global_load_lds_dwordx4 v150, s[100:101]
	s_mov_b32 m0, s67
	s_nop 0
	global_load_lds_dwordx4 v154, s[100:101]
	s_add_i32 s80, s80, 2
	s_add_u32 s54, s54, 0x100
	s_addc_u32 s55, s55, 0
	s_add_u32 s78, s78, 0x100
	s_addc_u32 s79, s79, 0
	s_cmp_gt_u32 s80, 29
	s_waitcnt vmcnt(8)
	s_waitcnt lgkmcnt(0)
	s_setprio 1
	s_barrier
	v_mfma_f32_16x16x32_bf16 v[62:65], v[142:145], v[184:187], v[62:65]
	v_mfma_f32_16x16x32_bf16 v[58:61], v[158:161], v[184:187], v[58:61]
	v_mfma_f32_16x16x32_bf16 v[50:53], v[142:145], v[192:195], v[50:53]
	v_mfma_f32_16x16x32_bf16 v[42:45], v[158:161], v[192:195], v[42:45]
	v_mfma_f32_16x16x32_bf16 v[34:37], v[142:145], v[200:203], v[34:37]
	v_mfma_f32_16x16x32_bf16 v[26:29], v[158:161], v[200:203], v[26:29]
	v_mfma_f32_16x16x32_bf16 v[18:21], v[142:145], v[208:211], v[18:21]
	v_mfma_f32_16x16x32_bf16 v[10:13], v[158:161], v[208:211], v[10:13]
	v_mfma_f32_16x16x32_bf16 v[62:65], v[146:149], v[188:191], v[62:65]
	v_mfma_f32_16x16x32_bf16 v[58:61], v[162:165], v[188:191], v[58:61]
	v_mfma_f32_16x16x32_bf16 v[50:53], v[146:149], v[196:199], v[50:53]
	v_mfma_f32_16x16x32_bf16 v[42:45], v[162:165], v[196:199], v[42:45]
	v_mfma_f32_16x16x32_bf16 v[34:37], v[146:149], v[204:207], v[34:37]
	v_mfma_f32_16x16x32_bf16 v[26:29], v[162:165], v[204:207], v[26:29]
	v_mfma_f32_16x16x32_bf16 v[18:21], v[146:149], v[212:215], v[18:21]
	v_mfma_f32_16x16x32_bf16 v[10:13], v[162:165], v[212:215], v[10:13]
	s_setprio 0
	s_setprio 1
	v_mfma_f32_16x16x32_bf16 v[54:57], v[166:169], v[184:187], v[54:57]
	v_mfma_f32_16x16x32_bf16 v[46:49], v[174:177], v[184:187], v[46:49]
	v_mfma_f32_16x16x32_bf16 v[38:41], v[166:169], v[192:195], v[38:41]
	v_mfma_f32_16x16x32_bf16 v[30:33], v[174:177], v[192:195], v[30:33]
	v_mfma_f32_16x16x32_bf16 v[22:25], v[166:169], v[200:203], v[22:25]
	v_mfma_f32_16x16x32_bf16 v[14:17], v[174:177], v[200:203], v[14:17]
	v_mfma_f32_16x16x32_bf16 v[6:9], v[166:169], v[208:211], v[6:9]
	v_mfma_f32_16x16x32_bf16 v[2:5], v[174:177], v[208:211], v[2:5]
	v_mfma_f32_16x16x32_bf16 v[54:57], v[170:173], v[188:191], v[54:57]
	v_mfma_f32_16x16x32_bf16 v[46:49], v[180:183], v[188:191], v[46:49]
	v_mfma_f32_16x16x32_bf16 v[38:41], v[170:173], v[196:199], v[38:41]
	v_mfma_f32_16x16x32_bf16 v[30:33], v[180:183], v[196:199], v[30:33]
	v_mfma_f32_16x16x32_bf16 v[22:25], v[170:173], v[204:207], v[22:25]
	v_mfma_f32_16x16x32_bf16 v[14:17], v[180:183], v[204:207], v[14:17]
	v_mfma_f32_16x16x32_bf16 v[6:9], v[170:173], v[212:215], v[6:9]
	v_mfma_f32_16x16x32_bf16 v[2:5], v[180:183], v[212:215], v[2:5]
	s_barrier
	s_setprio 0
	s_cbranch_scc0 .LBB0_725
	s_and_b64 vcc, exec, s[6:7]
	s_cbranch_vccz .LBB0_728
	s_barrier

.LBB0_1315:
	s_add_u32 s4, s26, 0x15c00000
	s_addc_u32 s5, s27, 0
	s_add_u32 s6, s26, 0x23c00000
	s_addc_u32 s7, s27, 0
	s_lshl_b32 s49, s8, 6
	s_lshl_b32 s12, s8, 13
	s_lshl_b32 s8, s9, 5
	s_and_b32 s52, s8, 0x60
	s_mov_b64 s[8:9], 0x80
	s_add_i32 m0, s29, 0x18000
	v_lshl_add_u64 v[10:11], v[10:11], 0, s[8:9]
	s_lshl_b32 s13, s52, 7
	s_waitcnt vmcnt(2)
	s_barrier
	global_load_lds_dwordx4 v[10:11], off
	v_lshl_add_u64 v[8:9], v[8:9], 0, s[8:9]
	s_add_i32 m0, s29, 0x1a000
	s_add_i32 s53, s29, 0x8000
	s_add_i32 s54, s29, 0xa000
	global_load_lds_dwordx4 v[8:9], off
	v_lshl_add_u64 v[4:5], v[4:5], 0, s[8:9]
	s_mov_b32 m0, s53
	s_add_u32 s10, s40, 0x80080
	global_load_lds_dwordx4 v[4:5], off
	v_lshl_add_u64 v[4:5], v[6:7], 0, s[8:9]
	s_mov_b32 m0, s54
	s_addc_u32 s11, s41, 0
	global_load_lds_dwordx4 v[4:5], off
	s_add_i32 m0, s29, 0x1c000
	s_nop 0
	global_load_lds_dwordx4 v176, s[10:11]
	v_lshl_add_u64 v[4:5], s[10:11], 0, v[180:181]
	s_add_i32 m0, s29, 0x1e000
	v_bfe_u32 v195, v0, 4, 2
	global_load_lds_dwordx4 v[4:5], off
	v_and_b32_e32 v194, 15, v0
	v_lshlrev_b32_e32 v1, 4, v195
	v_lshlrev_b32_e32 v5, 2, v0
	v_lshl_or_b32 v4, v194, 6, v1
	v_and_b32_e32 v5, 32, v5
	s_sext_i32_i8 s39, s2
	v_bitop3_b32 v6, v4, s12, v5 bitop3:0xde
	v_lshlrev_b32_e32 v4, 6, v0
	s_movk_i32 s2, 0x3c0
	v_and_or_b32 v1, v4, s2, v1
	v_bitop3_b32 v197, s13, v1, v5 bitop3:0xf6
	v_add_u32_e32 v236, 0x10000, v197
	v_lshlrev_b32_e32 v1, 9, v0
	v_and_b32_e32 v1, 0x30000, v1
	v_lshlrev_b32_e32 v7, 12, v13
	v_or3_b32 v1, v3, v1, v7
	v_add_u32_e32 v4, v1, v12
	v_lshlrev_b32_e32 v1, 5, v14
	v_and_b32_e32 v1, 0x70000, v1
	s_mov_b64 s[12:13], 0x80080
	s_waitcnt vmcnt(6)
	v_mov_b32_e32 v5, v2
	v_or3_b32 v1, v3, v1, v7
	s_cmpk_lt_u32 s3, 0x100
	v_lshl_add_u64 v[182:183], v[4:5], 0, s[12:13]
	v_add_u32_e32 v4, v1, v12
	v_or_b32_e32 v196, s49, v194
	s_cselect_b64 s[10:11], -1, 0
	v_lshl_or_b32 v198, v195, 3, s52
	s_ashr_i32 s55, s33, 31
	v_lshl_add_u64 v[184:185], v[4:5], 0, s[12:13]
	v_mov_b64_e32 v[186:187], 0x400
	v_mov_b64_e32 v[188:189], 0x3ff
	s_movk_i32 s56, 0x1000
	s_movk_i32 s57, 0x3000
	s_add_i32 s58, 0, 0x10000
	s_add_i32 s59, 0, 0x14000
	v_add_u32_e32 v199, 0, v6
	s_mov_b64 s[12:13], 0x2000
	s_barrier
	s_branch .LBB0_1318

.LBB0_1328:
	s_add_u32 s40, s36, s38
	ds_read_b128 v[134:137], v236
	ds_read_b128 v[138:141], v236 offset:1024
	ds_read_b128 v[142:145], v236 offset:2048
	ds_read_b128 v[146:149], v236 offset:3072
	s_addc_u32 s41, s37, s39
	ds_read_b128 v[150:153], v236 offset:16384
	ds_read_b128 v[154:157], v236 offset:17408
	ds_read_b128 v[158:161], v236 offset:18432
	ds_read_b128 v[162:165], v236 offset:19456
	s_add_u32 s40, s40, 0x100
	s_addc_u32 s41, s41, 0
	s_add_u32 s69, s66, s38
	s_addc_u32 s70, s67, s39
	s_cmpk_eq_i32 s38, 0xf00
	s_cselect_b32 s42, s60, s40
	s_cselect_b32 s40, s63, s69
	s_cselect_b32 s43, s17, s41
	s_cselect_b32 s41, s62, s70
	v_lshl_add_u64 v[4:5], v[190:191], 0, s[38:39]
	s_add_i32 m0, s29, 0xc000
	ds_read_b128 v[166:169], v199
	ds_read_b128 v[170:173], v199 offset:1024
	ds_read_b128 v[200:203], v199 offset:2048
	ds_read_b128 v[204:207], v199 offset:3072
	ds_read_b128 v[208:211], v199 offset:4096
	ds_read_b128 v[212:215], v199 offset:5120
	ds_read_b128 v[216:219], v199 offset:6144
	ds_read_b128 v[220:223], v199 offset:7168
	global_load_lds_dwordx4 v[4:5], off
	v_lshl_add_u64 v[4:5], v[192:193], 0, s[38:39]
	s_add_i32 m0, s29, 0xe000
	s_nop 0
	global_load_lds_dwordx4 v[4:5], off
	s_waitcnt vmcnt(8)
	s_waitcnt lgkmcnt(0)
	s_setprio 1
	s_barrier
	v_mfma_f32_16x16x32_bf16 v[130:133], v[134:137], v[166:169], v[130:133]
	v_mfma_f32_16x16x32_bf16 v[126:129], v[142:145], v[166:169], v[126:129]
	v_mfma_f32_16x16x32_bf16 v[114:117], v[134:137], v[200:203], v[114:117]
	v_mfma_f32_16x16x32_bf16 v[110:113], v[142:145], v[200:203], v[110:113]
	v_mfma_f32_16x16x32_bf16 v[98:101], v[134:137], v[208:211], v[98:101]
	v_mfma_f32_16x16x32_bf16 v[94:97], v[142:145], v[208:211], v[94:97]
	v_mfma_f32_16x16x32_bf16 v[82:85], v[134:137], v[216:219], v[82:85]
	v_mfma_f32_16x16x32_bf16 v[78:81], v[142:145], v[216:219], v[78:81]
	v_mfma_f32_16x16x32_bf16 v[130:133], v[138:141], v[170:173], v[130:133]
	v_mfma_f32_16x16x32_bf16 v[126:129], v[146:149], v[170:173], v[126:129]
	v_mfma_f32_16x16x32_bf16 v[114:117], v[138:141], v[204:207], v[114:117]
	v_mfma_f32_16x16x32_bf16 v[110:113], v[146:149], v[204:207], v[110:113]
	v_mfma_f32_16x16x32_bf16 v[98:101], v[138:141], v[212:215], v[98:101]
	v_mfma_f32_16x16x32_bf16 v[94:97], v[146:149], v[212:215], v[94:97]
	v_mfma_f32_16x16x32_bf16 v[82:85], v[138:141], v[220:223], v[82:85]
	v_mfma_f32_16x16x32_bf16 v[78:81], v[146:149], v[220:223], v[78:81]
	s_setprio 0
	s_setprio 1
	v_mfma_f32_16x16x32_bf16 v[122:125], v[150:153], v[166:169], v[122:125]
	v_mfma_f32_16x16x32_bf16 v[118:121], v[158:161], v[166:169], v[118:121]
	v_mfma_f32_16x16x32_bf16 v[106:109], v[150:153], v[200:203], v[106:109]
	v_mfma_f32_16x16x32_bf16 v[102:105], v[158:161], v[200:203], v[102:105]
	v_mfma_f32_16x16x32_bf16 v[90:93], v[150:153], v[208:211], v[90:93]
	v_mfma_f32_16x16x32_bf16 v[86:89], v[158:161], v[208:211], v[86:89]
	v_mfma_f32_16x16x32_bf16 v[74:77], v[150:153], v[216:219], v[74:77]
	v_mfma_f32_16x16x32_bf16 v[70:73], v[158:161], v[216:219], v[70:73]
	v_mfma_f32_16x16x32_bf16 v[122:125], v[154:157], v[170:173], v[122:125]
	v_mfma_f32_16x16x32_bf16 v[118:121], v[162:165], v[170:173], v[118:121]
	v_mfma_f32_16x16x32_bf16 v[106:109], v[154:157], v[204:207], v[106:109]
	v_mfma_f32_16x16x32_bf16 v[102:105], v[162:165], v[204:207], v[102:105]
	v_mfma_f32_16x16x32_bf16 v[90:93], v[154:157], v[212:215], v[90:93]
	v_mfma_f32_16x16x32_bf16 v[86:89], v[162:165], v[212:215], v[86:89]
	v_mfma_f32_16x16x32_bf16 v[74:77], v[154:157], v[220:223], v[74:77]
	v_mfma_f32_16x16x32_bf16 v[70:73], v[162:165], v[220:223], v[70:73]
	s_barrier
	s_setprio 0
	s_add_i32 s69, s58, s28
	s_add_u32 s98, s40, 0x80
	s_addc_u32 s99, s41, 0
	s_mov_b32 m0, s69
	ds_read_b128 v[166:169], v199 offset:16384
	ds_read_b128 v[170:173], v199 offset:17408
	ds_read_b128 v[200:203], v199 offset:18432
	ds_read_b128 v[204:207], v199 offset:19456
	ds_read_b128 v[208:211], v199 offset:20480
	ds_read_b128 v[212:215], v199 offset:21504
	ds_read_b128 v[216:219], v199 offset:22528
	ds_read_b128 v[220:223], v199 offset:23552
	global_load_lds_dwordx4 v176, s[40:41]
	s_add_i32 m0, s69, 0x2000
	s_add_u32 s70, s40, 0x80000
	s_addc_u32 s71, s41, 0
	s_add_i32 s69, s59, s28
	global_load_lds_dwordx4 v180, s[40:41]
	s_mov_b32 m0, s69
	s_add_u32 s100, s42, 0x80
	s_addc_u32 s101, s43, 0
	global_load_lds_dwordx4 v176, s[70:71]
	v_lshl_add_u64 v[4:5], s[70:71], 0, v[180:181]
	s_add_i32 m0, s69, 0x2000
	s_nop 0
	global_load_lds_dwordx4 v[4:5], off
	s_mov_b32 m0, s29
	s_nop 0
	global_load_lds_dwordx4 v174, s[42:43]
	s_mov_b32 m0, s44
	s_nop 0
	global_load_lds_dwordx4 v178, s[42:43]
	s_waitcnt vmcnt(8)
	s_waitcnt lgkmcnt(0)
	s_setprio 1
	s_barrier
	v_mfma_f32_16x16x32_bf16 v[66:69], v[134:137], v[166:169], v[66:69]
	v_mfma_f32_16x16x32_bf16 v[62:65], v[142:145], v[166:169], v[62:65]
	v_mfma_f32_16x16x32_bf16 v[50:53], v[134:137], v[200:203], v[50:53]
	v_mfma_f32_16x16x32_bf16 v[46:49], v[142:145], v[200:203], v[46:49]
	v_mfma_f32_16x16x32_bf16 v[34:37], v[134:137], v[208:211], v[34:37]
	v_mfma_f32_16x16x32_bf16 v[30:33], v[142:145], v[208:211], v[30:33]
	v_mfma_f32_16x16x32_bf16 v[18:21], v[134:137], v[216:219], v[18:21]
	v_mfma_f32_16x16x32_bf16 v[14:17], v[142:145], v[216:219], v[14:17]
	v_mfma_f32_16x16x32_bf16 v[66:69], v[138:141], v[170:173], v[66:69]
	v_mfma_f32_16x16x32_bf16 v[62:65], v[146:149], v[170:173], v[62:65]
	v_mfma_f32_16x16x32_bf16 v[50:53], v[138:141], v[204:207], v[50:53]
	v_mfma_f32_16x16x32_bf16 v[46:49], v[146:149], v[204:207], v[46:49]
	v_mfma_f32_16x16x32_bf16 v[34:37], v[138:141], v[212:215], v[34:37]
	v_mfma_f32_16x16x32_bf16 v[30:33], v[146:149], v[212:215], v[30:33]
	v_mfma_f32_16x16x32_bf16 v[18:21], v[138:141], v[220:223], v[18:21]
	v_mfma_f32_16x16x32_bf16 v[14:17], v[146:149], v[220:223], v[14:17]
	s_setprio 0
	s_setprio 1
	v_mfma_f32_16x16x32_bf16 v[58:61], v[150:153], v[166:169], v[58:61]
	v_mfma_f32_16x16x32_bf16 v[54:57], v[158:161], v[166:169], v[54:57]
	v_mfma_f32_16x16x32_bf16 v[42:45], v[150:153], v[200:203], v[42:45]
	v_mfma_f32_16x16x32_bf16 v[38:41], v[158:161], v[200:203], v[38:41]
	v_mfma_f32_16x16x32_bf16 v[26:29], v[150:153], v[208:211], v[26:29]
	v_mfma_f32_16x16x32_bf16 v[22:25], v[158:161], v[208:211], v[22:25]
	v_mfma_f32_16x16x32_bf16 v[10:13], v[150:153], v[216:219], v[10:13]
	v_mfma_f32_16x16x32_bf16 v[4:7], v[158:161], v[216:219], v[6:9]
	v_mfma_f32_16x16x32_bf16 v[58:61], v[154:157], v[170:173], v[58:61]
	v_mfma_f32_16x16x32_bf16 v[54:57], v[162:165], v[170:173], v[54:57]
	v_mfma_f32_16x16x32_bf16 v[42:45], v[154:157], v[204:207], v[42:45]
	v_mfma_f32_16x16x32_bf16 v[38:41], v[162:165], v[204:207], v[38:41]
	v_mfma_f32_16x16x32_bf16 v[26:29], v[154:157], v[212:215], v[26:29]
	v_mfma_f32_16x16x32_bf16 v[22:25], v[162:165], v[212:215], v[22:25]
	v_mfma_f32_16x16x32_bf16 v[10:13], v[154:157], v[220:223], v[10:13]
	v_mfma_f32_16x16x32_bf16 v[4:7], v[162:165], v[220:223], v[4:7]
	s_barrier
	s_setprio 0
	s_add_i32 s69, 0, 0x18000
	s_add_i32 s70, 0, 0x1c000
	ds_read_b128 v[134:137], v236 offset:32768
	ds_read_b128 v[138:141], v236 offset:33792
	ds_read_b128 v[142:145], v236 offset:34816
	ds_read_b128 v[146:149], v236 offset:35840
	ds_read_b128 v[150:153], v236 offset:49152
	ds_read_b128 v[154:157], v236 offset:50176
	ds_read_b128 v[158:161], v236 offset:51200
	ds_read_b128 v[162:165], v236 offset:52224
	s_add_u32 s42, s42, 0x80000
	s_addc_u32 s43, s43, 0
	s_mov_b32 m0, s45
	ds_read_b128 v[166:169], v199 offset:32768
	ds_read_b128 v[170:173], v199 offset:33792
	ds_read_b128 v[200:203], v199 offset:34816
	ds_read_b128 v[204:207], v199 offset:35840
	ds_read_b128 v[208:211], v199 offset:36864
	ds_read_b128 v[212:215], v199 offset:37888
	ds_read_b128 v[216:219], v199 offset:38912
	ds_read_b128 v[220:223], v199 offset:39936
	global_load_lds_dwordx4 v174, s[42:43]
	s_mov_b32 m0, s46
	s_nop 0
	global_load_lds_dwordx4 v178, s[42:43]
	s_waitcnt vmcnt(8)
	s_waitcnt lgkmcnt(0)
	s_setprio 1
	s_barrier
	v_mfma_f32_16x16x32_bf16 v[130:133], v[134:137], v[166:169], v[130:133]
	v_mfma_f32_16x16x32_bf16 v[126:129], v[142:145], v[166:169], v[126:129]
	v_mfma_f32_16x16x32_bf16 v[114:117], v[134:137], v[200:203], v[114:117]
	v_mfma_f32_16x16x32_bf16 v[110:113], v[142:145], v[200:203], v[110:113]
	v_mfma_f32_16x16x32_bf16 v[98:101], v[134:137], v[208:211], v[98:101]
	v_mfma_f32_16x16x32_bf16 v[94:97], v[142:145], v[208:211], v[94:97]
	v_mfma_f32_16x16x32_bf16 v[82:85], v[134:137], v[216:219], v[82:85]
	v_mfma_f32_16x16x32_bf16 v[78:81], v[142:145], v[216:219], v[78:81]
	v_mfma_f32_16x16x32_bf16 v[130:133], v[138:141], v[170:173], v[130:133]
	v_mfma_f32_16x16x32_bf16 v[126:129], v[146:149], v[170:173], v[126:129]
	v_mfma_f32_16x16x32_bf16 v[114:117], v[138:141], v[204:207], v[114:117]
	v_mfma_f32_16x16x32_bf16 v[110:113], v[146:149], v[204:207], v[110:113]
	v_mfma_f32_16x16x32_bf16 v[98:101], v[138:141], v[212:215], v[98:101]
	v_mfma_f32_16x16x32_bf16 v[94:97], v[146:149], v[212:215], v[94:97]
	v_mfma_f32_16x16x32_bf16 v[82:85], v[138:141], v[220:223], v[82:85]
	v_mfma_f32_16x16x32_bf16 v[78:81], v[146:149], v[220:223], v[78:81]
	s_setprio 0
	s_setprio 1
	v_mfma_f32_16x16x32_bf16 v[122:125], v[150:153], v[166:169], v[122:125]
	v_mfma_f32_16x16x32_bf16 v[118:121], v[158:161], v[166:169], v[118:121]
	v_mfma_f32_16x16x32_bf16 v[106:109], v[150:153], v[200:203], v[106:109]
	v_mfma_f32_16x16x32_bf16 v[102:105], v[158:161], v[200:203], v[102:105]
	v_mfma_f32_16x16x32_bf16 v[90:93], v[150:153], v[208:211], v[90:93]
	v_mfma_f32_16x16x32_bf16 v[86:89], v[158:161], v[208:211], v[86:89]
	v_mfma_f32_16x16x32_bf16 v[74:77], v[150:153], v[216:219], v[74:77]
	v_mfma_f32_16x16x32_bf16 v[70:73], v[158:161], v[216:219], v[70:73]
	v_mfma_f32_16x16x32_bf16 v[122:125], v[154:157], v[170:173], v[122:125]
	v_mfma_f32_16x16x32_bf16 v[118:121], v[162:165], v[170:173], v[118:121]
	v_mfma_f32_16x16x32_bf16 v[106:109], v[154:157], v[204:207], v[106:109]
	v_mfma_f32_16x16x32_bf16 v[102:105], v[162:165], v[204:207], v[102:105]
	v_mfma_f32_16x16x32_bf16 v[90:93], v[154:157], v[212:215], v[90:93]
	v_mfma_f32_16x16x32_bf16 v[86:89], v[162:165], v[212:215], v[86:89]
	v_mfma_f32_16x16x32_bf16 v[74:77], v[154:157], v[220:223], v[74:77]
	v_mfma_f32_16x16x32_bf16 v[70:73], v[162:165], v[220:223], v[70:73]
	s_barrier
	s_setprio 0
	s_add_i32 s42, s69, s28
	s_mov_b32 m0, s42
	ds_read_b128 v[166:169], v199 offset:49152
	ds_read_b128 v[170:173], v199 offset:50176
	ds_read_b128 v[200:203], v199 offset:51200
	ds_read_b128 v[204:207], v199 offset:52224
	ds_read_b128 v[208:211], v199 offset:53248
	ds_read_b128 v[212:215], v199 offset:54272
	ds_read_b128 v[216:219], v199 offset:55296
	ds_read_b128 v[220:223], v199 offset:56320
	global_load_lds_dwordx4 v176, s[98:99]
	s_add_i32 m0, s42, 0x2000
	s_add_u32 s40, s40, 0x80080
	s_addc_u32 s41, s41, 0
	s_add_i32 s42, s70, s28
	global_load_lds_dwordx4 v180, s[98:99]
	s_mov_b32 m0, s42
	s_nop 0
	global_load_lds_dwordx4 v176, s[40:41]
	s_add_i32 m0, s42, 0x2000
	s_nop 0
	global_load_lds_dwordx4 v180, s[40:41]
	s_mov_b32 m0, s53
	s_nop 0
	global_load_lds_dwordx4 v174, s[100:101]
	s_mov_b32 m0, s54
	s_nop 0
	global_load_lds_dwordx4 v178, s[100:101]
	s_waitcnt vmcnt(8)
	s_waitcnt lgkmcnt(0)
	s_setprio 1
	s_barrier
	v_mfma_f32_16x16x32_bf16 v[66:69], v[134:137], v[166:169], v[66:69]
	v_mfma_f32_16x16x32_bf16 v[62:65], v[142:145], v[166:169], v[62:65]
	v_mfma_f32_16x16x32_bf16 v[50:53], v[134:137], v[200:203], v[50:53]
	v_mfma_f32_16x16x32_bf16 v[46:49], v[142:145], v[200:203], v[46:49]
	v_mfma_f32_16x16x32_bf16 v[34:37], v[134:137], v[208:211], v[34:37]
	v_mfma_f32_16x16x32_bf16 v[30:33], v[142:145], v[208:211], v[30:33]
	v_mfma_f32_16x16x32_bf16 v[18:21], v[134:137], v[216:219], v[18:21]
	v_mfma_f32_16x16x32_bf16 v[14:17], v[142:145], v[216:219], v[14:17]
	v_mfma_f32_16x16x32_bf16 v[66:69], v[138:141], v[170:173], v[66:69]
	v_mfma_f32_16x16x32_bf16 v[62:65], v[146:149], v[170:173], v[62:65]
	v_mfma_f32_16x16x32_bf16 v[50:53], v[138:141], v[204:207], v[50:53]
	v_mfma_f32_16x16x32_bf16 v[46:49], v[146:149], v[204:207], v[46:49]
	v_mfma_f32_16x16x32_bf16 v[34:37], v[138:141], v[212:215], v[34:37]
	v_mfma_f32_16x16x32_bf16 v[30:33], v[146:149], v[212:215], v[30:33]
	v_mfma_f32_16x16x32_bf16 v[18:21], v[138:141], v[220:223], v[18:21]
	v_mfma_f32_16x16x32_bf16 v[14:17], v[146:149], v[220:223], v[14:17]
	s_setprio 0
	s_setprio 1
	v_mfma_f32_16x16x32_bf16 v[58:61], v[150:153], v[166:169], v[58:61]
	v_mfma_f32_16x16x32_bf16 v[54:57], v[158:161], v[166:169], v[54:57]
	v_mfma_f32_16x16x32_bf16 v[42:45], v[150:153], v[200:203], v[42:45]
	v_mfma_f32_16x16x32_bf16 v[38:41], v[158:161], v[200:203], v[38:41]
	v_mfma_f32_16x16x32_bf16 v[26:29], v[150:153], v[208:211], v[26:29]
	v_mfma_f32_16x16x32_bf16 v[22:25], v[158:161], v[208:211], v[22:25]
	v_mfma_f32_16x16x32_bf16 v[8:11], v[150:153], v[216:219], v[10:13]
	v_mfma_f32_16x16x32_bf16 v[4:7], v[158:161], v[216:219], v[4:7]
	v_mfma_f32_16x16x32_bf16 v[58:61], v[154:157], v[170:173], v[58:61]
	v_mfma_f32_16x16x32_bf16 v[54:57], v[162:165], v[170:173], v[54:57]
	v_mfma_f32_16x16x32_bf16 v[42:45], v[154:157], v[204:207], v[42:45]
	v_mfma_f32_16x16x32_bf16 v[38:41], v[162:165], v[204:207], v[38:41]
	v_mfma_f32_16x16x32_bf16 v[26:29], v[154:157], v[212:215], v[26:29]
	v_mfma_f32_16x16x32_bf16 v[22:25], v[162:165], v[212:215], v[22:25]
	v_mfma_f32_16x16x32_bf16 v[10:13], v[154:157], v[220:223], v[8:11]
	v_mfma_f32_16x16x32_bf16 v[6:9], v[162:165], v[220:223], v[4:7]
	s_barrier
	s_setprio 0
	s_add_i32 s40, s68, 2
	s_add_u32 s38, s38, 0x100
	s_addc_u32 s39, s39, 0
	s_cmp_gt_u32 s68, 29
	s_cbranch_scc1 .LBB0_1330
	s_mov_b32 s68, s40
	s_and_b32 s40, s68, 14
	s_cmp_eq_u32 s40, 8
	s_mov_b64 s[40:41], -1
	s_cbranch_scc0 .LBB0_1325
	s_branch .LBB0_1326

.LBB0_1407:
	s_ashr_i32 s39, s38, 31
	s_lshl_b64 s[40:41], s[38:39], 20
	s_add_u32 s40, s22, s40
	s_addc_u32 s41, s23, s41
	s_and_b64 s[42:43], s[10:11], exec
	s_cselect_b32 s39, s41, s47
	s_cselect_b32 s66, s40, s46
	s_ashr_i32 s37, s36, 31
	s_lshl_b64 s[42:43], s[36:37], 20
	s_add_u32 s42, s28, s42
	s_addc_u32 s43, s29, s43
	s_and_b64 s[52:53], s[10:11], exec
	s_cselect_b32 s37, s43, s49
	s_cselect_b32 s67, s42, s48
	s_add_u32 s46, s46, 0x80080
	s_addc_u32 s47, s47, 0
	s_add_u32 s68, s48, 0x100
	s_addc_u32 s69, s49, 0
	s_mov_b32 s70, -2
	ds_read_b128 v[130:133], v183
	ds_read_b128 v[134:137], v183 offset:1024
	ds_read_b128 v[138:141], v183 offset:2048
	ds_read_b128 v[142:145], v183 offset:3072
	ds_read_b128 v[162:165], v184
	ds_read_b128 v[166:169], v184 offset:1024
	ds_read_b128 v[170:173], v184 offset:2048
	ds_read_b128 v[174:177], v184 offset:3072
	s_add_u32 s48, s46, 0xfff80080
	s_addc_u32 s49, s47, -1
	s_cmp_eq_u32 s70, 28
	s_cselect_b32 s53, s39, s49
	s_cselect_b32 s52, s66, s48
	s_cselect_b32 s49, s37, s69
	s_cselect_b32 s48, s67, s68
	s_add_i32 m0, s45, 0xc000
	ds_read_b128 v[188:191], v185
	ds_read_b128 v[192:195], v185 offset:1024
	ds_read_b128 v[196:199], v185 offset:2048
	ds_read_b128 v[200:203], v185 offset:3072
	ds_read_b128 v[204:207], v185 offset:4096
	ds_read_b128 v[208:211], v185 offset:5120
	ds_read_b128 v[212:215], v185 offset:6144
	ds_read_b128 v[216:219], v185 offset:7168
	global_load_lds_dwordx4 v154, s[46:47]
	s_add_i32 m0, s45, 0xe000
	s_nop 0
	global_load_lds_dwordx4 v156, s[46:47]
	s_waitcnt vmcnt(8)
	s_waitcnt lgkmcnt(0)
	s_setprio 1
	s_barrier
	v_mfma_f32_16x16x32_bf16 v[126:129], v[130:133], v[188:191], 0
	v_mfma_f32_16x16x32_bf16 v[122:125], v[138:141], v[188:191], 0
	v_mfma_f32_16x16x32_bf16 v[110:113], v[130:133], v[196:199], 0
	v_mfma_f32_16x16x32_bf16 v[106:109], v[138:141], v[196:199], 0
	v_mfma_f32_16x16x32_bf16 v[94:97], v[130:133], v[204:207], 0
	v_mfma_f32_16x16x32_bf16 v[90:93], v[138:141], v[204:207], 0
	v_mfma_f32_16x16x32_bf16 v[78:81], v[130:133], v[212:215], 0
	v_mfma_f32_16x16x32_bf16 v[74:77], v[138:141], v[212:215], 0
	v_mfma_f32_16x16x32_bf16 v[126:129], v[134:137], v[192:195], v[126:129]
	v_mfma_f32_16x16x32_bf16 v[122:125], v[142:145], v[192:195], v[122:125]
	v_mfma_f32_16x16x32_bf16 v[110:113], v[134:137], v[200:203], v[110:113]
	v_mfma_f32_16x16x32_bf16 v[106:109], v[142:145], v[200:203], v[106:109]
	v_mfma_f32_16x16x32_bf16 v[94:97], v[134:137], v[208:211], v[94:97]
	v_mfma_f32_16x16x32_bf16 v[90:93], v[142:145], v[208:211], v[90:93]
	v_mfma_f32_16x16x32_bf16 v[78:81], v[134:137], v[216:219], v[78:81]
	v_mfma_f32_16x16x32_bf16 v[74:77], v[142:145], v[216:219], v[74:77]
	s_setprio 0
	s_setprio 1
	v_mfma_f32_16x16x32_bf16 v[118:121], v[162:165], v[188:191], 0
	v_mfma_f32_16x16x32_bf16 v[114:117], v[170:173], v[188:191], 0
	v_mfma_f32_16x16x32_bf16 v[102:105], v[162:165], v[196:199], 0
	v_mfma_f32_16x16x32_bf16 v[98:101], v[170:173], v[196:199], 0
	v_mfma_f32_16x16x32_bf16 v[86:89], v[162:165], v[204:207], 0
	v_mfma_f32_16x16x32_bf16 v[82:85], v[170:173], v[204:207], 0
	v_mfma_f32_16x16x32_bf16 v[70:73], v[162:165], v[212:215], 0
	v_mfma_f32_16x16x32_bf16 v[66:69], v[170:173], v[212:215], 0
	v_mfma_f32_16x16x32_bf16 v[118:121], v[166:169], v[192:195], v[118:121]
	v_mfma_f32_16x16x32_bf16 v[114:117], v[174:177], v[192:195], v[114:117]
	v_mfma_f32_16x16x32_bf16 v[102:105], v[166:169], v[200:203], v[102:105]
	v_mfma_f32_16x16x32_bf16 v[98:101], v[174:177], v[200:203], v[98:101]
	v_mfma_f32_16x16x32_bf16 v[86:89], v[166:169], v[208:211], v[86:89]
	v_mfma_f32_16x16x32_bf16 v[82:85], v[174:177], v[208:211], v[82:85]
	v_mfma_f32_16x16x32_bf16 v[70:73], v[166:169], v[216:219], v[70:73]
	v_mfma_f32_16x16x32_bf16 v[66:69], v[174:177], v[216:219], v[66:69]
	s_barrier
	s_setprio 0
	s_add_i32 s71, s63, s54
	s_add_u32 s98, s48, 0x80
	s_addc_u32 s99, s49, 0
	s_mov_b32 m0, s71
	ds_read_b128 v[188:191], v185 offset:16384
	ds_read_b128 v[192:195], v185 offset:17408
	ds_read_b128 v[196:199], v185 offset:18432
	ds_read_b128 v[200:203], v185 offset:19456
	ds_read_b128 v[204:207], v185 offset:20480
	ds_read_b128 v[208:211], v185 offset:21504
	ds_read_b128 v[212:215], v185 offset:22528
	ds_read_b128 v[216:219], v185 offset:23552
	global_load_lds_dwordx4 v148, s[48:49]
	s_add_i32 m0, s71, 0x2000
	s_add_u32 s72, s48, 0x80000
	s_addc_u32 s73, s49, 0
	s_add_i32 s71, s64, s54
	global_load_lds_dwordx4 v152, s[48:49]
	s_mov_b32 m0, s71
	s_nop 0
	global_load_lds_dwordx4 v148, s[72:73]
	s_add_i32 m0, s71, 0x2000
	s_nop 0
	global_load_lds_dwordx4 v152, s[72:73]
	s_add_u32 s100, s52, 0x80
	s_addc_u32 s101, s53, 0
	s_mov_b32 m0, s45
	s_nop 0
	global_load_lds_dwordx4 v146, s[52:53]
	s_mov_b32 m0, s55
	s_nop 0
	global_load_lds_dwordx4 v150, s[52:53]
	s_waitcnt vmcnt(8)
	s_waitcnt lgkmcnt(0)
	s_setprio 1
	s_barrier
	v_mfma_f32_16x16x32_bf16 v[62:65], v[130:133], v[188:191], 0
	v_mfma_f32_16x16x32_bf16 v[58:61], v[138:141], v[188:191], 0
	v_mfma_f32_16x16x32_bf16 v[46:49], v[130:133], v[196:199], 0
	v_mfma_f32_16x16x32_bf16 v[42:45], v[138:141], v[196:199], 0
	v_mfma_f32_16x16x32_bf16 v[30:33], v[130:133], v[204:207], 0
	v_mfma_f32_16x16x32_bf16 v[26:29], v[138:141], v[204:207], 0
	v_mfma_f32_16x16x32_bf16 v[14:17], v[130:133], v[212:215], 0
	v_mfma_f32_16x16x32_bf16 v[10:13], v[138:141], v[212:215], 0
	v_mfma_f32_16x16x32_bf16 v[62:65], v[134:137], v[192:195], v[62:65]
	v_mfma_f32_16x16x32_bf16 v[58:61], v[142:145], v[192:195], v[58:61]
	v_mfma_f32_16x16x32_bf16 v[46:49], v[134:137], v[200:203], v[46:49]
	v_mfma_f32_16x16x32_bf16 v[42:45], v[142:145], v[200:203], v[42:45]
	v_mfma_f32_16x16x32_bf16 v[30:33], v[134:137], v[208:211], v[30:33]
	v_mfma_f32_16x16x32_bf16 v[26:29], v[142:145], v[208:211], v[26:29]
	v_mfma_f32_16x16x32_bf16 v[14:17], v[134:137], v[216:219], v[14:17]
	v_mfma_f32_16x16x32_bf16 v[10:13], v[142:145], v[216:219], v[10:13]
	s_setprio 0
	s_setprio 1
	v_mfma_f32_16x16x32_bf16 v[54:57], v[162:165], v[188:191], 0
	v_mfma_f32_16x16x32_bf16 v[50:53], v[170:173], v[188:191], 0
	v_mfma_f32_16x16x32_bf16 v[38:41], v[162:165], v[196:199], 0
	v_mfma_f32_16x16x32_bf16 v[34:37], v[170:173], v[196:199], 0
	v_mfma_f32_16x16x32_bf16 v[22:25], v[162:165], v[204:207], 0
	v_mfma_f32_16x16x32_bf16 v[18:21], v[170:173], v[204:207], 0
	v_mfma_f32_16x16x32_bf16 v[6:9], v[162:165], v[212:215], 0
	v_mfma_f32_16x16x32_bf16 v[2:5], v[170:173], v[212:215], 0
	v_mfma_f32_16x16x32_bf16 v[54:57], v[166:169], v[192:195], v[54:57]
	v_mfma_f32_16x16x32_bf16 v[50:53], v[174:177], v[192:195], v[50:53]
	v_mfma_f32_16x16x32_bf16 v[38:41], v[166:169], v[200:203], v[38:41]
	v_mfma_f32_16x16x32_bf16 v[34:37], v[174:177], v[200:203], v[34:37]
	v_mfma_f32_16x16x32_bf16 v[22:25], v[166:169], v[208:211], v[22:25]
	v_mfma_f32_16x16x32_bf16 v[18:21], v[174:177], v[208:211], v[18:21]
	v_mfma_f32_16x16x32_bf16 v[6:9], v[166:169], v[216:219], v[6:9]
	v_mfma_f32_16x16x32_bf16 v[2:5], v[174:177], v[216:219], v[2:5]
	s_barrier
	s_setprio 0
	s_add_i32 s71, 0, 0x18000
	s_add_i32 s72, 0, 0x1c000
	ds_read_b128 v[130:133], v183 offset:32768
	ds_read_b128 v[134:137], v183 offset:33792
	ds_read_b128 v[138:141], v183 offset:34816
	ds_read_b128 v[142:145], v183 offset:35840
	ds_read_b128 v[162:165], v184 offset:32768
	ds_read_b128 v[166:169], v184 offset:33792
	ds_read_b128 v[170:173], v184 offset:34816
	ds_read_b128 v[174:177], v184 offset:35840
	s_add_u32 s52, s52, 0x80000
	s_addc_u32 s53, s53, 0
	s_mov_b32 m0, s56
	ds_read_b128 v[188:191], v185 offset:32768
	ds_read_b128 v[192:195], v185 offset:33792
	ds_read_b128 v[196:199], v185 offset:34816
	ds_read_b128 v[200:203], v185 offset:35840
	ds_read_b128 v[204:207], v185 offset:36864
	ds_read_b128 v[208:211], v185 offset:37888
	ds_read_b128 v[212:215], v185 offset:38912
	ds_read_b128 v[216:219], v185 offset:39936
	global_load_lds_dwordx4 v146, s[52:53]
	s_mov_b32 m0, s57
	s_nop 0
	global_load_lds_dwordx4 v150, s[52:53]
	s_waitcnt vmcnt(8)
	s_waitcnt lgkmcnt(0)
	s_setprio 1
	s_barrier
	v_mfma_f32_16x16x32_bf16 v[126:129], v[130:133], v[188:191], v[126:129]
	v_mfma_f32_16x16x32_bf16 v[122:125], v[138:141], v[188:191], v[122:125]
	v_mfma_f32_16x16x32_bf16 v[110:113], v[130:133], v[196:199], v[110:113]
	v_mfma_f32_16x16x32_bf16 v[106:109], v[138:141], v[196:199], v[106:109]
	v_mfma_f32_16x16x32_bf16 v[94:97], v[130:133], v[204:207], v[94:97]
	v_mfma_f32_16x16x32_bf16 v[90:93], v[138:141], v[204:207], v[90:93]
	v_mfma_f32_16x16x32_bf16 v[78:81], v[130:133], v[212:215], v[78:81]
	v_mfma_f32_16x16x32_bf16 v[74:77], v[138:141], v[212:215], v[74:77]
	v_mfma_f32_16x16x32_bf16 v[126:129], v[134:137], v[192:195], v[126:129]
	v_mfma_f32_16x16x32_bf16 v[122:125], v[142:145], v[192:195], v[122:125]
	v_mfma_f32_16x16x32_bf16 v[110:113], v[134:137], v[200:203], v[110:113]
	v_mfma_f32_16x16x32_bf16 v[106:109], v[142:145], v[200:203], v[106:109]
	v_mfma_f32_16x16x32_bf16 v[94:97], v[134:137], v[208:211], v[94:97]
	v_mfma_f32_16x16x32_bf16 v[90:93], v[142:145], v[208:211], v[90:93]
	v_mfma_f32_16x16x32_bf16 v[78:81], v[134:137], v[216:219], v[78:81]
	v_mfma_f32_16x16x32_bf16 v[74:77], v[142:145], v[216:219], v[74:77]
	s_setprio 0
	s_setprio 1
	v_mfma_f32_16x16x32_bf16 v[118:121], v[162:165], v[188:191], v[118:121]
	v_mfma_f32_16x16x32_bf16 v[114:117], v[170:173], v[188:191], v[114:117]
	v_mfma_f32_16x16x32_bf16 v[102:105], v[162:165], v[196:199], v[102:105]
	v_mfma_f32_16x16x32_bf16 v[98:101], v[170:173], v[196:199], v[98:101]
	v_mfma_f32_16x16x32_bf16 v[86:89], v[162:165], v[204:207], v[86:89]
	v_mfma_f32_16x16x32_bf16 v[82:85], v[170:173], v[204:207], v[82:85]
	v_mfma_f32_16x16x32_bf16 v[70:73], v[162:165], v[212:215], v[70:73]
	v_mfma_f32_16x16x32_bf16 v[66:69], v[170:173], v[212:215], v[66:69]
	v_mfma_f32_16x16x32_bf16 v[118:121], v[166:169], v[192:195], v[118:121]
	v_mfma_f32_16x16x32_bf16 v[114:117], v[174:177], v[192:195], v[114:117]
	v_mfma_f32_16x16x32_bf16 v[102:105], v[166:169], v[200:203], v[102:105]
	v_mfma_f32_16x16x32_bf16 v[98:101], v[174:177], v[200:203], v[98:101]
	v_mfma_f32_16x16x32_bf16 v[86:89], v[166:169], v[208:211], v[86:89]
	v_mfma_f32_16x16x32_bf16 v[82:85], v[174:177], v[208:211], v[82:85]
	v_mfma_f32_16x16x32_bf16 v[70:73], v[166:169], v[216:219], v[70:73]
	v_mfma_f32_16x16x32_bf16 v[66:69], v[174:177], v[216:219], v[66:69]
	s_barrier
	s_setprio 0
	s_add_i32 s52, s71, s54
	s_mov_b32 m0, s52
	ds_read_b128 v[188:191], v185 offset:49152
	ds_read_b128 v[192:195], v185 offset:50176
	ds_read_b128 v[196:199], v185 offset:51200
	ds_read_b128 v[200:203], v185 offset:52224
	ds_read_b128 v[204:207], v185 offset:53248
	ds_read_b128 v[208:211], v185 offset:54272
	ds_read_b128 v[212:215], v185 offset:55296
	ds_read_b128 v[216:219], v185 offset:56320
	global_load_lds_dwordx4 v148, s[98:99]
	s_add_i32 m0, s52, 0x2000
	s_add_u32 s48, s48, 0x80080
	s_addc_u32 s49, s49, 0
	s_add_i32 s52, s72, s54
	global_load_lds_dwordx4 v152, s[98:99]
	s_mov_b32 m0, s52
	s_nop 0
	global_load_lds_dwordx4 v148, s[48:49]
	s_add_i32 m0, s52, 0x2000
	s_nop 0
	global_load_lds_dwordx4 v152, s[48:49]
	s_mov_b32 m0, s60
	s_nop 0
	global_load_lds_dwordx4 v146, s[100:101]
	s_mov_b32 m0, s61
	s_nop 0
	global_load_lds_dwordx4 v150, s[100:101]
	s_waitcnt vmcnt(8)
	s_waitcnt lgkmcnt(0)
	s_setprio 1
	s_barrier
	v_mfma_f32_16x16x32_bf16 v[62:65], v[130:133], v[188:191], v[62:65]
	v_mfma_f32_16x16x32_bf16 v[58:61], v[138:141], v[188:191], v[58:61]
	v_mfma_f32_16x16x32_bf16 v[46:49], v[130:133], v[196:199], v[46:49]
	v_mfma_f32_16x16x32_bf16 v[42:45], v[138:141], v[196:199], v[42:45]
	v_mfma_f32_16x16x32_bf16 v[30:33], v[130:133], v[204:207], v[30:33]
	v_mfma_f32_16x16x32_bf16 v[26:29], v[138:141], v[204:207], v[26:29]
	v_mfma_f32_16x16x32_bf16 v[14:17], v[130:133], v[212:215], v[14:17]
	v_mfma_f32_16x16x32_bf16 v[10:13], v[138:141], v[212:215], v[10:13]
	v_mfma_f32_16x16x32_bf16 v[62:65], v[134:137], v[192:195], v[62:65]
	v_mfma_f32_16x16x32_bf16 v[58:61], v[142:145], v[192:195], v[58:61]
	v_mfma_f32_16x16x32_bf16 v[46:49], v[134:137], v[200:203], v[46:49]
	v_mfma_f32_16x16x32_bf16 v[42:45], v[142:145], v[200:203], v[42:45]
	v_mfma_f32_16x16x32_bf16 v[30:33], v[134:137], v[208:211], v[30:33]
	v_mfma_f32_16x16x32_bf16 v[26:29], v[142:145], v[208:211], v[26:29]
	v_mfma_f32_16x16x32_bf16 v[14:17], v[134:137], v[216:219], v[14:17]
	v_mfma_f32_16x16x32_bf16 v[10:13], v[142:145], v[216:219], v[10:13]
	s_setprio 0
	s_setprio 1
	v_mfma_f32_16x16x32_bf16 v[54:57], v[162:165], v[188:191], v[54:57]
	v_mfma_f32_16x16x32_bf16 v[50:53], v[170:173], v[188:191], v[50:53]
	v_mfma_f32_16x16x32_bf16 v[38:41], v[162:165], v[196:199], v[38:41]
	v_mfma_f32_16x16x32_bf16 v[34:37], v[170:173], v[196:199], v[34:37]
	v_mfma_f32_16x16x32_bf16 v[22:25], v[162:165], v[204:207], v[22:25]
	v_mfma_f32_16x16x32_bf16 v[18:21], v[170:173], v[204:207], v[18:21]
	v_mfma_f32_16x16x32_bf16 v[6:9], v[162:165], v[212:215], v[6:9]
	v_mfma_f32_16x16x32_bf16 v[2:5], v[170:173], v[212:215], v[2:5]
	v_mfma_f32_16x16x32_bf16 v[54:57], v[166:169], v[192:195], v[54:57]
	v_mfma_f32_16x16x32_bf16 v[50:53], v[174:177], v[192:195], v[50:53]
	v_mfma_f32_16x16x32_bf16 v[38:41], v[166:169], v[200:203], v[38:41]
	v_mfma_f32_16x16x32_bf16 v[34:37], v[174:177], v[200:203], v[34:37]
	v_mfma_f32_16x16x32_bf16 v[22:25], v[166:169], v[208:211], v[22:25]
	v_mfma_f32_16x16x32_bf16 v[18:21], v[174:177], v[208:211], v[18:21]
	v_mfma_f32_16x16x32_bf16 v[6:9], v[166:169], v[216:219], v[6:9]
	v_mfma_f32_16x16x32_bf16 v[2:5], v[174:177], v[216:219], v[2:5]
	s_barrier
	s_setprio 0
	s_add_i32 s70, s70, 2
	s_add_u32 s46, s46, 0x100
	s_addc_u32 s47, s47, 0
	s_add_u32 s68, s68, 0x100
	s_addc_u32 s69, s69, 0
	s_cmp_gt_u32 s70, 29
.LBB0_1408:
	ds_read_b128 v[130:133], v183
	ds_read_b128 v[134:137], v183 offset:1024
	ds_read_b128 v[138:141], v183 offset:2048
	ds_read_b128 v[142:145], v183 offset:3072
	ds_read_b128 v[162:165], v184
	ds_read_b128 v[166:169], v184 offset:1024
	ds_read_b128 v[170:173], v184 offset:2048
	ds_read_b128 v[174:177], v184 offset:3072
	s_add_u32 s48, s46, 0xfff80080
	s_addc_u32 s49, s47, -1
	s_cmp_eq_u32 s70, 28
	s_cselect_b32 s53, s39, s49
	s_cselect_b32 s52, s66, s48
	s_cselect_b32 s49, s37, s69
	s_cselect_b32 s48, s67, s68
	s_add_i32 m0, s45, 0xc000
	ds_read_b128 v[188:191], v185
	ds_read_b128 v[192:195], v185 offset:1024
	ds_read_b128 v[196:199], v185 offset:2048
	ds_read_b128 v[200:203], v185 offset:3072
	ds_read_b128 v[204:207], v185 offset:4096
	ds_read_b128 v[208:211], v185 offset:5120
	ds_read_b128 v[212:215], v185 offset:6144
	ds_read_b128 v[216:219], v185 offset:7168
	global_load_lds_dwordx4 v154, s[46:47]
	s_add_i32 m0, s45, 0xe000
	s_nop 0
	global_load_lds_dwordx4 v156, s[46:47]
	s_waitcnt vmcnt(8)
	s_waitcnt lgkmcnt(0)
	s_setprio 1
	s_barrier
	v_mfma_f32_16x16x32_bf16 v[126:129], v[130:133], v[188:191], v[126:129]
	v_mfma_f32_16x16x32_bf16 v[122:125], v[138:141], v[188:191], v[122:125]
	v_mfma_f32_16x16x32_bf16 v[110:113], v[130:133], v[196:199], v[110:113]
	v_mfma_f32_16x16x32_bf16 v[106:109], v[138:141], v[196:199], v[106:109]
	v_mfma_f32_16x16x32_bf16 v[94:97], v[130:133], v[204:207], v[94:97]
	v_mfma_f32_16x16x32_bf16 v[90:93], v[138:141], v[204:207], v[90:93]
	v_mfma_f32_16x16x32_bf16 v[78:81], v[130:133], v[212:215], v[78:81]
	v_mfma_f32_16x16x32_bf16 v[74:77], v[138:141], v[212:215], v[74:77]
	v_mfma_f32_16x16x32_bf16 v[126:129], v[134:137], v[192:195], v[126:129]
	v_mfma_f32_16x16x32_bf16 v[122:125], v[142:145], v[192:195], v[122:125]
	v_mfma_f32_16x16x32_bf16 v[110:113], v[134:137], v[200:203], v[110:113]
	v_mfma_f32_16x16x32_bf16 v[106:109], v[142:145], v[200:203], v[106:109]
	v_mfma_f32_16x16x32_bf16 v[94:97], v[134:137], v[208:211], v[94:97]
	v_mfma_f32_16x16x32_bf16 v[90:93], v[142:145], v[208:211], v[90:93]
	v_mfma_f32_16x16x32_bf16 v[78:81], v[134:137], v[216:219], v[78:81]
	v_mfma_f32_16x16x32_bf16 v[74:77], v[142:145], v[216:219], v[74:77]
	s_setprio 0
	s_setprio 1
	v_mfma_f32_16x16x32_bf16 v[118:121], v[162:165], v[188:191], v[118:121]
	v_mfma_f32_16x16x32_bf16 v[114:117], v[170:173], v[188:191], v[114:117]
	v_mfma_f32_16x16x32_bf16 v[102:105], v[162:165], v[196:199], v[102:105]
	v_mfma_f32_16x16x32_bf16 v[98:101], v[170:173], v[196:199], v[98:101]
	v_mfma_f32_16x16x32_bf16 v[86:89], v[162:165], v[204:207], v[86:89]
	v_mfma_f32_16x16x32_bf16 v[82:85], v[170:173], v[204:207], v[82:85]
	v_mfma_f32_16x16x32_bf16 v[70:73], v[162:165], v[212:215], v[70:73]
	v_mfma_f32_16x16x32_bf16 v[66:69], v[170:173], v[212:215], v[66:69]
	v_mfma_f32_16x16x32_bf16 v[118:121], v[166:169], v[192:195], v[118:121]
	v_mfma_f32_16x16x32_bf16 v[114:117], v[174:177], v[192:195], v[114:117]
	v_mfma_f32_16x16x32_bf16 v[102:105], v[166:169], v[200:203], v[102:105]
	v_mfma_f32_16x16x32_bf16 v[98:101], v[174:177], v[200:203], v[98:101]
	v_mfma_f32_16x16x32_bf16 v[86:89], v[166:169], v[208:211], v[86:89]
	v_mfma_f32_16x16x32_bf16 v[82:85], v[174:177], v[208:211], v[82:85]
	v_mfma_f32_16x16x32_bf16 v[70:73], v[166:169], v[216:219], v[70:73]
	v_mfma_f32_16x16x32_bf16 v[66:69], v[174:177], v[216:219], v[66:69]
	s_barrier
	s_setprio 0
	s_add_i32 s71, s63, s54
	s_add_u32 s98, s48, 0x80
	s_addc_u32 s99, s49, 0
	s_mov_b32 m0, s71
	ds_read_b128 v[188:191], v185 offset:16384
	ds_read_b128 v[192:195], v185 offset:17408
	ds_read_b128 v[196:199], v185 offset:18432
	ds_read_b128 v[200:203], v185 offset:19456
	ds_read_b128 v[204:207], v185 offset:20480
	ds_read_b128 v[208:211], v185 offset:21504
	ds_read_b128 v[212:215], v185 offset:22528
	ds_read_b128 v[216:219], v185 offset:23552
	global_load_lds_dwordx4 v148, s[48:49]
	s_add_i32 m0, s71, 0x2000
	s_add_u32 s72, s48, 0x80000
	s_addc_u32 s73, s49, 0
	s_add_i32 s71, s64, s54
	global_load_lds_dwordx4 v152, s[48:49]
	s_mov_b32 m0, s71
	s_nop 0
	global_load_lds_dwordx4 v148, s[72:73]
	s_add_i32 m0, s71, 0x2000
	s_nop 0
	global_load_lds_dwordx4 v152, s[72:73]
	s_add_u32 s100, s52, 0x80
	s_addc_u32 s101, s53, 0
	s_mov_b32 m0, s45
	s_nop 0
	global_load_lds_dwordx4 v146, s[52:53]
	s_mov_b32 m0, s55
	s_nop 0
	global_load_lds_dwordx4 v150, s[52:53]
	s_waitcnt vmcnt(8)
	s_waitcnt lgkmcnt(0)
	s_setprio 1
	s_barrier
	v_mfma_f32_16x16x32_bf16 v[62:65], v[130:133], v[188:191], v[62:65]
	v_mfma_f32_16x16x32_bf16 v[58:61], v[138:141], v[188:191], v[58:61]
	v_mfma_f32_16x16x32_bf16 v[46:49], v[130:133], v[196:199], v[46:49]
	v_mfma_f32_16x16x32_bf16 v[42:45], v[138:141], v[196:199], v[42:45]
	v_mfma_f32_16x16x32_bf16 v[30:33], v[130:133], v[204:207], v[30:33]
	v_mfma_f32_16x16x32_bf16 v[26:29], v[138:141], v[204:207], v[26:29]
	v_mfma_f32_16x16x32_bf16 v[14:17], v[130:133], v[212:215], v[14:17]
	v_mfma_f32_16x16x32_bf16 v[10:13], v[138:141], v[212:215], v[10:13]
	v_mfma_f32_16x16x32_bf16 v[62:65], v[134:137], v[192:195], v[62:65]
	v_mfma_f32_16x16x32_bf16 v[58:61], v[142:145], v[192:195], v[58:61]
	v_mfma_f32_16x16x32_bf16 v[46:49], v[134:137], v[200:203], v[46:49]
	v_mfma_f32_16x16x32_bf16 v[42:45], v[142:145], v[200:203], v[42:45]
	v_mfma_f32_16x16x32_bf16 v[30:33], v[134:137], v[208:211], v[30:33]
	v_mfma_f32_16x16x32_bf16 v[26:29], v[142:145], v[208:211], v[26:29]
	v_mfma_f32_16x16x32_bf16 v[14:17], v[134:137], v[216:219], v[14:17]
	v_mfma_f32_16x16x32_bf16 v[10:13], v[142:145], v[216:219], v[10:13]
	s_setprio 0
	s_setprio 1
	v_mfma_f32_16x16x32_bf16 v[54:57], v[162:165], v[188:191], v[54:57]
	v_mfma_f32_16x16x32_bf16 v[50:53], v[170:173], v[188:191], v[50:53]
	v_mfma_f32_16x16x32_bf16 v[38:41], v[162:165], v[196:199], v[38:41]
	v_mfma_f32_16x16x32_bf16 v[34:37], v[170:173], v[196:199], v[34:37]
	v_mfma_f32_16x16x32_bf16 v[22:25], v[162:165], v[204:207], v[22:25]
	v_mfma_f32_16x16x32_bf16 v[18:21], v[170:173], v[204:207], v[18:21]
	v_mfma_f32_16x16x32_bf16 v[6:9], v[162:165], v[212:215], v[6:9]
	v_mfma_f32_16x16x32_bf16 v[2:5], v[170:173], v[212:215], v[2:5]
	v_mfma_f32_16x16x32_bf16 v[54:57], v[166:169], v[192:195], v[54:57]
	v_mfma_f32_16x16x32_bf16 v[50:53], v[174:177], v[192:195], v[50:53]
	v_mfma_f32_16x16x32_bf16 v[38:41], v[166:169], v[200:203], v[38:41]
	v_mfma_f32_16x16x32_bf16 v[34:37], v[174:177], v[200:203], v[34:37]
	v_mfma_f32_16x16x32_bf16 v[22:25], v[166:169], v[208:211], v[22:25]
	v_mfma_f32_16x16x32_bf16 v[18:21], v[174:177], v[208:211], v[18:21]
	v_mfma_f32_16x16x32_bf16 v[6:9], v[166:169], v[216:219], v[6:9]
	v_mfma_f32_16x16x32_bf16 v[2:5], v[174:177], v[216:219], v[2:5]
	s_barrier
	s_setprio 0
	s_add_i32 s71, 0, 0x18000
	s_add_i32 s72, 0, 0x1c000
	ds_read_b128 v[130:133], v183 offset:32768
	ds_read_b128 v[134:137], v183 offset:33792
	ds_read_b128 v[138:141], v183 offset:34816
	ds_read_b128 v[142:145], v183 offset:35840
	ds_read_b128 v[162:165], v184 offset:32768
	ds_read_b128 v[166:169], v184 offset:33792
	ds_read_b128 v[170:173], v184 offset:34816
	ds_read_b128 v[174:177], v184 offset:35840
	s_add_u32 s52, s52, 0x80000
	s_addc_u32 s53, s53, 0
	s_mov_b32 m0, s56
	ds_read_b128 v[188:191], v185 offset:32768
	ds_read_b128 v[192:195], v185 offset:33792
	ds_read_b128 v[196:199], v185 offset:34816
	ds_read_b128 v[200:203], v185 offset:35840
	ds_read_b128 v[204:207], v185 offset:36864
	ds_read_b128 v[208:211], v185 offset:37888
	ds_read_b128 v[212:215], v185 offset:38912
	ds_read_b128 v[216:219], v185 offset:39936
	global_load_lds_dwordx4 v146, s[52:53]
	s_mov_b32 m0, s57
	s_nop 0
	global_load_lds_dwordx4 v150, s[52:53]
	s_waitcnt vmcnt(8)
	s_waitcnt lgkmcnt(0)
	s_setprio 1
	s_barrier
	v_mfma_f32_16x16x32_bf16 v[126:129], v[130:133], v[188:191], v[126:129]
	v_mfma_f32_16x16x32_bf16 v[122:125], v[138:141], v[188:191], v[122:125]
	v_mfma_f32_16x16x32_bf16 v[110:113], v[130:133], v[196:199], v[110:113]
	v_mfma_f32_16x16x32_bf16 v[106:109], v[138:141], v[196:199], v[106:109]
	v_mfma_f32_16x16x32_bf16 v[94:97], v[130:133], v[204:207], v[94:97]
	v_mfma_f32_16x16x32_bf16 v[90:93], v[138:141], v[204:207], v[90:93]
	v_mfma_f32_16x16x32_bf16 v[78:81], v[130:133], v[212:215], v[78:81]
	v_mfma_f32_16x16x32_bf16 v[74:77], v[138:141], v[212:215], v[74:77]
	v_mfma_f32_16x16x32_bf16 v[126:129], v[134:137], v[192:195], v[126:129]
	v_mfma_f32_16x16x32_bf16 v[122:125], v[142:145], v[192:195], v[122:125]
	v_mfma_f32_16x16x32_bf16 v[110:113], v[134:137], v[200:203], v[110:113]
	v_mfma_f32_16x16x32_bf16 v[106:109], v[142:145], v[200:203], v[106:109]
	v_mfma_f32_16x16x32_bf16 v[94:97], v[134:137], v[208:211], v[94:97]
	v_mfma_f32_16x16x32_bf16 v[90:93], v[142:145], v[208:211], v[90:93]
	v_mfma_f32_16x16x32_bf16 v[78:81], v[134:137], v[216:219], v[78:81]
	v_mfma_f32_16x16x32_bf16 v[74:77], v[142:145], v[216:219], v[74:77]
	s_setprio 0
	s_setprio 1
	v_mfma_f32_16x16x32_bf16 v[118:121], v[162:165], v[188:191], v[118:121]
	v_mfma_f32_16x16x32_bf16 v[114:117], v[170:173], v[188:191], v[114:117]
	v_mfma_f32_16x16x32_bf16 v[102:105], v[162:165], v[196:199], v[102:105]
	v_mfma_f32_16x16x32_bf16 v[98:101], v[170:173], v[196:199], v[98:101]
	v_mfma_f32_16x16x32_bf16 v[86:89], v[162:165], v[204:207], v[86:89]
	v_mfma_f32_16x16x32_bf16 v[82:85], v[170:173], v[204:207], v[82:85]
	v_mfma_f32_16x16x32_bf16 v[70:73], v[162:165], v[212:215], v[70:73]
	v_mfma_f32_16x16x32_bf16 v[66:69], v[170:173], v[212:215], v[66:69]
	v_mfma_f32_16x16x32_bf16 v[118:121], v[166:169], v[192:195], v[118:121]
	v_mfma_f32_16x16x32_bf16 v[114:117], v[174:177], v[192:195], v[114:117]
	v_mfma_f32_16x16x32_bf16 v[102:105], v[166:169], v[200:203], v[102:105]
	v_mfma_f32_16x16x32_bf16 v[98:101], v[174:177], v[200:203], v[98:101]
	v_mfma_f32_16x16x32_bf16 v[86:89], v[166:169], v[208:211], v[86:89]
	v_mfma_f32_16x16x32_bf16 v[82:85], v[174:177], v[208:211], v[82:85]
	v_mfma_f32_16x16x32_bf16 v[70:73], v[166:169], v[216:219], v[70:73]
	v_mfma_f32_16x16x32_bf16 v[66:69], v[174:177], v[216:219], v[66:69]
	s_barrier
	s_setprio 0
	s_add_i32 s52, s71, s54
	s_mov_b32 m0, s52
	ds_read_b128 v[188:191], v185 offset:49152
	ds_read_b128 v[192:195], v185 offset:50176
	ds_read_b128 v[196:199], v185 offset:51200
	ds_read_b128 v[200:203], v185 offset:52224
	ds_read_b128 v[204:207], v185 offset:53248
	ds_read_b128 v[208:211], v185 offset:54272
	ds_read_b128 v[212:215], v185 offset:55296
	ds_read_b128 v[216:219], v185 offset:56320
	global_load_lds_dwordx4 v148, s[98:99]
	s_add_i32 m0, s52, 0x2000
	s_add_u32 s48, s48, 0x80080
	s_addc_u32 s49, s49, 0
	s_add_i32 s52, s72, s54
	global_load_lds_dwordx4 v152, s[98:99]
	s_mov_b32 m0, s52
	s_nop 0
	global_load_lds_dwordx4 v148, s[48:49]
	s_add_i32 m0, s52, 0x2000
	s_nop 0
	global_load_lds_dwordx4 v152, s[48:49]
	s_mov_b32 m0, s60
	s_nop 0
	global_load_lds_dwordx4 v146, s[100:101]
	s_mov_b32 m0, s61
	s_nop 0
	global_load_lds_dwordx4 v150, s[100:101]
	s_add_i32 s70, s70, 2
	s_add_u32 s46, s46, 0x100
	s_addc_u32 s47, s47, 0
	s_add_u32 s68, s68, 0x100
	s_addc_u32 s69, s69, 0
	s_cmp_gt_u32 s70, 29
	s_waitcnt vmcnt(8)
	s_waitcnt lgkmcnt(0)
	s_setprio 1
	s_barrier
	v_mfma_f32_16x16x32_bf16 v[62:65], v[130:133], v[188:191], v[62:65]
	v_mfma_f32_16x16x32_bf16 v[58:61], v[138:141], v[188:191], v[58:61]
	v_mfma_f32_16x16x32_bf16 v[46:49], v[130:133], v[196:199], v[46:49]
	v_mfma_f32_16x16x32_bf16 v[42:45], v[138:141], v[196:199], v[42:45]
	v_mfma_f32_16x16x32_bf16 v[30:33], v[130:133], v[204:207], v[30:33]
	v_mfma_f32_16x16x32_bf16 v[26:29], v[138:141], v[204:207], v[26:29]
	v_mfma_f32_16x16x32_bf16 v[14:17], v[130:133], v[212:215], v[14:17]
	v_mfma_f32_16x16x32_bf16 v[10:13], v[138:141], v[212:215], v[10:13]
	v_mfma_f32_16x16x32_bf16 v[62:65], v[134:137], v[192:195], v[62:65]
	v_mfma_f32_16x16x32_bf16 v[58:61], v[142:145], v[192:195], v[58:61]
	v_mfma_f32_16x16x32_bf16 v[46:49], v[134:137], v[200:203], v[46:49]
	v_mfma_f32_16x16x32_bf16 v[42:45], v[142:145], v[200:203], v[42:45]
	v_mfma_f32_16x16x32_bf16 v[30:33], v[134:137], v[208:211], v[30:33]
	v_mfma_f32_16x16x32_bf16 v[26:29], v[142:145], v[208:211], v[26:29]
	v_mfma_f32_16x16x32_bf16 v[14:17], v[134:137], v[216:219], v[14:17]
	v_mfma_f32_16x16x32_bf16 v[10:13], v[142:145], v[216:219], v[10:13]
	s_setprio 0
	s_setprio 1
	v_mfma_f32_16x16x32_bf16 v[54:57], v[162:165], v[188:191], v[54:57]
	v_mfma_f32_16x16x32_bf16 v[50:53], v[170:173], v[188:191], v[50:53]
	v_mfma_f32_16x16x32_bf16 v[38:41], v[162:165], v[196:199], v[38:41]
	v_mfma_f32_16x16x32_bf16 v[34:37], v[170:173], v[196:199], v[34:37]
	v_mfma_f32_16x16x32_bf16 v[22:25], v[162:165], v[204:207], v[22:25]
	v_mfma_f32_16x16x32_bf16 v[18:21], v[170:173], v[204:207], v[18:21]
	v_mfma_f32_16x16x32_bf16 v[6:9], v[162:165], v[212:215], v[6:9]
	v_mfma_f32_16x16x32_bf16 v[2:5], v[170:173], v[212:215], v[2:5]
	v_mfma_f32_16x16x32_bf16 v[54:57], v[166:169], v[192:195], v[54:57]
	v_mfma_f32_16x16x32_bf16 v[50:53], v[174:177], v[192:195], v[50:53]
	v_mfma_f32_16x16x32_bf16 v[38:41], v[166:169], v[200:203], v[38:41]
	v_mfma_f32_16x16x32_bf16 v[34:37], v[174:177], v[200:203], v[34:37]
	v_mfma_f32_16x16x32_bf16 v[22:25], v[166:169], v[208:211], v[22:25]
	v_mfma_f32_16x16x32_bf16 v[18:21], v[174:177], v[208:211], v[18:21]
	v_mfma_f32_16x16x32_bf16 v[6:9], v[166:169], v[216:219], v[6:9]
	v_mfma_f32_16x16x32_bf16 v[2:5], v[174:177], v[216:219], v[2:5]
	s_barrier
	s_setprio 0
	s_cbranch_scc0 .LBB0_1408
	s_and_b64 vcc, exec, s[34:35]
	s_cbranch_vccz .LBB0_1411
	s_barrier

.LBB0_1478:
	s_ashr_i32 s11, s10, 31
	s_lshl_b64 s[6:7], s[10:11], 20
	s_add_u32 s38, s19, s6
	s_addc_u32 s39, s22, s7
	s_and_b64 s[6:7], s[2:3], exec
	s_cselect_b32 s9, s39, s1
	s_cselect_b32 s11, s38, s0
	s_ashr_i32 s37, s36, 31
	s_lshl_b64 s[6:7], s[36:37], 20
	s_add_u32 s40, s23, s6
	s_addc_u32 s41, s28, s7
	s_and_b64 s[6:7], s[2:3], exec
	s_cselect_b32 s37, s41, s5
	s_cselect_b32 s60, s40, s4
	s_add_u32 s0, s0, 0x80080
	s_addc_u32 s1, s1, 0
	s_add_u32 s61, s4, 0x100
	s_addc_u32 s62, s5, 0
	s_mov_b32 s63, -2
	ds_read_b128 v[132:135], v174
	ds_read_b128 v[158:161], v174 offset:1024
	ds_read_b128 v[166:169], v174 offset:2048
	ds_read_b128 v[170:173], v174 offset:3072
	ds_read_b128 v[182:185], v175
	ds_read_b128 v[186:189], v175 offset:1024
	ds_read_b128 v[190:193], v175 offset:2048
	ds_read_b128 v[194:197], v175 offset:3072
	s_add_u32 s4, s0, 0xfff80080
	s_addc_u32 s5, s1, -1
	s_cmp_eq_u32 s63, 28
	s_cselect_b32 s7, s9, s5
	s_cselect_b32 s6, s11, s4
	s_cselect_b32 s5, s37, s62
	s_cselect_b32 s4, s60, s61
	s_add_i32 m0, s44, 0xc000
	ds_read_b128 v[198:201], v176
	ds_read_b128 v[202:205], v176 offset:1024
	ds_read_b128 v[206:209], v176 offset:2048
	ds_read_b128 v[210:213], v176 offset:3072
	ds_read_b128 v[214:217], v176 offset:4096
	ds_read_b128 v[218:221], v176 offset:5120
	ds_read_b128 v[222:225], v176 offset:6144
	ds_read_b128 v[226:229], v176 offset:7168
	global_load_lds_dwordx4 v146, s[0:1]
	s_add_i32 m0, s44, 0xe000
	s_nop 0
	global_load_lds_dwordx4 v148, s[0:1]
	s_waitcnt vmcnt(8)
	s_waitcnt lgkmcnt(0)
	s_setprio 1
	s_barrier
	v_mfma_f32_16x16x32_bf16 v[128:131], v[132:135], v[198:201], 0
	v_mfma_f32_16x16x32_bf16 v[124:127], v[166:169], v[198:201], 0
	v_mfma_f32_16x16x32_bf16 v[112:115], v[132:135], v[206:209], 0
	v_mfma_f32_16x16x32_bf16 v[108:111], v[166:169], v[206:209], 0
	v_mfma_f32_16x16x32_bf16 v[96:99], v[132:135], v[214:217], 0
	v_mfma_f32_16x16x32_bf16 v[92:95], v[166:169], v[214:217], 0
	v_mfma_f32_16x16x32_bf16 v[80:83], v[132:135], v[222:225], 0
	v_mfma_f32_16x16x32_bf16 v[76:79], v[166:169], v[222:225], 0
	v_mfma_f32_16x16x32_bf16 v[128:131], v[158:161], v[202:205], v[128:131]
	v_mfma_f32_16x16x32_bf16 v[124:127], v[170:173], v[202:205], v[124:127]
	v_mfma_f32_16x16x32_bf16 v[112:115], v[158:161], v[210:213], v[112:115]
	v_mfma_f32_16x16x32_bf16 v[108:111], v[170:173], v[210:213], v[108:111]
	v_mfma_f32_16x16x32_bf16 v[96:99], v[158:161], v[218:221], v[96:99]
	v_mfma_f32_16x16x32_bf16 v[92:95], v[170:173], v[218:221], v[92:95]
	v_mfma_f32_16x16x32_bf16 v[80:83], v[158:161], v[226:229], v[80:83]
	v_mfma_f32_16x16x32_bf16 v[76:79], v[170:173], v[226:229], v[76:79]
	s_setprio 0
	s_setprio 1
	v_mfma_f32_16x16x32_bf16 v[120:123], v[182:185], v[198:201], 0
	v_mfma_f32_16x16x32_bf16 v[116:119], v[190:193], v[198:201], 0
	v_mfma_f32_16x16x32_bf16 v[104:107], v[182:185], v[206:209], 0
	v_mfma_f32_16x16x32_bf16 v[100:103], v[190:193], v[206:209], 0
	v_mfma_f32_16x16x32_bf16 v[88:91], v[182:185], v[214:217], 0
	v_mfma_f32_16x16x32_bf16 v[84:87], v[190:193], v[214:217], 0
	v_mfma_f32_16x16x32_bf16 v[72:75], v[182:185], v[222:225], 0
	v_mfma_f32_16x16x32_bf16 v[68:71], v[190:193], v[222:225], 0
	v_mfma_f32_16x16x32_bf16 v[120:123], v[186:189], v[202:205], v[120:123]
	v_mfma_f32_16x16x32_bf16 v[116:119], v[194:197], v[202:205], v[116:119]
	v_mfma_f32_16x16x32_bf16 v[104:107], v[186:189], v[210:213], v[104:107]
	v_mfma_f32_16x16x32_bf16 v[100:103], v[194:197], v[210:213], v[100:103]
	v_mfma_f32_16x16x32_bf16 v[88:91], v[186:189], v[218:221], v[88:91]
	v_mfma_f32_16x16x32_bf16 v[84:87], v[194:197], v[218:221], v[84:87]
	v_mfma_f32_16x16x32_bf16 v[72:75], v[186:189], v[226:229], v[72:75]
	v_mfma_f32_16x16x32_bf16 v[68:71], v[194:197], v[226:229], v[68:71]
	s_barrier
	s_setprio 0
	s_add_i32 s64, s54, s29
	s_add_u32 s98, s4, 0x80
	s_addc_u32 s99, s5, 0
	s_mov_b32 m0, s64
	ds_read_b128 v[198:201], v176 offset:16384
	ds_read_b128 v[202:205], v176 offset:17408
	ds_read_b128 v[206:209], v176 offset:18432
	ds_read_b128 v[210:213], v176 offset:19456
	ds_read_b128 v[214:217], v176 offset:20480
	ds_read_b128 v[218:221], v176 offset:21504
	ds_read_b128 v[222:225], v176 offset:22528
	ds_read_b128 v[226:229], v176 offset:23552
	global_load_lds_dwordx4 v142, s[4:5]
	s_add_i32 m0, s64, 0x2000
	s_add_u32 s64, s4, 0x80000
	s_addc_u32 s65, s5, 0
	s_add_i32 s66, s55, s29
	global_load_lds_dwordx4 v138, s[4:5]
	s_mov_b32 m0, s66
	s_nop 0
	global_load_lds_dwordx4 v142, s[64:65]
	s_add_i32 m0, s66, 0x2000
	s_nop 0
	global_load_lds_dwordx4 v138, s[64:65]
	s_add_u32 s100, s6, 0x80
	s_addc_u32 s101, s7, 0
	s_mov_b32 m0, s44
	s_nop 0
	global_load_lds_dwordx4 v144, s[6:7]
	s_mov_b32 m0, s45
	s_nop 0
	global_load_lds_dwordx4 v140, s[6:7]
	s_waitcnt vmcnt(8)
	s_waitcnt lgkmcnt(0)
	s_setprio 1
	s_barrier
	v_mfma_f32_16x16x32_bf16 v[62:65], v[132:135], v[198:201], 0
	v_mfma_f32_16x16x32_bf16 v[58:61], v[166:169], v[198:201], 0
	v_mfma_f32_16x16x32_bf16 v[46:49], v[132:135], v[206:209], 0
	v_mfma_f32_16x16x32_bf16 v[42:45], v[166:169], v[206:209], 0
	v_mfma_f32_16x16x32_bf16 v[30:33], v[132:135], v[214:217], 0
	v_mfma_f32_16x16x32_bf16 v[26:29], v[166:169], v[214:217], 0
	v_mfma_f32_16x16x32_bf16 v[14:17], v[132:135], v[222:225], 0
	v_mfma_f32_16x16x32_bf16 v[10:13], v[166:169], v[222:225], 0
	v_mfma_f32_16x16x32_bf16 v[62:65], v[158:161], v[202:205], v[62:65]
	v_mfma_f32_16x16x32_bf16 v[58:61], v[170:173], v[202:205], v[58:61]
	v_mfma_f32_16x16x32_bf16 v[46:49], v[158:161], v[210:213], v[46:49]
	v_mfma_f32_16x16x32_bf16 v[42:45], v[170:173], v[210:213], v[42:45]
	v_mfma_f32_16x16x32_bf16 v[30:33], v[158:161], v[218:221], v[30:33]
	v_mfma_f32_16x16x32_bf16 v[26:29], v[170:173], v[218:221], v[26:29]
	v_mfma_f32_16x16x32_bf16 v[14:17], v[158:161], v[226:229], v[14:17]
	v_mfma_f32_16x16x32_bf16 v[10:13], v[170:173], v[226:229], v[10:13]
	s_setprio 0
	s_setprio 1
	v_mfma_f32_16x16x32_bf16 v[54:57], v[182:185], v[198:201], 0
	v_mfma_f32_16x16x32_bf16 v[50:53], v[190:193], v[198:201], 0
	v_mfma_f32_16x16x32_bf16 v[38:41], v[182:185], v[206:209], 0
	v_mfma_f32_16x16x32_bf16 v[34:37], v[190:193], v[206:209], 0
	v_mfma_f32_16x16x32_bf16 v[22:25], v[182:185], v[214:217], 0
	v_mfma_f32_16x16x32_bf16 v[18:21], v[190:193], v[214:217], 0
	v_mfma_f32_16x16x32_bf16 v[6:9], v[182:185], v[222:225], 0
	v_mfma_f32_16x16x32_bf16 v[2:5], v[190:193], v[222:225], 0
	v_mfma_f32_16x16x32_bf16 v[54:57], v[186:189], v[202:205], v[54:57]
	v_mfma_f32_16x16x32_bf16 v[50:53], v[194:197], v[202:205], v[50:53]
	v_mfma_f32_16x16x32_bf16 v[38:41], v[186:189], v[210:213], v[38:41]
	v_mfma_f32_16x16x32_bf16 v[34:37], v[194:197], v[210:213], v[34:37]
	v_mfma_f32_16x16x32_bf16 v[22:25], v[186:189], v[218:221], v[22:25]
	v_mfma_f32_16x16x32_bf16 v[18:21], v[194:197], v[218:221], v[18:21]
	v_mfma_f32_16x16x32_bf16 v[6:9], v[186:189], v[226:229], v[6:9]
	v_mfma_f32_16x16x32_bf16 v[2:5], v[194:197], v[226:229], v[2:5]
	s_barrier
	s_setprio 0
	s_add_i32 s64, 0, 0x18000
	s_add_i32 s65, 0, 0x1c000
	ds_read_b128 v[132:135], v174 offset:32768
	ds_read_b128 v[158:161], v174 offset:33792
	ds_read_b128 v[166:169], v174 offset:34816
	ds_read_b128 v[170:173], v174 offset:35840
	ds_read_b128 v[182:185], v175 offset:32768
	ds_read_b128 v[186:189], v175 offset:33792
	ds_read_b128 v[190:193], v175 offset:34816
	ds_read_b128 v[194:197], v175 offset:35840
	s_add_u32 s6, s6, 0x80000
	s_addc_u32 s7, s7, 0
	s_mov_b32 m0, s46
	ds_read_b128 v[198:201], v176 offset:32768
	ds_read_b128 v[202:205], v176 offset:33792
	ds_read_b128 v[206:209], v176 offset:34816
	ds_read_b128 v[210:213], v176 offset:35840
	ds_read_b128 v[214:217], v176 offset:36864
	ds_read_b128 v[218:221], v176 offset:37888
	ds_read_b128 v[222:225], v176 offset:38912
	ds_read_b128 v[226:229], v176 offset:39936
	global_load_lds_dwordx4 v144, s[6:7]
	s_mov_b32 m0, s47
	s_nop 0
	global_load_lds_dwordx4 v140, s[6:7]
	s_waitcnt vmcnt(8)
	s_waitcnt lgkmcnt(0)
	s_setprio 1
	s_barrier
	v_mfma_f32_16x16x32_bf16 v[128:131], v[132:135], v[198:201], v[128:131]
	v_mfma_f32_16x16x32_bf16 v[124:127], v[166:169], v[198:201], v[124:127]
	v_mfma_f32_16x16x32_bf16 v[112:115], v[132:135], v[206:209], v[112:115]
	v_mfma_f32_16x16x32_bf16 v[108:111], v[166:169], v[206:209], v[108:111]
	v_mfma_f32_16x16x32_bf16 v[96:99], v[132:135], v[214:217], v[96:99]
	v_mfma_f32_16x16x32_bf16 v[92:95], v[166:169], v[214:217], v[92:95]
	v_mfma_f32_16x16x32_bf16 v[80:83], v[132:135], v[222:225], v[80:83]
	v_mfma_f32_16x16x32_bf16 v[76:79], v[166:169], v[222:225], v[76:79]
	v_mfma_f32_16x16x32_bf16 v[128:131], v[158:161], v[202:205], v[128:131]
	v_mfma_f32_16x16x32_bf16 v[124:127], v[170:173], v[202:205], v[124:127]
	v_mfma_f32_16x16x32_bf16 v[112:115], v[158:161], v[210:213], v[112:115]
	v_mfma_f32_16x16x32_bf16 v[108:111], v[170:173], v[210:213], v[108:111]
	v_mfma_f32_16x16x32_bf16 v[96:99], v[158:161], v[218:221], v[96:99]
	v_mfma_f32_16x16x32_bf16 v[92:95], v[170:173], v[218:221], v[92:95]
	v_mfma_f32_16x16x32_bf16 v[80:83], v[158:161], v[226:229], v[80:83]
	v_mfma_f32_16x16x32_bf16 v[76:79], v[170:173], v[226:229], v[76:79]
	s_setprio 0
	s_setprio 1
	v_mfma_f32_16x16x32_bf16 v[120:123], v[182:185], v[198:201], v[120:123]
	v_mfma_f32_16x16x32_bf16 v[116:119], v[190:193], v[198:201], v[116:119]
	v_mfma_f32_16x16x32_bf16 v[104:107], v[182:185], v[206:209], v[104:107]
	v_mfma_f32_16x16x32_bf16 v[100:103], v[190:193], v[206:209], v[100:103]
	v_mfma_f32_16x16x32_bf16 v[88:91], v[182:185], v[214:217], v[88:91]
	v_mfma_f32_16x16x32_bf16 v[84:87], v[190:193], v[214:217], v[84:87]
	v_mfma_f32_16x16x32_bf16 v[72:75], v[182:185], v[222:225], v[72:75]
	v_mfma_f32_16x16x32_bf16 v[68:71], v[190:193], v[222:225], v[68:71]
	v_mfma_f32_16x16x32_bf16 v[120:123], v[186:189], v[202:205], v[120:123]
	v_mfma_f32_16x16x32_bf16 v[116:119], v[194:197], v[202:205], v[116:119]
	v_mfma_f32_16x16x32_bf16 v[104:107], v[186:189], v[210:213], v[104:107]
	v_mfma_f32_16x16x32_bf16 v[100:103], v[194:197], v[210:213], v[100:103]
	v_mfma_f32_16x16x32_bf16 v[88:91], v[186:189], v[218:221], v[88:91]
	v_mfma_f32_16x16x32_bf16 v[84:87], v[194:197], v[218:221], v[84:87]
	v_mfma_f32_16x16x32_bf16 v[72:75], v[186:189], v[226:229], v[72:75]
	v_mfma_f32_16x16x32_bf16 v[68:71], v[194:197], v[226:229], v[68:71]
	s_barrier
	s_setprio 0
	s_add_i32 s6, s64, s29
	s_mov_b32 m0, s6
	ds_read_b128 v[198:201], v176 offset:49152
	ds_read_b128 v[202:205], v176 offset:50176
	ds_read_b128 v[206:209], v176 offset:51200
	ds_read_b128 v[210:213], v176 offset:52224
	ds_read_b128 v[214:217], v176 offset:53248
	ds_read_b128 v[218:221], v176 offset:54272
	ds_read_b128 v[222:225], v176 offset:55296
	ds_read_b128 v[226:229], v176 offset:56320
	global_load_lds_dwordx4 v142, s[98:99]
	s_add_i32 m0, s6, 0x2000
	s_add_u32 s4, s4, 0x80080
	s_addc_u32 s5, s5, 0
	s_add_i32 s6, s65, s29
	global_load_lds_dwordx4 v138, s[98:99]
	s_mov_b32 m0, s6
	s_nop 0
	global_load_lds_dwordx4 v142, s[4:5]
	s_add_i32 m0, s6, 0x2000
	s_nop 0
	global_load_lds_dwordx4 v138, s[4:5]
	s_mov_b32 m0, s48
	s_nop 0
	global_load_lds_dwordx4 v144, s[100:101]
	s_mov_b32 m0, s49
	s_nop 0
	global_load_lds_dwordx4 v140, s[100:101]
	s_waitcnt vmcnt(8)
	s_waitcnt lgkmcnt(0)
	s_setprio 1
	s_barrier
	v_mfma_f32_16x16x32_bf16 v[62:65], v[132:135], v[198:201], v[62:65]
	v_mfma_f32_16x16x32_bf16 v[58:61], v[166:169], v[198:201], v[58:61]
	v_mfma_f32_16x16x32_bf16 v[46:49], v[132:135], v[206:209], v[46:49]
	v_mfma_f32_16x16x32_bf16 v[42:45], v[166:169], v[206:209], v[42:45]
	v_mfma_f32_16x16x32_bf16 v[30:33], v[132:135], v[214:217], v[30:33]
	v_mfma_f32_16x16x32_bf16 v[26:29], v[166:169], v[214:217], v[26:29]
	v_mfma_f32_16x16x32_bf16 v[14:17], v[132:135], v[222:225], v[14:17]
	v_mfma_f32_16x16x32_bf16 v[10:13], v[166:169], v[222:225], v[10:13]
	v_mfma_f32_16x16x32_bf16 v[62:65], v[158:161], v[202:205], v[62:65]
	v_mfma_f32_16x16x32_bf16 v[58:61], v[170:173], v[202:205], v[58:61]
	v_mfma_f32_16x16x32_bf16 v[46:49], v[158:161], v[210:213], v[46:49]
	v_mfma_f32_16x16x32_bf16 v[42:45], v[170:173], v[210:213], v[42:45]
	v_mfma_f32_16x16x32_bf16 v[30:33], v[158:161], v[218:221], v[30:33]
	v_mfma_f32_16x16x32_bf16 v[26:29], v[170:173], v[218:221], v[26:29]
	v_mfma_f32_16x16x32_bf16 v[14:17], v[158:161], v[226:229], v[14:17]
	v_mfma_f32_16x16x32_bf16 v[10:13], v[170:173], v[226:229], v[10:13]
	s_setprio 0
	s_setprio 1
	v_mfma_f32_16x16x32_bf16 v[54:57], v[182:185], v[198:201], v[54:57]
	v_mfma_f32_16x16x32_bf16 v[50:53], v[190:193], v[198:201], v[50:53]
	v_mfma_f32_16x16x32_bf16 v[38:41], v[182:185], v[206:209], v[38:41]
	v_mfma_f32_16x16x32_bf16 v[34:37], v[190:193], v[206:209], v[34:37]
	v_mfma_f32_16x16x32_bf16 v[22:25], v[182:185], v[214:217], v[22:25]
	v_mfma_f32_16x16x32_bf16 v[18:21], v[190:193], v[214:217], v[18:21]
	v_mfma_f32_16x16x32_bf16 v[6:9], v[182:185], v[222:225], v[6:9]
	v_mfma_f32_16x16x32_bf16 v[2:5], v[190:193], v[222:225], v[2:5]
	v_mfma_f32_16x16x32_bf16 v[54:57], v[186:189], v[202:205], v[54:57]
	v_mfma_f32_16x16x32_bf16 v[50:53], v[194:197], v[202:205], v[50:53]
	v_mfma_f32_16x16x32_bf16 v[38:41], v[186:189], v[210:213], v[38:41]
	v_mfma_f32_16x16x32_bf16 v[34:37], v[194:197], v[210:213], v[34:37]
	v_mfma_f32_16x16x32_bf16 v[22:25], v[186:189], v[218:221], v[22:25]
	v_mfma_f32_16x16x32_bf16 v[18:21], v[194:197], v[218:221], v[18:21]
	v_mfma_f32_16x16x32_bf16 v[6:9], v[186:189], v[226:229], v[6:9]
	v_mfma_f32_16x16x32_bf16 v[2:5], v[194:197], v[226:229], v[2:5]
	s_barrier
	s_setprio 0
	s_add_i32 s63, s63, 2
	s_add_u32 s0, s0, 0x100
	s_addc_u32 s1, s1, 0
	s_add_u32 s61, s61, 0x100
	s_addc_u32 s62, s62, 0
	s_cmp_gt_u32 s63, 29
.LBB0_1479:
	ds_read_b128 v[132:135], v174
	ds_read_b128 v[158:161], v174 offset:1024
	ds_read_b128 v[166:169], v174 offset:2048
	ds_read_b128 v[170:173], v174 offset:3072
	ds_read_b128 v[182:185], v175
	ds_read_b128 v[186:189], v175 offset:1024
	ds_read_b128 v[190:193], v175 offset:2048
	ds_read_b128 v[194:197], v175 offset:3072
	s_add_u32 s4, s0, 0xfff80080
	s_addc_u32 s5, s1, -1
	s_cmp_eq_u32 s63, 28
	s_cselect_b32 s7, s9, s5
	s_cselect_b32 s6, s11, s4
	s_cselect_b32 s5, s37, s62
	s_cselect_b32 s4, s60, s61
	s_add_i32 m0, s44, 0xc000
	ds_read_b128 v[198:201], v176
	ds_read_b128 v[202:205], v176 offset:1024
	ds_read_b128 v[206:209], v176 offset:2048
	ds_read_b128 v[210:213], v176 offset:3072
	ds_read_b128 v[214:217], v176 offset:4096
	ds_read_b128 v[218:221], v176 offset:5120
	ds_read_b128 v[222:225], v176 offset:6144
	ds_read_b128 v[226:229], v176 offset:7168
	global_load_lds_dwordx4 v146, s[0:1]
	s_add_i32 m0, s44, 0xe000
	s_nop 0
	global_load_lds_dwordx4 v148, s[0:1]
	s_waitcnt vmcnt(8)
	s_waitcnt lgkmcnt(0)
	s_setprio 1
	s_barrier
	v_mfma_f32_16x16x32_bf16 v[128:131], v[132:135], v[198:201], v[128:131]
	v_mfma_f32_16x16x32_bf16 v[124:127], v[166:169], v[198:201], v[124:127]
	v_mfma_f32_16x16x32_bf16 v[112:115], v[132:135], v[206:209], v[112:115]
	v_mfma_f32_16x16x32_bf16 v[108:111], v[166:169], v[206:209], v[108:111]
	v_mfma_f32_16x16x32_bf16 v[96:99], v[132:135], v[214:217], v[96:99]
	v_mfma_f32_16x16x32_bf16 v[92:95], v[166:169], v[214:217], v[92:95]
	v_mfma_f32_16x16x32_bf16 v[80:83], v[132:135], v[222:225], v[80:83]
	v_mfma_f32_16x16x32_bf16 v[76:79], v[166:169], v[222:225], v[76:79]
	v_mfma_f32_16x16x32_bf16 v[128:131], v[158:161], v[202:205], v[128:131]
	v_mfma_f32_16x16x32_bf16 v[124:127], v[170:173], v[202:205], v[124:127]
	v_mfma_f32_16x16x32_bf16 v[112:115], v[158:161], v[210:213], v[112:115]
	v_mfma_f32_16x16x32_bf16 v[108:111], v[170:173], v[210:213], v[108:111]
	v_mfma_f32_16x16x32_bf16 v[96:99], v[158:161], v[218:221], v[96:99]
	v_mfma_f32_16x16x32_bf16 v[92:95], v[170:173], v[218:221], v[92:95]
	v_mfma_f32_16x16x32_bf16 v[80:83], v[158:161], v[226:229], v[80:83]
	v_mfma_f32_16x16x32_bf16 v[76:79], v[170:173], v[226:229], v[76:79]
	s_setprio 0
	s_setprio 1
	v_mfma_f32_16x16x32_bf16 v[120:123], v[182:185], v[198:201], v[120:123]
	v_mfma_f32_16x16x32_bf16 v[116:119], v[190:193], v[198:201], v[116:119]
	v_mfma_f32_16x16x32_bf16 v[104:107], v[182:185], v[206:209], v[104:107]
	v_mfma_f32_16x16x32_bf16 v[100:103], v[190:193], v[206:209], v[100:103]
	v_mfma_f32_16x16x32_bf16 v[88:91], v[182:185], v[214:217], v[88:91]
	v_mfma_f32_16x16x32_bf16 v[84:87], v[190:193], v[214:217], v[84:87]
	v_mfma_f32_16x16x32_bf16 v[72:75], v[182:185], v[222:225], v[72:75]
	v_mfma_f32_16x16x32_bf16 v[68:71], v[190:193], v[222:225], v[68:71]
	v_mfma_f32_16x16x32_bf16 v[120:123], v[186:189], v[202:205], v[120:123]
	v_mfma_f32_16x16x32_bf16 v[116:119], v[194:197], v[202:205], v[116:119]
	v_mfma_f32_16x16x32_bf16 v[104:107], v[186:189], v[210:213], v[104:107]
	v_mfma_f32_16x16x32_bf16 v[100:103], v[194:197], v[210:213], v[100:103]
	v_mfma_f32_16x16x32_bf16 v[88:91], v[186:189], v[218:221], v[88:91]
	v_mfma_f32_16x16x32_bf16 v[84:87], v[194:197], v[218:221], v[84:87]
	v_mfma_f32_16x16x32_bf16 v[72:75], v[186:189], v[226:229], v[72:75]
	v_mfma_f32_16x16x32_bf16 v[68:71], v[194:197], v[226:229], v[68:71]
	s_barrier
	s_setprio 0
	s_add_i32 s64, s54, s29
	s_add_u32 s98, s4, 0x80
	s_addc_u32 s99, s5, 0
	s_mov_b32 m0, s64
	ds_read_b128 v[198:201], v176 offset:16384
	ds_read_b128 v[202:205], v176 offset:17408
	ds_read_b128 v[206:209], v176 offset:18432
	ds_read_b128 v[210:213], v176 offset:19456
	ds_read_b128 v[214:217], v176 offset:20480
	ds_read_b128 v[218:221], v176 offset:21504
	ds_read_b128 v[222:225], v176 offset:22528
	ds_read_b128 v[226:229], v176 offset:23552
	global_load_lds_dwordx4 v142, s[4:5]
	s_add_i32 m0, s64, 0x2000
	s_add_u32 s64, s4, 0x80000
	s_addc_u32 s65, s5, 0
	s_add_i32 s66, s55, s29
	global_load_lds_dwordx4 v138, s[4:5]
	s_mov_b32 m0, s66
	s_nop 0
	global_load_lds_dwordx4 v142, s[64:65]
	s_add_i32 m0, s66, 0x2000
	s_nop 0
	global_load_lds_dwordx4 v138, s[64:65]
	s_add_u32 s100, s6, 0x80
	s_addc_u32 s101, s7, 0
	s_mov_b32 m0, s44
	s_nop 0
	global_load_lds_dwordx4 v144, s[6:7]
	s_mov_b32 m0, s45
	s_nop 0
	global_load_lds_dwordx4 v140, s[6:7]
	s_waitcnt vmcnt(8)
	s_waitcnt lgkmcnt(0)
	s_setprio 1
	s_barrier
	v_mfma_f32_16x16x32_bf16 v[62:65], v[132:135], v[198:201], v[62:65]
	v_mfma_f32_16x16x32_bf16 v[58:61], v[166:169], v[198:201], v[58:61]
	v_mfma_f32_16x16x32_bf16 v[46:49], v[132:135], v[206:209], v[46:49]
	v_mfma_f32_16x16x32_bf16 v[42:45], v[166:169], v[206:209], v[42:45]
	v_mfma_f32_16x16x32_bf16 v[30:33], v[132:135], v[214:217], v[30:33]
	v_mfma_f32_16x16x32_bf16 v[26:29], v[166:169], v[214:217], v[26:29]
	v_mfma_f32_16x16x32_bf16 v[14:17], v[132:135], v[222:225], v[14:17]
	v_mfma_f32_16x16x32_bf16 v[10:13], v[166:169], v[222:225], v[10:13]
	v_mfma_f32_16x16x32_bf16 v[62:65], v[158:161], v[202:205], v[62:65]
	v_mfma_f32_16x16x32_bf16 v[58:61], v[170:173], v[202:205], v[58:61]
	v_mfma_f32_16x16x32_bf16 v[46:49], v[158:161], v[210:213], v[46:49]
	v_mfma_f32_16x16x32_bf16 v[42:45], v[170:173], v[210:213], v[42:45]
	v_mfma_f32_16x16x32_bf16 v[30:33], v[158:161], v[218:221], v[30:33]
	v_mfma_f32_16x16x32_bf16 v[26:29], v[170:173], v[218:221], v[26:29]
	v_mfma_f32_16x16x32_bf16 v[14:17], v[158:161], v[226:229], v[14:17]
	v_mfma_f32_16x16x32_bf16 v[10:13], v[170:173], v[226:229], v[10:13]
	s_setprio 0
	s_setprio 1
	v_mfma_f32_16x16x32_bf16 v[54:57], v[182:185], v[198:201], v[54:57]
	v_mfma_f32_16x16x32_bf16 v[50:53], v[190:193], v[198:201], v[50:53]
	v_mfma_f32_16x16x32_bf16 v[38:41], v[182:185], v[206:209], v[38:41]
	v_mfma_f32_16x16x32_bf16 v[34:37], v[190:193], v[206:209], v[34:37]
	v_mfma_f32_16x16x32_bf16 v[22:25], v[182:185], v[214:217], v[22:25]
	v_mfma_f32_16x16x32_bf16 v[18:21], v[190:193], v[214:217], v[18:21]
	v_mfma_f32_16x16x32_bf16 v[6:9], v[182:185], v[222:225], v[6:9]
	v_mfma_f32_16x16x32_bf16 v[2:5], v[190:193], v[222:225], v[2:5]
	v_mfma_f32_16x16x32_bf16 v[54:57], v[186:189], v[202:205], v[54:57]
	v_mfma_f32_16x16x32_bf16 v[50:53], v[194:197], v[202:205], v[50:53]
	v_mfma_f32_16x16x32_bf16 v[38:41], v[186:189], v[210:213], v[38:41]
	v_mfma_f32_16x16x32_bf16 v[34:37], v[194:197], v[210:213], v[34:37]
	v_mfma_f32_16x16x32_bf16 v[22:25], v[186:189], v[218:221], v[22:25]
	v_mfma_f32_16x16x32_bf16 v[18:21], v[194:197], v[218:221], v[18:21]
	v_mfma_f32_16x16x32_bf16 v[6:9], v[186:189], v[226:229], v[6:9]
	v_mfma_f32_16x16x32_bf16 v[2:5], v[194:197], v[226:229], v[2:5]
	s_barrier
	s_setprio 0
	s_add_i32 s64, 0, 0x18000
	s_add_i32 s65, 0, 0x1c000
	ds_read_b128 v[132:135], v174 offset:32768
	ds_read_b128 v[158:161], v174 offset:33792
	ds_read_b128 v[166:169], v174 offset:34816
	ds_read_b128 v[170:173], v174 offset:35840
	ds_read_b128 v[182:185], v175 offset:32768
	ds_read_b128 v[186:189], v175 offset:33792
	ds_read_b128 v[190:193], v175 offset:34816
	ds_read_b128 v[194:197], v175 offset:35840
	s_add_u32 s6, s6, 0x80000
	s_addc_u32 s7, s7, 0
	s_mov_b32 m0, s46
	ds_read_b128 v[198:201], v176 offset:32768
	ds_read_b128 v[202:205], v176 offset:33792
	ds_read_b128 v[206:209], v176 offset:34816
	ds_read_b128 v[210:213], v176 offset:35840
	ds_read_b128 v[214:217], v176 offset:36864
	ds_read_b128 v[218:221], v176 offset:37888
	ds_read_b128 v[222:225], v176 offset:38912
	ds_read_b128 v[226:229], v176 offset:39936
	global_load_lds_dwordx4 v144, s[6:7]
	s_mov_b32 m0, s47
	s_nop 0
	global_load_lds_dwordx4 v140, s[6:7]
	s_waitcnt vmcnt(8)
	s_waitcnt lgkmcnt(0)
	s_setprio 1
	s_barrier
	v_mfma_f32_16x16x32_bf16 v[128:131], v[132:135], v[198:201], v[128:131]
	v_mfma_f32_16x16x32_bf16 v[124:127], v[166:169], v[198:201], v[124:127]
	v_mfma_f32_16x16x32_bf16 v[112:115], v[132:135], v[206:209], v[112:115]
	v_mfma_f32_16x16x32_bf16 v[108:111], v[166:169], v[206:209], v[108:111]
	v_mfma_f32_16x16x32_bf16 v[96:99], v[132:135], v[214:217], v[96:99]
	v_mfma_f32_16x16x32_bf16 v[92:95], v[166:169], v[214:217], v[92:95]
	v_mfma_f32_16x16x32_bf16 v[80:83], v[132:135], v[222:225], v[80:83]
	v_mfma_f32_16x16x32_bf16 v[76:79], v[166:169], v[222:225], v[76:79]
	v_mfma_f32_16x16x32_bf16 v[128:131], v[158:161], v[202:205], v[128:131]
	v_mfma_f32_16x16x32_bf16 v[124:127], v[170:173], v[202:205], v[124:127]
	v_mfma_f32_16x16x32_bf16 v[112:115], v[158:161], v[210:213], v[112:115]
	v_mfma_f32_16x16x32_bf16 v[108:111], v[170:173], v[210:213], v[108:111]
	v_mfma_f32_16x16x32_bf16 v[96:99], v[158:161], v[218:221], v[96:99]
	v_mfma_f32_16x16x32_bf16 v[92:95], v[170:173], v[218:221], v[92:95]
	v_mfma_f32_16x16x32_bf16 v[80:83], v[158:161], v[226:229], v[80:83]
	v_mfma_f32_16x16x32_bf16 v[76:79], v[170:173], v[226:229], v[76:79]
	s_setprio 0
	s_setprio 1
	v_mfma_f32_16x16x32_bf16 v[120:123], v[182:185], v[198:201], v[120:123]
	v_mfma_f32_16x16x32_bf16 v[116:119], v[190:193], v[198:201], v[116:119]
	v_mfma_f32_16x16x32_bf16 v[104:107], v[182:185], v[206:209], v[104:107]
	v_mfma_f32_16x16x32_bf16 v[100:103], v[190:193], v[206:209], v[100:103]
	v_mfma_f32_16x16x32_bf16 v[88:91], v[182:185], v[214:217], v[88:91]
	v_mfma_f32_16x16x32_bf16 v[84:87], v[190:193], v[214:217], v[84:87]
	v_mfma_f32_16x16x32_bf16 v[72:75], v[182:185], v[222:225], v[72:75]
	v_mfma_f32_16x16x32_bf16 v[68:71], v[190:193], v[222:225], v[68:71]
	v_mfma_f32_16x16x32_bf16 v[120:123], v[186:189], v[202:205], v[120:123]
	v_mfma_f32_16x16x32_bf16 v[116:119], v[194:197], v[202:205], v[116:119]
	v_mfma_f32_16x16x32_bf16 v[104:107], v[186:189], v[210:213], v[104:107]
	v_mfma_f32_16x16x32_bf16 v[100:103], v[194:197], v[210:213], v[100:103]
	v_mfma_f32_16x16x32_bf16 v[88:91], v[186:189], v[218:221], v[88:91]
	v_mfma_f32_16x16x32_bf16 v[84:87], v[194:197], v[218:221], v[84:87]
	v_mfma_f32_16x16x32_bf16 v[72:75], v[186:189], v[226:229], v[72:75]
	v_mfma_f32_16x16x32_bf16 v[68:71], v[194:197], v[226:229], v[68:71]
	s_barrier
	s_setprio 0
	s_add_i32 s6, s64, s29
	s_mov_b32 m0, s6
	ds_read_b128 v[198:201], v176 offset:49152
	ds_read_b128 v[202:205], v176 offset:50176
	ds_read_b128 v[206:209], v176 offset:51200
	ds_read_b128 v[210:213], v176 offset:52224
	ds_read_b128 v[214:217], v176 offset:53248
	ds_read_b128 v[218:221], v176 offset:54272
	ds_read_b128 v[222:225], v176 offset:55296
	ds_read_b128 v[226:229], v176 offset:56320
	global_load_lds_dwordx4 v142, s[98:99]
	s_add_i32 m0, s6, 0x2000
	s_add_u32 s4, s4, 0x80080
	s_addc_u32 s5, s5, 0
	s_add_i32 s6, s65, s29
	global_load_lds_dwordx4 v138, s[98:99]
	s_mov_b32 m0, s6
	s_nop 0
	global_load_lds_dwordx4 v142, s[4:5]
	s_add_i32 m0, s6, 0x2000
	s_nop 0
	global_load_lds_dwordx4 v138, s[4:5]
	s_mov_b32 m0, s48
	s_nop 0
	global_load_lds_dwordx4 v144, s[100:101]
	s_mov_b32 m0, s49
	s_nop 0
	global_load_lds_dwordx4 v140, s[100:101]
	s_add_i32 s63, s63, 2
	s_add_u32 s0, s0, 0x100
	s_addc_u32 s1, s1, 0
	s_add_u32 s61, s61, 0x100
	s_addc_u32 s62, s62, 0
	s_cmp_gt_u32 s63, 29
	s_waitcnt vmcnt(8)
	s_waitcnt lgkmcnt(0)
	s_setprio 1
	s_barrier
	v_mfma_f32_16x16x32_bf16 v[62:65], v[132:135], v[198:201], v[62:65]
	v_mfma_f32_16x16x32_bf16 v[58:61], v[166:169], v[198:201], v[58:61]
	v_mfma_f32_16x16x32_bf16 v[46:49], v[132:135], v[206:209], v[46:49]
	v_mfma_f32_16x16x32_bf16 v[42:45], v[166:169], v[206:209], v[42:45]
	v_mfma_f32_16x16x32_bf16 v[30:33], v[132:135], v[214:217], v[30:33]
	v_mfma_f32_16x16x32_bf16 v[26:29], v[166:169], v[214:217], v[26:29]
	v_mfma_f32_16x16x32_bf16 v[14:17], v[132:135], v[222:225], v[14:17]
	v_mfma_f32_16x16x32_bf16 v[10:13], v[166:169], v[222:225], v[10:13]
	v_mfma_f32_16x16x32_bf16 v[62:65], v[158:161], v[202:205], v[62:65]
	v_mfma_f32_16x16x32_bf16 v[58:61], v[170:173], v[202:205], v[58:61]
	v_mfma_f32_16x16x32_bf16 v[46:49], v[158:161], v[210:213], v[46:49]
	v_mfma_f32_16x16x32_bf16 v[42:45], v[170:173], v[210:213], v[42:45]
	v_mfma_f32_16x16x32_bf16 v[30:33], v[158:161], v[218:221], v[30:33]
	v_mfma_f32_16x16x32_bf16 v[26:29], v[170:173], v[218:221], v[26:29]
	v_mfma_f32_16x16x32_bf16 v[14:17], v[158:161], v[226:229], v[14:17]
	v_mfma_f32_16x16x32_bf16 v[10:13], v[170:173], v[226:229], v[10:13]
	s_setprio 0
	s_setprio 1
	v_mfma_f32_16x16x32_bf16 v[54:57], v[182:185], v[198:201], v[54:57]
	v_mfma_f32_16x16x32_bf16 v[50:53], v[190:193], v[198:201], v[50:53]
	v_mfma_f32_16x16x32_bf16 v[38:41], v[182:185], v[206:209], v[38:41]
	v_mfma_f32_16x16x32_bf16 v[34:37], v[190:193], v[206:209], v[34:37]
	v_mfma_f32_16x16x32_bf16 v[22:25], v[182:185], v[214:217], v[22:25]
	v_mfma_f32_16x16x32_bf16 v[18:21], v[190:193], v[214:217], v[18:21]
	v_mfma_f32_16x16x32_bf16 v[6:9], v[182:185], v[222:225], v[6:9]
	v_mfma_f32_16x16x32_bf16 v[2:5], v[190:193], v[222:225], v[2:5]
	v_mfma_f32_16x16x32_bf16 v[54:57], v[186:189], v[202:205], v[54:57]
	v_mfma_f32_16x16x32_bf16 v[50:53], v[194:197], v[202:205], v[50:53]
	v_mfma_f32_16x16x32_bf16 v[38:41], v[186:189], v[210:213], v[38:41]
	v_mfma_f32_16x16x32_bf16 v[34:37], v[194:197], v[210:213], v[34:37]
	v_mfma_f32_16x16x32_bf16 v[22:25], v[186:189], v[218:221], v[22:25]
	v_mfma_f32_16x16x32_bf16 v[18:21], v[194:197], v[218:221], v[18:21]
	v_mfma_f32_16x16x32_bf16 v[6:9], v[186:189], v[226:229], v[6:9]
	v_mfma_f32_16x16x32_bf16 v[2:5], v[194:197], v[226:229], v[2:5]
	s_barrier
	s_setprio 0
	s_cbranch_scc0 .LBB0_1479
	s_and_b64 vcc, exec, s[34:35]
	s_cbranch_vccz .LBB0_1482
	s_barrier

.LBB0_1565:
	s_add_u32 s16, s16, 0x160080
	s_addc_u32 s17, s17, 0
	s_add_u32 s46, s20, 0x100
	s_addc_u32 s47, s21, 0
	s_mov_b32 s48, -2
	ds_read_b128 v[144:147], v151
	ds_read_b128 v[154:157], v151 offset:1024
	ds_read_b128 v[158:161], v151 offset:2048
	ds_read_b128 v[162:165], v151 offset:3072
	ds_read_b128 v[166:169], v152
	ds_read_b128 v[170:173], v152 offset:1024
	ds_read_b128 v[174:177], v152 offset:2048
	ds_read_b128 v[178:181], v152 offset:3072
	s_add_u32 s20, s16, 0xffea0080
	s_addc_u32 s21, s17, -1
	s_cmpk_eq_i32 s48, 0x54
	s_cselect_b32 s27, s5, s21
	s_cselect_b32 s26, s4, s20
	s_cselect_b32 s21, s15, s47
	s_cselect_b32 s20, s14, s46
	s_add_i32 m0, s30, 0xc000
	ds_read_b128 v[182:185], v153
	ds_read_b128 v[186:189], v153 offset:1024
	ds_read_b128 v[190:193], v153 offset:2048
	ds_read_b128 v[194:197], v153 offset:3072
	ds_read_b128 v[198:201], v153 offset:4096
	ds_read_b128 v[202:205], v153 offset:5120
	ds_read_b128 v[206:209], v153 offset:6144
	ds_read_b128 v[210:213], v153 offset:7168
	global_load_lds_dwordx4 v136, s[16:17]
	s_add_i32 m0, s30, 0xe000
	s_nop 0
	global_load_lds_dwordx4 v138, s[16:17]
	s_waitcnt vmcnt(8)
	s_waitcnt lgkmcnt(0)
	s_setprio 1
	s_barrier
	v_mfma_f32_16x16x32_bf16 v[124:127], v[144:147], v[182:185], 0
	v_mfma_f32_16x16x32_bf16 v[120:123], v[158:161], v[182:185], 0
	v_mfma_f32_16x16x32_bf16 v[108:111], v[144:147], v[190:193], 0
	v_mfma_f32_16x16x32_bf16 v[104:107], v[158:161], v[190:193], 0
	v_mfma_f32_16x16x32_bf16 v[88:91], v[144:147], v[198:201], 0
	v_mfma_f32_16x16x32_bf16 v[92:95], v[158:161], v[198:201], 0
	v_mfma_f32_16x16x32_bf16 v[72:75], v[144:147], v[206:209], 0
	v_mfma_f32_16x16x32_bf16 v[76:79], v[158:161], v[206:209], 0
	v_mfma_f32_16x16x32_bf16 v[124:127], v[154:157], v[186:189], v[124:127]
	v_mfma_f32_16x16x32_bf16 v[120:123], v[162:165], v[186:189], v[120:123]
	v_mfma_f32_16x16x32_bf16 v[108:111], v[154:157], v[194:197], v[108:111]
	v_mfma_f32_16x16x32_bf16 v[104:107], v[162:165], v[194:197], v[104:107]
	v_mfma_f32_16x16x32_bf16 v[88:91], v[154:157], v[202:205], v[88:91]
	v_mfma_f32_16x16x32_bf16 v[92:95], v[162:165], v[202:205], v[92:95]
	v_mfma_f32_16x16x32_bf16 v[72:75], v[154:157], v[210:213], v[72:75]
	v_mfma_f32_16x16x32_bf16 v[76:79], v[162:165], v[210:213], v[76:79]
	s_setprio 0
	s_setprio 1
	v_mfma_f32_16x16x32_bf16 v[116:119], v[166:169], v[182:185], 0
	v_mfma_f32_16x16x32_bf16 v[112:115], v[174:177], v[182:185], 0
	v_mfma_f32_16x16x32_bf16 v[96:99], v[166:169], v[190:193], 0
	v_mfma_f32_16x16x32_bf16 v[100:103], v[174:177], v[190:193], 0
	v_mfma_f32_16x16x32_bf16 v[80:83], v[166:169], v[198:201], 0
	v_mfma_f32_16x16x32_bf16 v[84:87], v[174:177], v[198:201], 0
	v_mfma_f32_16x16x32_bf16 v[64:67], v[166:169], v[206:209], 0
	v_mfma_f32_16x16x32_bf16 v[68:71], v[174:177], v[206:209], 0
	v_mfma_f32_16x16x32_bf16 v[116:119], v[170:173], v[186:189], v[116:119]
	v_mfma_f32_16x16x32_bf16 v[112:115], v[178:181], v[186:189], v[112:115]
	v_mfma_f32_16x16x32_bf16 v[96:99], v[170:173], v[194:197], v[96:99]
	v_mfma_f32_16x16x32_bf16 v[100:103], v[178:181], v[194:197], v[100:103]
	v_mfma_f32_16x16x32_bf16 v[80:83], v[170:173], v[202:205], v[80:83]
	v_mfma_f32_16x16x32_bf16 v[84:87], v[178:181], v[202:205], v[84:87]
	v_mfma_f32_16x16x32_bf16 v[64:67], v[170:173], v[210:213], v[64:67]
	v_mfma_f32_16x16x32_bf16 v[68:71], v[178:181], v[210:213], v[68:71]
	s_barrier
	s_setprio 0
	s_add_i32 s49, s40, s29
	s_add_u32 s98, s20, 0x80
	s_addc_u32 s99, s21, 0
	s_mov_b32 m0, s49
	ds_read_b128 v[182:185], v153 offset:16384
	ds_read_b128 v[186:189], v153 offset:17408
	ds_read_b128 v[190:193], v153 offset:18432
	ds_read_b128 v[194:197], v153 offset:19456
	ds_read_b128 v[198:201], v153 offset:20480
	ds_read_b128 v[202:205], v153 offset:21504
	ds_read_b128 v[206:209], v153 offset:22528
	ds_read_b128 v[210:213], v153 offset:23552
	global_load_lds_dwordx4 v130, s[20:21]
	s_add_i32 m0, s49, 0x2000
	s_add_u32 s52, s20, 0x160000
	s_addc_u32 s53, s21, 0
	s_add_i32 s49, s41, s29
	global_load_lds_dwordx4 v134, s[20:21]
	s_mov_b32 m0, s49
	s_nop 0
	global_load_lds_dwordx4 v130, s[52:53]
	s_add_i32 m0, s49, 0x2000
	s_nop 0
	global_load_lds_dwordx4 v134, s[52:53]
	s_add_u32 s100, s26, 0x80
	s_addc_u32 s101, s27, 0
	s_mov_b32 m0, s30
	s_nop 0
	global_load_lds_dwordx4 v128, s[26:27]
	s_mov_b32 m0, s31
	s_nop 0
	global_load_lds_dwordx4 v132, s[26:27]
	s_waitcnt vmcnt(8)
	s_waitcnt lgkmcnt(0)
	s_setprio 1
	s_barrier
	v_mfma_f32_16x16x32_bf16 v[56:59], v[144:147], v[182:185], 0
	v_mfma_f32_16x16x32_bf16 v[60:63], v[158:161], v[182:185], 0
	v_mfma_f32_16x16x32_bf16 v[40:43], v[144:147], v[190:193], 0
	v_mfma_f32_16x16x32_bf16 v[44:47], v[158:161], v[190:193], 0
	v_mfma_f32_16x16x32_bf16 v[24:27], v[144:147], v[198:201], 0
	v_mfma_f32_16x16x32_bf16 v[28:31], v[158:161], v[198:201], 0
	v_mfma_f32_16x16x32_bf16 v[8:11], v[144:147], v[206:209], 0
	v_mfma_f32_16x16x32_bf16 v[12:15], v[158:161], v[206:209], 0
	v_mfma_f32_16x16x32_bf16 v[56:59], v[154:157], v[186:189], v[56:59]
	v_mfma_f32_16x16x32_bf16 v[60:63], v[162:165], v[186:189], v[60:63]
	v_mfma_f32_16x16x32_bf16 v[40:43], v[154:157], v[194:197], v[40:43]
	v_mfma_f32_16x16x32_bf16 v[44:47], v[162:165], v[194:197], v[44:47]
	v_mfma_f32_16x16x32_bf16 v[24:27], v[154:157], v[202:205], v[24:27]
	v_mfma_f32_16x16x32_bf16 v[28:31], v[162:165], v[202:205], v[28:31]
	v_mfma_f32_16x16x32_bf16 v[8:11], v[154:157], v[210:213], v[8:11]
	v_mfma_f32_16x16x32_bf16 v[12:15], v[162:165], v[210:213], v[12:15]
	s_setprio 0
	s_setprio 1
	v_mfma_f32_16x16x32_bf16 v[48:51], v[166:169], v[182:185], 0
	v_mfma_f32_16x16x32_bf16 v[52:55], v[174:177], v[182:185], 0
	v_mfma_f32_16x16x32_bf16 v[32:35], v[166:169], v[190:193], 0
	v_mfma_f32_16x16x32_bf16 v[36:39], v[174:177], v[190:193], 0
	v_mfma_f32_16x16x32_bf16 v[16:19], v[166:169], v[198:201], 0
	v_mfma_f32_16x16x32_bf16 v[20:23], v[174:177], v[198:201], 0
	v_mfma_f32_16x16x32_bf16 v[0:3], v[166:169], v[206:209], 0
	v_mfma_f32_16x16x32_bf16 v[4:7], v[174:177], v[206:209], 0
	v_mfma_f32_16x16x32_bf16 v[48:51], v[170:173], v[186:189], v[48:51]
	v_mfma_f32_16x16x32_bf16 v[52:55], v[178:181], v[186:189], v[52:55]
	v_mfma_f32_16x16x32_bf16 v[32:35], v[170:173], v[194:197], v[32:35]
	v_mfma_f32_16x16x32_bf16 v[36:39], v[178:181], v[194:197], v[36:39]
	v_mfma_f32_16x16x32_bf16 v[16:19], v[170:173], v[202:205], v[16:19]
	v_mfma_f32_16x16x32_bf16 v[20:23], v[178:181], v[202:205], v[20:23]
	v_mfma_f32_16x16x32_bf16 v[0:3], v[170:173], v[210:213], v[0:3]
	v_mfma_f32_16x16x32_bf16 v[4:7], v[178:181], v[210:213], v[4:7]
	s_barrier
	s_setprio 0
	s_add_i32 s49, 0, 0x18000
	s_add_i32 s52, 0, 0x1c000
	ds_read_b128 v[144:147], v151 offset:32768
	ds_read_b128 v[154:157], v151 offset:33792
	ds_read_b128 v[158:161], v151 offset:34816
	ds_read_b128 v[162:165], v151 offset:35840
	ds_read_b128 v[166:169], v152 offset:32768
	ds_read_b128 v[170:173], v152 offset:33792
	ds_read_b128 v[174:177], v152 offset:34816
	ds_read_b128 v[178:181], v152 offset:35840
	s_add_u32 s26, s26, 0x160000
	s_addc_u32 s27, s27, 0
	s_mov_b32 m0, s34
	ds_read_b128 v[182:185], v153 offset:32768
	ds_read_b128 v[186:189], v153 offset:33792
	ds_read_b128 v[190:193], v153 offset:34816
	ds_read_b128 v[194:197], v153 offset:35840
	ds_read_b128 v[198:201], v153 offset:36864
	ds_read_b128 v[202:205], v153 offset:37888
	ds_read_b128 v[206:209], v153 offset:38912
	ds_read_b128 v[210:213], v153 offset:39936
	global_load_lds_dwordx4 v128, s[26:27]
	s_mov_b32 m0, s35
	s_nop 0
	global_load_lds_dwordx4 v132, s[26:27]
	s_waitcnt vmcnt(8)
	s_waitcnt lgkmcnt(0)
	s_setprio 1
	s_barrier
	v_mfma_f32_16x16x32_bf16 v[124:127], v[144:147], v[182:185], v[124:127]
	v_mfma_f32_16x16x32_bf16 v[120:123], v[158:161], v[182:185], v[120:123]
	v_mfma_f32_16x16x32_bf16 v[108:111], v[144:147], v[190:193], v[108:111]
	v_mfma_f32_16x16x32_bf16 v[104:107], v[158:161], v[190:193], v[104:107]
	v_mfma_f32_16x16x32_bf16 v[88:91], v[144:147], v[198:201], v[88:91]
	v_mfma_f32_16x16x32_bf16 v[92:95], v[158:161], v[198:201], v[92:95]
	v_mfma_f32_16x16x32_bf16 v[72:75], v[144:147], v[206:209], v[72:75]
	v_mfma_f32_16x16x32_bf16 v[76:79], v[158:161], v[206:209], v[76:79]
	v_mfma_f32_16x16x32_bf16 v[124:127], v[154:157], v[186:189], v[124:127]
	v_mfma_f32_16x16x32_bf16 v[120:123], v[162:165], v[186:189], v[120:123]
	v_mfma_f32_16x16x32_bf16 v[108:111], v[154:157], v[194:197], v[108:111]
	v_mfma_f32_16x16x32_bf16 v[104:107], v[162:165], v[194:197], v[104:107]
	v_mfma_f32_16x16x32_bf16 v[88:91], v[154:157], v[202:205], v[88:91]
	v_mfma_f32_16x16x32_bf16 v[92:95], v[162:165], v[202:205], v[92:95]
	v_mfma_f32_16x16x32_bf16 v[72:75], v[154:157], v[210:213], v[72:75]
	v_mfma_f32_16x16x32_bf16 v[76:79], v[162:165], v[210:213], v[76:79]
	s_setprio 0
	s_setprio 1
	v_mfma_f32_16x16x32_bf16 v[116:119], v[166:169], v[182:185], v[116:119]
	v_mfma_f32_16x16x32_bf16 v[112:115], v[174:177], v[182:185], v[112:115]
	v_mfma_f32_16x16x32_bf16 v[96:99], v[166:169], v[190:193], v[96:99]
	v_mfma_f32_16x16x32_bf16 v[100:103], v[174:177], v[190:193], v[100:103]
	v_mfma_f32_16x16x32_bf16 v[80:83], v[166:169], v[198:201], v[80:83]
	v_mfma_f32_16x16x32_bf16 v[84:87], v[174:177], v[198:201], v[84:87]
	v_mfma_f32_16x16x32_bf16 v[64:67], v[166:169], v[206:209], v[64:67]
	v_mfma_f32_16x16x32_bf16 v[68:71], v[174:177], v[206:209], v[68:71]
	v_mfma_f32_16x16x32_bf16 v[116:119], v[170:173], v[186:189], v[116:119]
	v_mfma_f32_16x16x32_bf16 v[112:115], v[178:181], v[186:189], v[112:115]
	v_mfma_f32_16x16x32_bf16 v[96:99], v[170:173], v[194:197], v[96:99]
	v_mfma_f32_16x16x32_bf16 v[100:103], v[178:181], v[194:197], v[100:103]
	v_mfma_f32_16x16x32_bf16 v[80:83], v[170:173], v[202:205], v[80:83]
	v_mfma_f32_16x16x32_bf16 v[84:87], v[178:181], v[202:205], v[84:87]
	v_mfma_f32_16x16x32_bf16 v[64:67], v[170:173], v[210:213], v[64:67]
	v_mfma_f32_16x16x32_bf16 v[68:71], v[178:181], v[210:213], v[68:71]
	s_barrier
	s_setprio 0
	s_add_i32 s26, s49, s29
	s_mov_b32 m0, s26
	ds_read_b128 v[182:185], v153 offset:49152
	ds_read_b128 v[186:189], v153 offset:50176
	ds_read_b128 v[190:193], v153 offset:51200
	ds_read_b128 v[194:197], v153 offset:52224
	ds_read_b128 v[198:201], v153 offset:53248
	ds_read_b128 v[202:205], v153 offset:54272
	ds_read_b128 v[206:209], v153 offset:55296
	ds_read_b128 v[210:213], v153 offset:56320
	global_load_lds_dwordx4 v130, s[98:99]
	s_add_i32 m0, s26, 0x2000
	s_add_u32 s20, s20, 0x160080
	s_addc_u32 s21, s21, 0
	s_add_i32 s26, s52, s29
	global_load_lds_dwordx4 v134, s[98:99]
	s_mov_b32 m0, s26
	s_nop 0
	global_load_lds_dwordx4 v130, s[20:21]
	s_add_i32 m0, s26, 0x2000
	s_nop 0
	global_load_lds_dwordx4 v134, s[20:21]
	s_mov_b32 m0, s37
	s_nop 0
	global_load_lds_dwordx4 v128, s[100:101]
	s_mov_b32 m0, s38
	s_nop 0
	global_load_lds_dwordx4 v132, s[100:101]
	s_waitcnt vmcnt(8)
	s_waitcnt lgkmcnt(0)
	s_setprio 1
	s_barrier
	v_mfma_f32_16x16x32_bf16 v[56:59], v[144:147], v[182:185], v[56:59]
	v_mfma_f32_16x16x32_bf16 v[60:63], v[158:161], v[182:185], v[60:63]
	v_mfma_f32_16x16x32_bf16 v[40:43], v[144:147], v[190:193], v[40:43]
	v_mfma_f32_16x16x32_bf16 v[44:47], v[158:161], v[190:193], v[44:47]
	v_mfma_f32_16x16x32_bf16 v[24:27], v[144:147], v[198:201], v[24:27]
	v_mfma_f32_16x16x32_bf16 v[28:31], v[158:161], v[198:201], v[28:31]
	v_mfma_f32_16x16x32_bf16 v[8:11], v[144:147], v[206:209], v[8:11]
	v_mfma_f32_16x16x32_bf16 v[12:15], v[158:161], v[206:209], v[12:15]
	v_mfma_f32_16x16x32_bf16 v[56:59], v[154:157], v[186:189], v[56:59]
	v_mfma_f32_16x16x32_bf16 v[60:63], v[162:165], v[186:189], v[60:63]
	v_mfma_f32_16x16x32_bf16 v[40:43], v[154:157], v[194:197], v[40:43]
	v_mfma_f32_16x16x32_bf16 v[44:47], v[162:165], v[194:197], v[44:47]
	v_mfma_f32_16x16x32_bf16 v[24:27], v[154:157], v[202:205], v[24:27]
	v_mfma_f32_16x16x32_bf16 v[28:31], v[162:165], v[202:205], v[28:31]
	v_mfma_f32_16x16x32_bf16 v[8:11], v[154:157], v[210:213], v[8:11]
	v_mfma_f32_16x16x32_bf16 v[12:15], v[162:165], v[210:213], v[12:15]
	s_setprio 0
	s_setprio 1
	v_mfma_f32_16x16x32_bf16 v[48:51], v[166:169], v[182:185], v[48:51]
	v_mfma_f32_16x16x32_bf16 v[52:55], v[174:177], v[182:185], v[52:55]
	v_mfma_f32_16x16x32_bf16 v[32:35], v[166:169], v[190:193], v[32:35]
	v_mfma_f32_16x16x32_bf16 v[36:39], v[174:177], v[190:193], v[36:39]
	v_mfma_f32_16x16x32_bf16 v[16:19], v[166:169], v[198:201], v[16:19]
	v_mfma_f32_16x16x32_bf16 v[20:23], v[174:177], v[198:201], v[20:23]
	v_mfma_f32_16x16x32_bf16 v[0:3], v[166:169], v[206:209], v[0:3]
	v_mfma_f32_16x16x32_bf16 v[4:7], v[174:177], v[206:209], v[4:7]
	v_mfma_f32_16x16x32_bf16 v[48:51], v[170:173], v[186:189], v[48:51]
	v_mfma_f32_16x16x32_bf16 v[52:55], v[178:181], v[186:189], v[52:55]
	v_mfma_f32_16x16x32_bf16 v[32:35], v[170:173], v[194:197], v[32:35]
	v_mfma_f32_16x16x32_bf16 v[36:39], v[178:181], v[194:197], v[36:39]
	v_mfma_f32_16x16x32_bf16 v[16:19], v[170:173], v[202:205], v[16:19]
	v_mfma_f32_16x16x32_bf16 v[20:23], v[178:181], v[202:205], v[20:23]
	v_mfma_f32_16x16x32_bf16 v[0:3], v[170:173], v[210:213], v[0:3]
	v_mfma_f32_16x16x32_bf16 v[4:7], v[178:181], v[210:213], v[4:7]
	s_barrier
	s_setprio 0
	s_add_i32 s48, s48, 2
	s_add_u32 s16, s16, 0x100
	s_addc_u32 s17, s17, 0
	s_add_u32 s46, s46, 0x100
	s_addc_u32 s47, s47, 0
	s_cmpk_gt_u32 s48, 0x55
.LBB0_1566:
	ds_read_b128 v[144:147], v151
	ds_read_b128 v[154:157], v151 offset:1024
	ds_read_b128 v[158:161], v151 offset:2048
	ds_read_b128 v[162:165], v151 offset:3072
	ds_read_b128 v[166:169], v152
	ds_read_b128 v[170:173], v152 offset:1024
	ds_read_b128 v[174:177], v152 offset:2048
	ds_read_b128 v[178:181], v152 offset:3072
	s_add_u32 s20, s16, 0xffea0080
	s_addc_u32 s21, s17, -1
	s_cmpk_eq_i32 s48, 0x54
	s_cselect_b32 s27, s5, s21
	s_cselect_b32 s26, s4, s20
	s_cselect_b32 s21, s15, s47
	s_cselect_b32 s20, s14, s46
	s_add_i32 m0, s30, 0xc000
	ds_read_b128 v[182:185], v153
	ds_read_b128 v[186:189], v153 offset:1024
	ds_read_b128 v[190:193], v153 offset:2048
	ds_read_b128 v[194:197], v153 offset:3072
	ds_read_b128 v[198:201], v153 offset:4096
	ds_read_b128 v[202:205], v153 offset:5120
	ds_read_b128 v[206:209], v153 offset:6144
	ds_read_b128 v[210:213], v153 offset:7168
	global_load_lds_dwordx4 v136, s[16:17]
	s_add_i32 m0, s30, 0xe000
	s_nop 0
	global_load_lds_dwordx4 v138, s[16:17]
	s_waitcnt vmcnt(8)
	s_waitcnt lgkmcnt(0)
	s_setprio 1
	s_barrier
	v_mfma_f32_16x16x32_bf16 v[124:127], v[144:147], v[182:185], v[124:127]
	v_mfma_f32_16x16x32_bf16 v[120:123], v[158:161], v[182:185], v[120:123]
	v_mfma_f32_16x16x32_bf16 v[108:111], v[144:147], v[190:193], v[108:111]
	v_mfma_f32_16x16x32_bf16 v[104:107], v[158:161], v[190:193], v[104:107]
	v_mfma_f32_16x16x32_bf16 v[88:91], v[144:147], v[198:201], v[88:91]
	v_mfma_f32_16x16x32_bf16 v[92:95], v[158:161], v[198:201], v[92:95]
	v_mfma_f32_16x16x32_bf16 v[72:75], v[144:147], v[206:209], v[72:75]
	v_mfma_f32_16x16x32_bf16 v[76:79], v[158:161], v[206:209], v[76:79]
	v_mfma_f32_16x16x32_bf16 v[124:127], v[154:157], v[186:189], v[124:127]
	v_mfma_f32_16x16x32_bf16 v[120:123], v[162:165], v[186:189], v[120:123]
	v_mfma_f32_16x16x32_bf16 v[108:111], v[154:157], v[194:197], v[108:111]
	v_mfma_f32_16x16x32_bf16 v[104:107], v[162:165], v[194:197], v[104:107]
	v_mfma_f32_16x16x32_bf16 v[88:91], v[154:157], v[202:205], v[88:91]
	v_mfma_f32_16x16x32_bf16 v[92:95], v[162:165], v[202:205], v[92:95]
	v_mfma_f32_16x16x32_bf16 v[72:75], v[154:157], v[210:213], v[72:75]
	v_mfma_f32_16x16x32_bf16 v[76:79], v[162:165], v[210:213], v[76:79]
	s_setprio 0
	s_setprio 1
	v_mfma_f32_16x16x32_bf16 v[116:119], v[166:169], v[182:185], v[116:119]
	v_mfma_f32_16x16x32_bf16 v[112:115], v[174:177], v[182:185], v[112:115]
	v_mfma_f32_16x16x32_bf16 v[96:99], v[166:169], v[190:193], v[96:99]
	v_mfma_f32_16x16x32_bf16 v[100:103], v[174:177], v[190:193], v[100:103]
	v_mfma_f32_16x16x32_bf16 v[80:83], v[166:169], v[198:201], v[80:83]
	v_mfma_f32_16x16x32_bf16 v[84:87], v[174:177], v[198:201], v[84:87]
	v_mfma_f32_16x16x32_bf16 v[64:67], v[166:169], v[206:209], v[64:67]
	v_mfma_f32_16x16x32_bf16 v[68:71], v[174:177], v[206:209], v[68:71]
	v_mfma_f32_16x16x32_bf16 v[116:119], v[170:173], v[186:189], v[116:119]
	v_mfma_f32_16x16x32_bf16 v[112:115], v[178:181], v[186:189], v[112:115]
	v_mfma_f32_16x16x32_bf16 v[96:99], v[170:173], v[194:197], v[96:99]
	v_mfma_f32_16x16x32_bf16 v[100:103], v[178:181], v[194:197], v[100:103]
	v_mfma_f32_16x16x32_bf16 v[80:83], v[170:173], v[202:205], v[80:83]
	v_mfma_f32_16x16x32_bf16 v[84:87], v[178:181], v[202:205], v[84:87]
	v_mfma_f32_16x16x32_bf16 v[64:67], v[170:173], v[210:213], v[64:67]
	v_mfma_f32_16x16x32_bf16 v[68:71], v[178:181], v[210:213], v[68:71]
	s_barrier
	s_setprio 0
	s_add_i32 s49, s40, s29
	s_add_u32 s98, s20, 0x80
	s_addc_u32 s99, s21, 0
	s_mov_b32 m0, s49
	ds_read_b128 v[182:185], v153 offset:16384
	ds_read_b128 v[186:189], v153 offset:17408
	ds_read_b128 v[190:193], v153 offset:18432
	ds_read_b128 v[194:197], v153 offset:19456
	ds_read_b128 v[198:201], v153 offset:20480
	ds_read_b128 v[202:205], v153 offset:21504
	ds_read_b128 v[206:209], v153 offset:22528
	ds_read_b128 v[210:213], v153 offset:23552
	global_load_lds_dwordx4 v130, s[20:21]
	s_add_i32 m0, s49, 0x2000
	s_add_u32 s52, s20, 0x160000
	s_addc_u32 s53, s21, 0
	s_add_i32 s49, s41, s29
	global_load_lds_dwordx4 v134, s[20:21]
	s_mov_b32 m0, s49
	s_nop 0
	global_load_lds_dwordx4 v130, s[52:53]
	s_add_i32 m0, s49, 0x2000
	s_nop 0
	global_load_lds_dwordx4 v134, s[52:53]
	s_add_u32 s100, s26, 0x80
	s_addc_u32 s101, s27, 0
	s_mov_b32 m0, s30
	s_nop 0
	global_load_lds_dwordx4 v128, s[26:27]
	s_mov_b32 m0, s31
	s_nop 0
	global_load_lds_dwordx4 v132, s[26:27]
	s_waitcnt vmcnt(8)
	s_waitcnt lgkmcnt(0)
	s_setprio 1
	s_barrier
	v_mfma_f32_16x16x32_bf16 v[56:59], v[144:147], v[182:185], v[56:59]
	v_mfma_f32_16x16x32_bf16 v[60:63], v[158:161], v[182:185], v[60:63]
	v_mfma_f32_16x16x32_bf16 v[40:43], v[144:147], v[190:193], v[40:43]
	v_mfma_f32_16x16x32_bf16 v[44:47], v[158:161], v[190:193], v[44:47]
	v_mfma_f32_16x16x32_bf16 v[24:27], v[144:147], v[198:201], v[24:27]
	v_mfma_f32_16x16x32_bf16 v[28:31], v[158:161], v[198:201], v[28:31]
	v_mfma_f32_16x16x32_bf16 v[8:11], v[144:147], v[206:209], v[8:11]
	v_mfma_f32_16x16x32_bf16 v[12:15], v[158:161], v[206:209], v[12:15]
	v_mfma_f32_16x16x32_bf16 v[56:59], v[154:157], v[186:189], v[56:59]
	v_mfma_f32_16x16x32_bf16 v[60:63], v[162:165], v[186:189], v[60:63]
	v_mfma_f32_16x16x32_bf16 v[40:43], v[154:157], v[194:197], v[40:43]
	v_mfma_f32_16x16x32_bf16 v[44:47], v[162:165], v[194:197], v[44:47]
	v_mfma_f32_16x16x32_bf16 v[24:27], v[154:157], v[202:205], v[24:27]
	v_mfma_f32_16x16x32_bf16 v[28:31], v[162:165], v[202:205], v[28:31]
	v_mfma_f32_16x16x32_bf16 v[8:11], v[154:157], v[210:213], v[8:11]
	v_mfma_f32_16x16x32_bf16 v[12:15], v[162:165], v[210:213], v[12:15]
	s_setprio 0
	s_setprio 1
	v_mfma_f32_16x16x32_bf16 v[48:51], v[166:169], v[182:185], v[48:51]
	v_mfma_f32_16x16x32_bf16 v[52:55], v[174:177], v[182:185], v[52:55]
	v_mfma_f32_16x16x32_bf16 v[32:35], v[166:169], v[190:193], v[32:35]
	v_mfma_f32_16x16x32_bf16 v[36:39], v[174:177], v[190:193], v[36:39]
	v_mfma_f32_16x16x32_bf16 v[16:19], v[166:169], v[198:201], v[16:19]
	v_mfma_f32_16x16x32_bf16 v[20:23], v[174:177], v[198:201], v[20:23]
	v_mfma_f32_16x16x32_bf16 v[0:3], v[166:169], v[206:209], v[0:3]
	v_mfma_f32_16x16x32_bf16 v[4:7], v[174:177], v[206:209], v[4:7]
	v_mfma_f32_16x16x32_bf16 v[48:51], v[170:173], v[186:189], v[48:51]
	v_mfma_f32_16x16x32_bf16 v[52:55], v[178:181], v[186:189], v[52:55]
	v_mfma_f32_16x16x32_bf16 v[32:35], v[170:173], v[194:197], v[32:35]
	v_mfma_f32_16x16x32_bf16 v[36:39], v[178:181], v[194:197], v[36:39]
	v_mfma_f32_16x16x32_bf16 v[16:19], v[170:173], v[202:205], v[16:19]
	v_mfma_f32_16x16x32_bf16 v[20:23], v[178:181], v[202:205], v[20:23]
	v_mfma_f32_16x16x32_bf16 v[0:3], v[170:173], v[210:213], v[0:3]
	v_mfma_f32_16x16x32_bf16 v[4:7], v[178:181], v[210:213], v[4:7]
	s_barrier
	s_setprio 0
	s_add_i32 s49, 0, 0x18000
	s_add_i32 s52, 0, 0x1c000
	ds_read_b128 v[144:147], v151 offset:32768
	ds_read_b128 v[154:157], v151 offset:33792
	ds_read_b128 v[158:161], v151 offset:34816
	ds_read_b128 v[162:165], v151 offset:35840
	ds_read_b128 v[166:169], v152 offset:32768
	ds_read_b128 v[170:173], v152 offset:33792
	ds_read_b128 v[174:177], v152 offset:34816
	ds_read_b128 v[178:181], v152 offset:35840
	s_add_u32 s26, s26, 0x160000
	s_addc_u32 s27, s27, 0
	s_mov_b32 m0, s34
	ds_read_b128 v[182:185], v153 offset:32768
	ds_read_b128 v[186:189], v153 offset:33792
	ds_read_b128 v[190:193], v153 offset:34816
	ds_read_b128 v[194:197], v153 offset:35840
	ds_read_b128 v[198:201], v153 offset:36864
	ds_read_b128 v[202:205], v153 offset:37888
	ds_read_b128 v[206:209], v153 offset:38912
	ds_read_b128 v[210:213], v153 offset:39936
	global_load_lds_dwordx4 v128, s[26:27]
	s_mov_b32 m0, s35
	s_nop 0
	global_load_lds_dwordx4 v132, s[26:27]
	s_waitcnt vmcnt(8)
	s_waitcnt lgkmcnt(0)
	s_setprio 1
	s_barrier
	v_mfma_f32_16x16x32_bf16 v[124:127], v[144:147], v[182:185], v[124:127]
	v_mfma_f32_16x16x32_bf16 v[120:123], v[158:161], v[182:185], v[120:123]
	v_mfma_f32_16x16x32_bf16 v[108:111], v[144:147], v[190:193], v[108:111]
	v_mfma_f32_16x16x32_bf16 v[104:107], v[158:161], v[190:193], v[104:107]
	v_mfma_f32_16x16x32_bf16 v[88:91], v[144:147], v[198:201], v[88:91]
	v_mfma_f32_16x16x32_bf16 v[92:95], v[158:161], v[198:201], v[92:95]
	v_mfma_f32_16x16x32_bf16 v[72:75], v[144:147], v[206:209], v[72:75]
	v_mfma_f32_16x16x32_bf16 v[76:79], v[158:161], v[206:209], v[76:79]
	v_mfma_f32_16x16x32_bf16 v[124:127], v[154:157], v[186:189], v[124:127]
	v_mfma_f32_16x16x32_bf16 v[120:123], v[162:165], v[186:189], v[120:123]
	v_mfma_f32_16x16x32_bf16 v[108:111], v[154:157], v[194:197], v[108:111]
	v_mfma_f32_16x16x32_bf16 v[104:107], v[162:165], v[194:197], v[104:107]
	v_mfma_f32_16x16x32_bf16 v[88:91], v[154:157], v[202:205], v[88:91]
	v_mfma_f32_16x16x32_bf16 v[92:95], v[162:165], v[202:205], v[92:95]
	v_mfma_f32_16x16x32_bf16 v[72:75], v[154:157], v[210:213], v[72:75]
	v_mfma_f32_16x16x32_bf16 v[76:79], v[162:165], v[210:213], v[76:79]
	s_setprio 0
	s_setprio 1
	v_mfma_f32_16x16x32_bf16 v[116:119], v[166:169], v[182:185], v[116:119]
	v_mfma_f32_16x16x32_bf16 v[112:115], v[174:177], v[182:185], v[112:115]
	v_mfma_f32_16x16x32_bf16 v[96:99], v[166:169], v[190:193], v[96:99]
	v_mfma_f32_16x16x32_bf16 v[100:103], v[174:177], v[190:193], v[100:103]
	v_mfma_f32_16x16x32_bf16 v[80:83], v[166:169], v[198:201], v[80:83]
	v_mfma_f32_16x16x32_bf16 v[84:87], v[174:177], v[198:201], v[84:87]
	v_mfma_f32_16x16x32_bf16 v[64:67], v[166:169], v[206:209], v[64:67]
	v_mfma_f32_16x16x32_bf16 v[68:71], v[174:177], v[206:209], v[68:71]
	v_mfma_f32_16x16x32_bf16 v[116:119], v[170:173], v[186:189], v[116:119]
	v_mfma_f32_16x16x32_bf16 v[112:115], v[178:181], v[186:189], v[112:115]
	v_mfma_f32_16x16x32_bf16 v[96:99], v[170:173], v[194:197], v[96:99]
	v_mfma_f32_16x16x32_bf16 v[100:103], v[178:181], v[194:197], v[100:103]
	v_mfma_f32_16x16x32_bf16 v[80:83], v[170:173], v[202:205], v[80:83]
	v_mfma_f32_16x16x32_bf16 v[84:87], v[178:181], v[202:205], v[84:87]
	v_mfma_f32_16x16x32_bf16 v[64:67], v[170:173], v[210:213], v[64:67]
	v_mfma_f32_16x16x32_bf16 v[68:71], v[178:181], v[210:213], v[68:71]
	s_barrier
	s_setprio 0
	s_add_i32 s26, s49, s29
	s_mov_b32 m0, s26
	ds_read_b128 v[182:185], v153 offset:49152
	ds_read_b128 v[186:189], v153 offset:50176
	ds_read_b128 v[190:193], v153 offset:51200
	ds_read_b128 v[194:197], v153 offset:52224
	ds_read_b128 v[198:201], v153 offset:53248
	ds_read_b128 v[202:205], v153 offset:54272
	ds_read_b128 v[206:209], v153 offset:55296
	ds_read_b128 v[210:213], v153 offset:56320
	global_load_lds_dwordx4 v130, s[98:99]
	s_add_i32 m0, s26, 0x2000
	s_add_u32 s20, s20, 0x160080
	s_addc_u32 s21, s21, 0
	s_add_i32 s26, s52, s29
	global_load_lds_dwordx4 v134, s[98:99]
	s_mov_b32 m0, s26
	s_nop 0
	global_load_lds_dwordx4 v130, s[20:21]
	s_add_i32 m0, s26, 0x2000
	s_nop 0
	global_load_lds_dwordx4 v134, s[20:21]
	s_mov_b32 m0, s37
	s_nop 0
	global_load_lds_dwordx4 v128, s[100:101]
	s_mov_b32 m0, s38
	s_nop 0
	global_load_lds_dwordx4 v132, s[100:101]
	s_add_i32 s48, s48, 2
	s_add_u32 s16, s16, 0x100
	s_addc_u32 s17, s17, 0
	s_add_u32 s46, s46, 0x100
	s_addc_u32 s47, s47, 0
	s_cmpk_gt_u32 s48, 0x55
	s_waitcnt vmcnt(8)
	s_waitcnt lgkmcnt(0)
	s_setprio 1
	s_barrier
	v_mfma_f32_16x16x32_bf16 v[56:59], v[144:147], v[182:185], v[56:59]
	v_mfma_f32_16x16x32_bf16 v[60:63], v[158:161], v[182:185], v[60:63]
	v_mfma_f32_16x16x32_bf16 v[40:43], v[144:147], v[190:193], v[40:43]
	v_mfma_f32_16x16x32_bf16 v[44:47], v[158:161], v[190:193], v[44:47]
	v_mfma_f32_16x16x32_bf16 v[24:27], v[144:147], v[198:201], v[24:27]
	v_mfma_f32_16x16x32_bf16 v[28:31], v[158:161], v[198:201], v[28:31]
	v_mfma_f32_16x16x32_bf16 v[8:11], v[144:147], v[206:209], v[8:11]
	v_mfma_f32_16x16x32_bf16 v[12:15], v[158:161], v[206:209], v[12:15]
	v_mfma_f32_16x16x32_bf16 v[56:59], v[154:157], v[186:189], v[56:59]
	v_mfma_f32_16x16x32_bf16 v[60:63], v[162:165], v[186:189], v[60:63]
	v_mfma_f32_16x16x32_bf16 v[40:43], v[154:157], v[194:197], v[40:43]
	v_mfma_f32_16x16x32_bf16 v[44:47], v[162:165], v[194:197], v[44:47]
	v_mfma_f32_16x16x32_bf16 v[24:27], v[154:157], v[202:205], v[24:27]
	v_mfma_f32_16x16x32_bf16 v[28:31], v[162:165], v[202:205], v[28:31]
	v_mfma_f32_16x16x32_bf16 v[8:11], v[154:157], v[210:213], v[8:11]
	v_mfma_f32_16x16x32_bf16 v[12:15], v[162:165], v[210:213], v[12:15]
	s_setprio 0
	s_setprio 1
	v_mfma_f32_16x16x32_bf16 v[48:51], v[166:169], v[182:185], v[48:51]
	v_mfma_f32_16x16x32_bf16 v[52:55], v[174:177], v[182:185], v[52:55]
	v_mfma_f32_16x16x32_bf16 v[32:35], v[166:169], v[190:193], v[32:35]
	v_mfma_f32_16x16x32_bf16 v[36:39], v[174:177], v[190:193], v[36:39]
	v_mfma_f32_16x16x32_bf16 v[16:19], v[166:169], v[198:201], v[16:19]
	v_mfma_f32_16x16x32_bf16 v[20:23], v[174:177], v[198:201], v[20:23]
	v_mfma_f32_16x16x32_bf16 v[0:3], v[166:169], v[206:209], v[0:3]
	v_mfma_f32_16x16x32_bf16 v[4:7], v[174:177], v[206:209], v[4:7]
	v_mfma_f32_16x16x32_bf16 v[48:51], v[170:173], v[186:189], v[48:51]
	v_mfma_f32_16x16x32_bf16 v[52:55], v[178:181], v[186:189], v[52:55]
	v_mfma_f32_16x16x32_bf16 v[32:35], v[170:173], v[194:197], v[32:35]
	v_mfma_f32_16x16x32_bf16 v[36:39], v[178:181], v[194:197], v[36:39]
	v_mfma_f32_16x16x32_bf16 v[16:19], v[170:173], v[202:205], v[16:19]
	v_mfma_f32_16x16x32_bf16 v[20:23], v[178:181], v[202:205], v[20:23]
	v_mfma_f32_16x16x32_bf16 v[0:3], v[170:173], v[210:213], v[0:3]
	v_mfma_f32_16x16x32_bf16 v[4:7], v[178:181], v[210:213], v[4:7]
	s_barrier
	s_setprio 0
	s_cbranch_scc0 .LBB0_1566
	s_and_b64 vcc, exec, s[10:11]
	s_cbranch_vccz .LBB0_1569
	s_barrier
